# MFMA issue order in all GEMM K-loops: each accumulator's two K-half MFMAs back-to-back (SrcC forwarding), consecutive pairs share one operand (snake over m,n; k order alternates); out-proj instance ke
# speedup vs baseline: 1.0276x; 1.0276x over previous
; #define PG8_STAGE(bufoff, gbase, voff) do { _Pragma("unroll") for (int _i = 0; _i < 2; ++_i) \
;         __builtin_amdgcn_global_load_lds((const unsigned*)((const char*)(gbase) + (voff)[_i]), (PG8_LAS unsigned*)(lds + (bufoff) + ldsw + _i * 8192), 16, 0, 0); } while (0)
; #define PG8_LDA(dst, b, h) do { _Pragma("unroll") for (int m = 0; m < 4; ++m) _Pragma("unroll") for (int k = 0; k < 2; ++k) dst[m][k] = *(const PG8_LAS bf16x8*)(lds + PG8_SA(b, h) + aoff + m * 2048 + k * 1024); } while (0)
; #define PG8_LDB(dst, b, h) do { _Pragma("unroll") for (int n = 0; n < 2; ++n) _Pragma("unroll") for (int k = 0; k < 2; ++k) dst[n][k] = *(const PG8_LAS bf16x8*)(lds + PG8_SB(b, h) + boff + n * 2048 + k * 1024); } while (0)
; #define PG8_MMA(ai, bj, At, Bt) do { __builtin_amdgcn_s_setprio(1); _Pragma("unroll") for (int m = 0; m < 4; ++m) _Pragma("unroll") for (int n = 0; n < 2; ++n) _Pragma("unroll") for (int k = 0; k < 2; ++k) \
;         acc[ai][bj][m][n] = __builtin_amdgcn_mfma_f32_16x16x32_bf16(Bt[n][k], At[m][k], acc[ai][bj][m][n], 0, 0, 0); __builtin_amdgcn_s_setprio(0); } while (0)
; #define PG8_BAR __builtin_amdgcn_s_barrier()
; template <class Epi, class Sched, bool ALIGN_EPI = false, bool SP2 = false>
; __device__ __forceinline__ void gemm_phase(PG8_LAS unsigned char* lds, const Gemm g, const Sched& S, const Epi& E) {
;     ...
;         for (int t = 0; t < nt; t += 2) {
;             if constexpr (Epi::MIDSCALE) { if (t == (nt >> 1)) E.mid(acc, cur, wr, fr); }
;             const bool last = (t == nt - 2);
;             const char* a1 = cA + (size_t)(t + 1) * kstep;
;             const char* a2 = last ? nA : cA + (size_t)(t + 2) * kstep; const char* b2 = last ? nB : cB + (size_t)(t + 2) * kstep;
;             const char* a3 = a2 + kstep; const char* b3 = b2 + kstep;
;             if (last && has_next) S.a_ready(nxt);
;             if constexpr (SP2) {
;             PG8_LDB(B0, 0, 0); PG8_LDB(B1, 0, 1); PG8_SCHED; PG8_LDA(At, 0, 0); PG8_STAGE(PG8_SA(1, 1), a1 + hstepA, voffA);
;             PG8_WAIT_V(8); PG8_WAIT_L(0); PG8_BAR; PG8_MMA(0, 0, At, B0); PG8_MMA(0, 1, At, B1); PG8_BAR; PG8_SCHED;
;             PG8_LDA(At, 0, 1); PG8_STAGE(PG8_SB(0, 0), b2, voffB); PG8_STAGE(PG8_SB(0, 1), b2 + hstepB, voffB); PG8_STAGE(PG8_SA(0, 0), a2, voffA);
;             PG8_WAIT_V(8); PG8_WAIT_L(0); PG8_BAR; PG8_MMA(1, 0, At, B0); PG8_MMA(1, 1, At, B1); PG8_BAR; PG8_SCHED;
.LBB0_324:
	s_add_u32 s22, s42, 0xfff80080
	s_addc_u32 s23, s43, -1
	s_add_i32 s65, 0, 0x10000
	s_cmp_eq_u32 s64, 28
	s_cselect_b32 s57, s21, s23
	s_cselect_b32 s56, s35, s22
	v_add_u32_e32 v80, s65, v186
	s_cselect_b32 s23, s1, s51
	s_cselect_b32 s22, s37, s49
	s_add_i32 s74, 0, 0x14000
	ds_read_b128 v[130:133], v80
	ds_read_b128 v[134:137], v80 offset:1024
	ds_read_b128 v[138:141], v80 offset:2048
	ds_read_b128 v[142:145], v80 offset:3072
	v_add_u32_e32 v80, s74, v186
	ds_read_b128 v[146:149], v80
	ds_read_b128 v[150:153], v80 offset:1024
	ds_read_b128 v[174:177], v80 offset:2048
	ds_read_b128 v[182:185], v80 offset:3072
	v_lshl_add_u64 v[192:193], s[42:43], 0, v[168:169]
	s_add_i32 m0, s63, 0xc000
	ds_read_b128 v[216:219], v191
	ds_read_b128 v[220:223], v191 offset:1024
	ds_read_b128 v[224:227], v191 offset:2048
	ds_read_b128 v[228:231], v191 offset:3072
	ds_read_b128 v[232:235], v191 offset:4096
	ds_read_b128 v[236:239], v191 offset:5120
	ds_read_b128 v[240:243], v191 offset:6144
	ds_read_b128 v[244:247], v191 offset:7168
	global_load_lds_dwordx4 v[192:193], off
	v_lshl_add_u64 v[192:193], s[42:43], 0, v[170:171]
	s_add_i32 m0, s63, 0xe000
	s_nop 0
	global_load_lds_dwordx4 v[192:193], off
	s_waitcnt vmcnt(8)
	s_waitcnt lgkmcnt(0)
	s_barrier
	s_setprio 1
	s_waitcnt lgkmcnt(0)
	v_mfma_f32_16x16x32_bf16 v[126:129], v[130:133], v[216:219], v[126:129]
	v_mfma_f32_16x16x32_bf16 v[126:129], v[134:137], v[220:223], v[126:129]
	v_mfma_f32_16x16x32_bf16 v[122:125], v[142:145], v[220:223], v[122:125]
	v_mfma_f32_16x16x32_bf16 v[122:125], v[138:141], v[216:219], v[122:125]
	v_mfma_f32_16x16x32_bf16 v[106:109], v[138:141], v[224:227], v[106:109]
	v_mfma_f32_16x16x32_bf16 v[106:109], v[142:145], v[228:231], v[106:109]
	v_mfma_f32_16x16x32_bf16 v[110:113], v[134:137], v[228:231], v[110:113]
	v_mfma_f32_16x16x32_bf16 v[110:113], v[130:133], v[224:227], v[110:113]
	v_mfma_f32_16x16x32_bf16 v[94:97], v[130:133], v[232:235], v[94:97]
	v_mfma_f32_16x16x32_bf16 v[94:97], v[134:137], v[236:239], v[94:97]
	v_mfma_f32_16x16x32_bf16 v[90:93], v[142:145], v[236:239], v[90:93]
	v_mfma_f32_16x16x32_bf16 v[90:93], v[138:141], v[232:235], v[90:93]
	v_mfma_f32_16x16x32_bf16 v[72:75], v[138:141], v[240:243], v[72:75]
	v_mfma_f32_16x16x32_bf16 v[72:75], v[142:145], v[244:247], v[72:75]
	v_mfma_f32_16x16x32_bf16 v[76:79], v[134:137], v[244:247], v[76:79]
	v_mfma_f32_16x16x32_bf16 v[76:79], v[130:133], v[240:243], v[76:79]
	s_setprio 0
	s_setprio 1
	v_mfma_f32_16x16x32_bf16 v[118:121], v[146:149], v[216:219], v[118:121]
	v_mfma_f32_16x16x32_bf16 v[118:121], v[150:153], v[220:223], v[118:121]
	v_mfma_f32_16x16x32_bf16 v[114:117], v[182:185], v[220:223], v[114:117]
	v_mfma_f32_16x16x32_bf16 v[114:117], v[174:177], v[216:219], v[114:117]
	v_mfma_f32_16x16x32_bf16 v[98:101], v[174:177], v[224:227], v[98:101]
	v_mfma_f32_16x16x32_bf16 v[98:101], v[182:185], v[228:231], v[98:101]
	v_mfma_f32_16x16x32_bf16 v[102:105], v[150:153], v[228:231], v[102:105]
	v_mfma_f32_16x16x32_bf16 v[102:105], v[146:149], v[224:227], v[102:105]
	v_mfma_f32_16x16x32_bf16 v[86:89], v[146:149], v[232:235], v[86:89]
	v_mfma_f32_16x16x32_bf16 v[86:89], v[150:153], v[236:239], v[86:89]
	v_mfma_f32_16x16x32_bf16 v[82:85], v[182:185], v[236:239], v[82:85]
	v_mfma_f32_16x16x32_bf16 v[82:85], v[174:177], v[232:235], v[82:85]
	v_mfma_f32_16x16x32_bf16 v[64:67], v[174:177], v[240:243], v[64:67]
	v_mfma_f32_16x16x32_bf16 v[64:67], v[182:185], v[244:247], v[64:67]
	v_mfma_f32_16x16x32_bf16 v[68:71], v[150:153], v[244:247], v[68:71]
	v_mfma_f32_16x16x32_bf16 v[68:71], v[146:149], v[240:243], v[68:71]
	s_setprio 0
	s_barrier
	s_add_i32 s65, s65, s55
	v_lshl_add_u64 v[192:193], s[22:23], 0, v[156:157]
	s_mov_b32 m0, s65
	ds_read_b128 v[216:219], v191 offset:16384
	ds_read_b128 v[220:223], v191 offset:17408
	ds_read_b128 v[224:227], v191 offset:18432
	ds_read_b128 v[228:231], v191 offset:19456
	ds_read_b128 v[232:235], v191 offset:20480
	ds_read_b128 v[236:239], v191 offset:21504
	ds_read_b128 v[240:243], v191 offset:22528
	ds_read_b128 v[244:247], v191 offset:23552
	global_load_lds_dwordx4 v[192:193], off
	s_add_i32 m0, s65, 0x2000
	s_add_u32 s72, s22, 0x80000
	v_lshl_add_u64 v[248:249], s[22:23], 0, v[160:161]
	s_addc_u32 s73, s23, 0
	s_add_i32 s65, s74, s55
	global_load_lds_dwordx4 v[248:249], off
	v_lshl_add_u64 v[202:203], s[72:73], 0, v[156:157]
	s_mov_b32 m0, s65
	v_lshl_add_u64 v[204:205], s[56:57], 0, v[158:159]
	global_load_lds_dwordx4 v[202:203], off
	v_lshl_add_u64 v[202:203], s[72:73], 0, v[160:161]
	s_add_i32 m0, s65, 0x2000
	s_nop 0
	global_load_lds_dwordx4 v[202:203], off
	v_lshl_add_u64 v[202:203], s[56:57], 0, v[154:155]
	s_mov_b32 m0, s63
	s_nop 0
	global_load_lds_dwordx4 v[202:203], off
	s_mov_b32 m0, s66
	s_nop 0
	global_load_lds_dwordx4 v[204:205], off
	s_waitcnt vmcnt(8)
	s_waitcnt lgkmcnt(0)
	s_barrier
; #define PG8_STAGE(bufoff, gbase, voff) do { _Pragma("unroll") for (int _i = 0; _i < 2; ++_i) \
;         __builtin_amdgcn_global_load_lds((const unsigned*)((const char*)(gbase) + (voff)[_i]), (PG8_LAS unsigned*)(lds + (bufoff) + ldsw + _i * 8192), 16, 0, 0); } while (0)
; #define PG8_LDA(dst, b, h) do { _Pragma("unroll") for (int m = 0; m < 4; ++m) _Pragma("unroll") for (int k = 0; k < 2; ++k) dst[m][k] = *(const PG8_LAS bf16x8*)(lds + PG8_SA(b, h) + aoff + m * 2048 + k * 1024); } while (0)
; #define PG8_LDB(dst, b, h) do { _Pragma("unroll") for (int n = 0; n < 2; ++n) _Pragma("unroll") for (int k = 0; k < 2; ++k) dst[n][k] = *(const PG8_LAS bf16x8*)(lds + PG8_SB(b, h) + boff + n * 2048 + k * 1024); } while (0)
; #define PG8_MMA(ai, bj, At, Bt) do { __builtin_amdgcn_s_setprio(1); _Pragma("unroll") for (int m = 0; m < 4; ++m) _Pragma("unroll") for (int n = 0; n < 2; ++n) _Pragma("unroll") for (int k = 0; k < 2; ++k) \
;         acc[ai][bj][m][n] = __builtin_amdgcn_mfma_f32_16x16x32_bf16(Bt[n][k], At[m][k], acc[ai][bj][m][n], 0, 0, 0); __builtin_amdgcn_s_setprio(0); } while (0)
; #define PG8_WAIT_V(n) asm volatile("s_waitcnt vmcnt(" #n ")" ::: "memory")
; #define PG8_WAIT_L(n) asm volatile("s_waitcnt lgkmcnt(" #n ")" ::: "memory")
; #define PG8_BAR __builtin_amdgcn_s_barrier()
; #define PG8_SCHED __builtin_amdgcn_sched_barrier(0)
; template <class Epi, class Sched, bool ALIGN_EPI = false, bool SP2 = false>
; __device__ __forceinline__ void gemm_phase(PG8_LAS unsigned char* lds, const Gemm g, const Sched& S, const Epi& E) {
;     ...
;             PG8_WAIT_V(8); PG8_WAIT_L(0); PG8_BAR; PG8_MMA(1, 0, At, B0); PG8_MMA(1, 1, At, B1); PG8_BAR; PG8_SCHED;
;             PG8_LDB(B0, 1, 0); PG8_LDB(B1, 1, 1); PG8_SCHED; PG8_LDA(At, 1, 0); PG8_STAGE(PG8_SA(0, 1), a2 + hstepA, voffA);
;             PG8_WAIT_V(8); PG8_WAIT_L(0); PG8_BAR; PG8_MMA(0, 0, At, B0); PG8_MMA(0, 1, At, B1); PG8_BAR; PG8_SCHED;
	s_setprio 1
	s_waitcnt lgkmcnt(0)
	v_mfma_f32_16x16x32_bf16 v[60:63], v[130:133], v[216:219], v[60:63]
	v_mfma_f32_16x16x32_bf16 v[60:63], v[134:137], v[220:223], v[60:63]
	v_mfma_f32_16x16x32_bf16 v[56:59], v[142:145], v[220:223], v[56:59]
	v_mfma_f32_16x16x32_bf16 v[56:59], v[138:141], v[216:219], v[56:59]
	v_mfma_f32_16x16x32_bf16 v[40:43], v[138:141], v[224:227], v[40:43]
	v_mfma_f32_16x16x32_bf16 v[40:43], v[142:145], v[228:231], v[40:43]
	v_mfma_f32_16x16x32_bf16 v[44:47], v[134:137], v[228:231], v[44:47]
	v_mfma_f32_16x16x32_bf16 v[44:47], v[130:133], v[224:227], v[44:47]
	v_mfma_f32_16x16x32_bf16 v[28:31], v[130:133], v[232:235], v[28:31]
	v_mfma_f32_16x16x32_bf16 v[28:31], v[134:137], v[236:239], v[28:31]
	v_mfma_f32_16x16x32_bf16 v[24:27], v[142:145], v[236:239], v[24:27]
	v_mfma_f32_16x16x32_bf16 v[24:27], v[138:141], v[232:235], v[24:27]
	v_mfma_f32_16x16x32_bf16 v[8:11], v[138:141], v[240:243], v[8:11]
	v_mfma_f32_16x16x32_bf16 v[8:11], v[142:145], v[244:247], v[8:11]
	v_mfma_f32_16x16x32_bf16 v[12:15], v[134:137], v[244:247], v[12:15]
	v_mfma_f32_16x16x32_bf16 v[12:15], v[130:133], v[240:243], v[12:15]
	s_setprio 0
	s_setprio 1
	v_mfma_f32_16x16x32_bf16 v[52:55], v[146:149], v[216:219], v[52:55]
	v_mfma_f32_16x16x32_bf16 v[52:55], v[150:153], v[220:223], v[52:55]
	v_mfma_f32_16x16x32_bf16 v[48:51], v[182:185], v[220:223], v[48:51]
	v_mfma_f32_16x16x32_bf16 v[48:51], v[174:177], v[216:219], v[48:51]
	v_mfma_f32_16x16x32_bf16 v[32:35], v[174:177], v[224:227], v[32:35]
	v_mfma_f32_16x16x32_bf16 v[32:35], v[182:185], v[228:231], v[32:35]
	v_mfma_f32_16x16x32_bf16 v[36:39], v[150:153], v[228:231], v[36:39]
	v_mfma_f32_16x16x32_bf16 v[36:39], v[146:149], v[224:227], v[36:39]
	v_mfma_f32_16x16x32_bf16 v[20:23], v[146:149], v[232:235], v[20:23]
	v_mfma_f32_16x16x32_bf16 v[20:23], v[150:153], v[236:239], v[20:23]
	v_mfma_f32_16x16x32_bf16 v[16:19], v[182:185], v[236:239], v[16:19]
	v_mfma_f32_16x16x32_bf16 v[16:19], v[174:177], v[232:235], v[16:19]
	v_mfma_f32_16x16x32_bf16 v[0:3], v[174:177], v[240:243], v[0:3]
	v_mfma_f32_16x16x32_bf16 v[0:3], v[182:185], v[244:247], v[0:3]
	v_mfma_f32_16x16x32_bf16 v[4:7], v[150:153], v[244:247], v[4:7]
	v_mfma_f32_16x16x32_bf16 v[4:7], v[146:149], v[240:243], v[4:7]
	s_setprio 0
	s_barrier
	s_add_i32 s65, 0, 0x18000
	v_add_u32_e32 v80, s65, v186
	s_add_i32 s72, 0, 0x1c000
	ds_read_b128 v[130:133], v80
	ds_read_b128 v[134:137], v80 offset:1024
	ds_read_b128 v[138:141], v80 offset:2048
	ds_read_b128 v[142:145], v80 offset:3072
	v_add_u32_e32 v80, s72, v186
	ds_read_b128 v[146:149], v80
	ds_read_b128 v[150:153], v80 offset:1024
	ds_read_b128 v[174:177], v80 offset:2048
	ds_read_b128 v[182:185], v80 offset:3072
	s_add_u32 s56, s56, 0x80000
	s_addc_u32 s57, s57, 0
	s_mov_b32 m0, s67
	v_lshl_add_u64 v[206:207], s[56:57], 0, v[154:155]
	ds_read_b128 v[216:219], v191 offset:32768
	ds_read_b128 v[220:223], v191 offset:33792
	ds_read_b128 v[224:227], v191 offset:34816
	ds_read_b128 v[228:231], v191 offset:35840
	ds_read_b128 v[232:235], v191 offset:36864
	ds_read_b128 v[236:239], v191 offset:37888
	ds_read_b128 v[240:243], v191 offset:38912
	ds_read_b128 v[244:247], v191 offset:39936
	global_load_lds_dwordx4 v[206:207], off
	v_lshl_add_u64 v[206:207], s[56:57], 0, v[158:159]
	s_mov_b32 m0, s68
	s_nop 0
	global_load_lds_dwordx4 v[206:207], off
	s_waitcnt vmcnt(8)
	s_waitcnt lgkmcnt(0)
	s_barrier
	s_setprio 1
	s_waitcnt lgkmcnt(0)
	v_mfma_f32_16x16x32_bf16 v[126:129], v[130:133], v[216:219], v[126:129]
	v_mfma_f32_16x16x32_bf16 v[126:129], v[134:137], v[220:223], v[126:129]
	v_mfma_f32_16x16x32_bf16 v[122:125], v[142:145], v[220:223], v[122:125]
	v_mfma_f32_16x16x32_bf16 v[122:125], v[138:141], v[216:219], v[122:125]
	v_mfma_f32_16x16x32_bf16 v[106:109], v[138:141], v[224:227], v[106:109]
	v_mfma_f32_16x16x32_bf16 v[106:109], v[142:145], v[228:231], v[106:109]
	v_mfma_f32_16x16x32_bf16 v[110:113], v[134:137], v[228:231], v[110:113]
	v_mfma_f32_16x16x32_bf16 v[110:113], v[130:133], v[224:227], v[110:113]
	v_mfma_f32_16x16x32_bf16 v[94:97], v[130:133], v[232:235], v[94:97]
	v_mfma_f32_16x16x32_bf16 v[94:97], v[134:137], v[236:239], v[94:97]
	v_mfma_f32_16x16x32_bf16 v[90:93], v[142:145], v[236:239], v[90:93]
	v_mfma_f32_16x16x32_bf16 v[90:93], v[138:141], v[232:235], v[90:93]
	v_mfma_f32_16x16x32_bf16 v[72:75], v[138:141], v[240:243], v[72:75]
	v_mfma_f32_16x16x32_bf16 v[72:75], v[142:145], v[244:247], v[72:75]
	v_mfma_f32_16x16x32_bf16 v[76:79], v[134:137], v[244:247], v[76:79]
	v_mfma_f32_16x16x32_bf16 v[76:79], v[130:133], v[240:243], v[76:79]
	s_setprio 0
	s_setprio 1
	v_mfma_f32_16x16x32_bf16 v[118:121], v[146:149], v[216:219], v[118:121]
	v_mfma_f32_16x16x32_bf16 v[118:121], v[150:153], v[220:223], v[118:121]
	v_mfma_f32_16x16x32_bf16 v[114:117], v[182:185], v[220:223], v[114:117]
	v_mfma_f32_16x16x32_bf16 v[114:117], v[174:177], v[216:219], v[114:117]
	v_mfma_f32_16x16x32_bf16 v[98:101], v[174:177], v[224:227], v[98:101]
	v_mfma_f32_16x16x32_bf16 v[98:101], v[182:185], v[228:231], v[98:101]
	v_mfma_f32_16x16x32_bf16 v[102:105], v[150:153], v[228:231], v[102:105]
	v_mfma_f32_16x16x32_bf16 v[102:105], v[146:149], v[224:227], v[102:105]
	v_mfma_f32_16x16x32_bf16 v[86:89], v[146:149], v[232:235], v[86:89]
	v_mfma_f32_16x16x32_bf16 v[86:89], v[150:153], v[236:239], v[86:89]
	v_mfma_f32_16x16x32_bf16 v[82:85], v[182:185], v[236:239], v[82:85]
	v_mfma_f32_16x16x32_bf16 v[82:85], v[174:177], v[232:235], v[82:85]
	v_mfma_f32_16x16x32_bf16 v[64:67], v[174:177], v[240:243], v[64:67]
	v_mfma_f32_16x16x32_bf16 v[64:67], v[182:185], v[244:247], v[64:67]
	v_mfma_f32_16x16x32_bf16 v[68:71], v[150:153], v[244:247], v[68:71]
	v_mfma_f32_16x16x32_bf16 v[68:71], v[146:149], v[240:243], v[68:71]
	s_setprio 0
	s_barrier
; #define PG8_STAGE(bufoff, gbase, voff) do { _Pragma("unroll") for (int _i = 0; _i < 2; ++_i) \
;         __builtin_amdgcn_global_load_lds((const unsigned*)((const char*)(gbase) + (voff)[_i]), (PG8_LAS unsigned*)(lds + (bufoff) + ldsw + _i * 8192), 16, 0, 0); } while (0)
; #define PG8_LDA(dst, b, h) do { _Pragma("unroll") for (int m = 0; m < 4; ++m) _Pragma("unroll") for (int k = 0; k < 2; ++k) dst[m][k] = *(const PG8_LAS bf16x8*)(lds + PG8_SA(b, h) + aoff + m * 2048 + k * 1024); } while (0)
; #define PG8_MMA(ai, bj, At, Bt) do { __builtin_amdgcn_s_setprio(1); _Pragma("unroll") for (int m = 0; m < 4; ++m) _Pragma("unroll") for (int n = 0; n < 2; ++n) _Pragma("unroll") for (int k = 0; k < 2; ++k) \
;         acc[ai][bj][m][n] = __builtin_amdgcn_mfma_f32_16x16x32_bf16(Bt[n][k], At[m][k], acc[ai][bj][m][n], 0, 0, 0); __builtin_amdgcn_s_setprio(0); } while (0)
; #define PG8_WAIT_V(n) asm volatile("s_waitcnt vmcnt(" #n ")" ::: "memory")
; #define PG8_WAIT_L(n) asm volatile("s_waitcnt lgkmcnt(" #n ")" ::: "memory")
; #define PG8_BAR __builtin_amdgcn_s_barrier()
; #define PG8_SCHED __builtin_amdgcn_sched_barrier(0)
; template <class Epi, class Sched, bool ALIGN_EPI = false, bool SP2 = false>
; __device__ __forceinline__ void gemm_phase(PG8_LAS unsigned char* lds, const Gemm g, const Sched& S, const Epi& E) {
;     ...
;             PG8_LDA(At, 1, 1); PG8_STAGE(PG8_SB(1, 0), b3, voffB); PG8_STAGE(PG8_SB(1, 1), b3 + hstepB, voffB); PG8_STAGE(PG8_SA(1, 0), a3, voffA);
;             PG8_WAIT_V(8); PG8_WAIT_L(0); PG8_BAR; PG8_MMA(1, 0, At, B0); PG8_MMA(1, 1, At, B1); PG8_BAR; PG8_SCHED;
;     ...
;         if constexpr (ALIGN_EPI) { if (wr == 0) PG8_BAR; }
	s_add_i32 s56, s65, s55
	v_lshl_add_u64 v[192:193], v[192:193], 0, s[60:61]
	s_mov_b32 m0, s56
	ds_read_b128 v[216:219], v191 offset:49152
	ds_read_b128 v[220:223], v191 offset:50176
	ds_read_b128 v[224:227], v191 offset:51200
	ds_read_b128 v[228:231], v191 offset:52224
	ds_read_b128 v[232:235], v191 offset:53248
	ds_read_b128 v[236:239], v191 offset:54272
	ds_read_b128 v[240:243], v191 offset:55296
	ds_read_b128 v[244:247], v191 offset:56320
	global_load_lds_dwordx4 v[192:193], off
	s_add_i32 m0, s56, 0x2000
	s_add_u32 s22, s22, 0x80080
	v_lshl_add_u64 v[192:193], v[248:249], 0, s[60:61]
	s_addc_u32 s23, s23, 0
	s_add_i32 s56, s72, s55
	global_load_lds_dwordx4 v[192:193], off
	v_lshl_add_u64 v[192:193], s[22:23], 0, v[156:157]
	s_mov_b32 m0, s56
	s_nop 0
	global_load_lds_dwordx4 v[192:193], off
	v_lshl_add_u64 v[192:193], s[22:23], 0, v[160:161]
	s_add_i32 m0, s56, 0x2000
	s_nop 0
	global_load_lds_dwordx4 v[192:193], off
	v_lshl_add_u64 v[192:193], v[202:203], 0, s[60:61]
	s_mov_b32 m0, s71
	s_nop 0
	global_load_lds_dwordx4 v[192:193], off
	v_lshl_add_u64 v[192:193], v[204:205], 0, s[60:61]
	s_mov_b32 m0, s48
	s_nop 0
	global_load_lds_dwordx4 v[192:193], off
	s_waitcnt vmcnt(8)
	s_waitcnt lgkmcnt(0)
	s_barrier
	s_setprio 1
	s_waitcnt lgkmcnt(0)
	v_mfma_f32_16x16x32_bf16 v[60:63], v[130:133], v[216:219], v[60:63]
	v_mfma_f32_16x16x32_bf16 v[60:63], v[134:137], v[220:223], v[60:63]
	v_mfma_f32_16x16x32_bf16 v[56:59], v[142:145], v[220:223], v[56:59]
	v_mfma_f32_16x16x32_bf16 v[56:59], v[138:141], v[216:219], v[56:59]
	v_mfma_f32_16x16x32_bf16 v[40:43], v[138:141], v[224:227], v[40:43]
	v_mfma_f32_16x16x32_bf16 v[40:43], v[142:145], v[228:231], v[40:43]
	v_mfma_f32_16x16x32_bf16 v[44:47], v[134:137], v[228:231], v[44:47]
	v_mfma_f32_16x16x32_bf16 v[44:47], v[130:133], v[224:227], v[44:47]
	v_mfma_f32_16x16x32_bf16 v[28:31], v[130:133], v[232:235], v[28:31]
	v_mfma_f32_16x16x32_bf16 v[28:31], v[134:137], v[236:239], v[28:31]
	v_mfma_f32_16x16x32_bf16 v[24:27], v[142:145], v[236:239], v[24:27]
	v_mfma_f32_16x16x32_bf16 v[24:27], v[138:141], v[232:235], v[24:27]
	v_mfma_f32_16x16x32_bf16 v[8:11], v[138:141], v[240:243], v[8:11]
	v_mfma_f32_16x16x32_bf16 v[8:11], v[142:145], v[244:247], v[8:11]
	v_mfma_f32_16x16x32_bf16 v[12:15], v[134:137], v[244:247], v[12:15]
	v_mfma_f32_16x16x32_bf16 v[12:15], v[130:133], v[240:243], v[12:15]
	s_setprio 0
	s_setprio 1
	v_mfma_f32_16x16x32_bf16 v[52:55], v[146:149], v[216:219], v[52:55]
	v_mfma_f32_16x16x32_bf16 v[52:55], v[150:153], v[220:223], v[52:55]
	v_mfma_f32_16x16x32_bf16 v[48:51], v[182:185], v[220:223], v[48:51]
	v_mfma_f32_16x16x32_bf16 v[48:51], v[174:177], v[216:219], v[48:51]
	v_mfma_f32_16x16x32_bf16 v[32:35], v[174:177], v[224:227], v[32:35]
	v_mfma_f32_16x16x32_bf16 v[32:35], v[182:185], v[228:231], v[32:35]
	v_mfma_f32_16x16x32_bf16 v[36:39], v[150:153], v[228:231], v[36:39]
	v_mfma_f32_16x16x32_bf16 v[36:39], v[146:149], v[224:227], v[36:39]
	v_mfma_f32_16x16x32_bf16 v[20:23], v[146:149], v[232:235], v[20:23]
	v_mfma_f32_16x16x32_bf16 v[20:23], v[150:153], v[236:239], v[20:23]
	v_mfma_f32_16x16x32_bf16 v[16:19], v[182:185], v[236:239], v[16:19]
	v_mfma_f32_16x16x32_bf16 v[16:19], v[174:177], v[232:235], v[16:19]
	v_mfma_f32_16x16x32_bf16 v[0:3], v[174:177], v[240:243], v[0:3]
	v_mfma_f32_16x16x32_bf16 v[0:3], v[182:185], v[244:247], v[0:3]
	v_mfma_f32_16x16x32_bf16 v[4:7], v[150:153], v[244:247], v[4:7]
	v_mfma_f32_16x16x32_bf16 v[4:7], v[146:149], v[240:243], v[4:7]
	s_setprio 0
	s_barrier
	s_add_i32 s64, s64, 2
	s_add_u32 s42, s42, 0x100
	s_addc_u32 s43, s43, 0
	s_add_u32 s49, s49, 0x100
	s_addc_u32 s51, s51, 0
	s_cmp_gt_u32 s64, 29
	s_cbranch_scc0 .LBB0_324
	s_and_b64 vcc, exec, s[46:47]
	s_cbranch_vccz .LBB0_327
	s_barrier

; #define PG8_STAGE(bufoff, gbase, voff) do { _Pragma("unroll") for (int _i = 0; _i < 2; ++_i) \
;         __builtin_amdgcn_global_load_lds((const unsigned*)((const char*)(gbase) + (voff)[_i]), (PG8_LAS unsigned*)(lds + (bufoff) + ldsw + _i * 8192), 16, 0, 0); } while (0)
; #define PG8_LDA(dst, b, h) do { _Pragma("unroll") for (int m = 0; m < 4; ++m) _Pragma("unroll") for (int k = 0; k < 2; ++k) dst[m][k] = *(const PG8_LAS bf16x8*)(lds + PG8_SA(b, h) + aoff + m * 2048 + k * 1024); } while (0)
; #define PG8_LDB(dst, b, h) do { _Pragma("unroll") for (int n = 0; n < 2; ++n) _Pragma("unroll") for (int k = 0; k < 2; ++k) dst[n][k] = *(const PG8_LAS bf16x8*)(lds + PG8_SB(b, h) + boff + n * 2048 + k * 1024); } while (0)
; #define PG8_MMA(ai, bj, At, Bt) do { __builtin_amdgcn_s_setprio(1); _Pragma("unroll") for (int m = 0; m < 4; ++m) _Pragma("unroll") for (int n = 0; n < 2; ++n) _Pragma("unroll") for (int k = 0; k < 2; ++k) \
;         acc[ai][bj][m][n] = __builtin_amdgcn_mfma_f32_16x16x32_bf16(Bt[n][k], At[m][k], acc[ai][bj][m][n], 0, 0, 0); __builtin_amdgcn_s_setprio(0); } while (0)
; #define PG8_BAR __builtin_amdgcn_s_barrier()
; template <class Epi, class Sched, bool ALIGN_EPI = false, bool SP2 = false>
; __device__ __forceinline__ void gemm_phase(PG8_LAS unsigned char* lds, const Gemm g, const Sched& S, const Epi& E) {
;     ...
;         for (int t = 0; t < nt; t += 2) {
;             if constexpr (Epi::MIDSCALE) { if (t == (nt >> 1)) E.mid(acc, cur, wr, fr); }
;             const bool last = (t == nt - 2);
;             const char* a1 = cA + (size_t)(t + 1) * kstep;
;             const char* a2 = last ? nA : cA + (size_t)(t + 2) * kstep; const char* b2 = last ? nB : cB + (size_t)(t + 2) * kstep;
;             const char* a3 = a2 + kstep; const char* b3 = b2 + kstep;
;             if (last && has_next) S.a_ready(nxt);
;             if constexpr (SP2) {
;             PG8_LDB(B0, 0, 0); PG8_LDB(B1, 0, 1); PG8_SCHED; PG8_LDA(At, 0, 0); PG8_STAGE(PG8_SA(1, 1), a1 + hstepA, voffA);
;             PG8_WAIT_V(8); PG8_WAIT_L(0); PG8_BAR; PG8_MMA(0, 0, At, B0); PG8_MMA(0, 1, At, B1); PG8_BAR; PG8_SCHED;
;             PG8_LDA(At, 0, 1); PG8_STAGE(PG8_SB(0, 0), b2, voffB); PG8_STAGE(PG8_SB(0, 1), b2 + hstepB, voffB); PG8_STAGE(PG8_SA(0, 0), a2, voffA);
;             PG8_WAIT_V(8); PG8_WAIT_L(0); PG8_BAR; PG8_MMA(1, 0, At, B0); PG8_MMA(1, 1, At, B1); PG8_BAR; PG8_SCHED;
.LBB0_618:
	s_add_u32 s48, s46, 0x100
	s_addc_u32 s49, s47, 0
	s_add_i32 s66, 0, 0x10000
	s_cmp_eq_u32 s65, 4
	s_cselect_b32 s51, s43, s49
	s_cselect_b32 s50, s42, s48
	v_add_u32_e32 v145, s66, v143
	s_cselect_b32 s23, s41, s64
	s_cselect_b32 s22, s62, s63
	s_add_i32 s67, 0, 0x14000
	ds_read_b128 v[146:149], v145
	ds_read_b128 v[150:153], v145 offset:1024
	ds_read_b128 v[154:157], v145 offset:2048
	ds_read_b128 v[158:161], v145 offset:3072
	v_add_u32_e32 v145, s67, v143
	ds_read_b128 v[162:165], v145
	ds_read_b128 v[166:169], v145 offset:1024
	ds_read_b128 v[170:173], v145 offset:2048
	ds_read_b128 v[174:177], v145 offset:3072
	v_lshl_add_u64 v[192:193], s[46:47], 0, v[138:139]
	s_add_i32 m0, s33, 0xc000
	ds_read_b128 v[182:185], v144
	ds_read_b128 v[188:191], v144 offset:1024
	ds_read_b128 v[216:219], v144 offset:2048
	ds_read_b128 v[220:223], v144 offset:3072
	ds_read_b128 v[224:227], v144 offset:4096
	ds_read_b128 v[228:231], v144 offset:5120
	ds_read_b128 v[232:235], v144 offset:6144
	ds_read_b128 v[236:239], v144 offset:7168
	global_load_lds_dwordx4 v[192:193], off
	v_lshl_add_u64 v[192:193], s[46:47], 0, v[140:141]
	s_add_i32 m0, s33, 0xe000
	s_nop 0
	global_load_lds_dwordx4 v[192:193], off
	s_waitcnt vmcnt(8)
	s_waitcnt lgkmcnt(0)
	s_barrier
	s_setprio 1
	s_waitcnt lgkmcnt(0)
	v_mfma_f32_16x16x32_bf16 v[126:129], v[146:149], v[182:185], v[126:129]
	v_mfma_f32_16x16x32_bf16 v[126:129], v[150:153], v[188:191], v[126:129]
	v_mfma_f32_16x16x32_bf16 v[122:125], v[158:161], v[188:191], v[122:125]
	v_mfma_f32_16x16x32_bf16 v[122:125], v[154:157], v[182:185], v[122:125]
	v_mfma_f32_16x16x32_bf16 v[114:117], v[154:157], v[216:219], v[114:117]
	v_mfma_f32_16x16x32_bf16 v[114:117], v[158:161], v[220:223], v[114:117]
	v_mfma_f32_16x16x32_bf16 v[118:121], v[150:153], v[220:223], v[118:121]
	v_mfma_f32_16x16x32_bf16 v[118:121], v[146:149], v[216:219], v[118:121]
	v_mfma_f32_16x16x32_bf16 v[102:105], v[146:149], v[224:227], v[102:105]
	v_mfma_f32_16x16x32_bf16 v[102:105], v[150:153], v[228:231], v[102:105]
	v_mfma_f32_16x16x32_bf16 v[98:101], v[158:161], v[228:231], v[98:101]
	v_mfma_f32_16x16x32_bf16 v[98:101], v[154:157], v[224:227], v[98:101]
	v_mfma_f32_16x16x32_bf16 v[82:85], v[154:157], v[232:235], v[82:85]
	v_mfma_f32_16x16x32_bf16 v[82:85], v[158:161], v[236:239], v[82:85]
	v_mfma_f32_16x16x32_bf16 v[86:89], v[150:153], v[236:239], v[86:89]
	v_mfma_f32_16x16x32_bf16 v[86:89], v[146:149], v[232:235], v[86:89]
	s_setprio 0
	s_setprio 1
	v_mfma_f32_16x16x32_bf16 v[110:113], v[162:165], v[182:185], v[110:113]
	v_mfma_f32_16x16x32_bf16 v[110:113], v[166:169], v[188:191], v[110:113]
	v_mfma_f32_16x16x32_bf16 v[106:109], v[174:177], v[188:191], v[106:109]
	v_mfma_f32_16x16x32_bf16 v[106:109], v[170:173], v[182:185], v[106:109]
	v_mfma_f32_16x16x32_bf16 v[90:93], v[170:173], v[216:219], v[90:93]
	v_mfma_f32_16x16x32_bf16 v[90:93], v[174:177], v[220:223], v[90:93]
	v_mfma_f32_16x16x32_bf16 v[94:97], v[166:169], v[220:223], v[94:97]
	v_mfma_f32_16x16x32_bf16 v[94:97], v[162:165], v[216:219], v[94:97]
	v_mfma_f32_16x16x32_bf16 v[76:79], v[162:165], v[224:227], v[76:79]
	v_mfma_f32_16x16x32_bf16 v[76:79], v[166:169], v[228:231], v[76:79]
	v_mfma_f32_16x16x32_bf16 v[72:75], v[174:177], v[228:231], v[72:75]
	v_mfma_f32_16x16x32_bf16 v[72:75], v[170:173], v[224:227], v[72:75]
	v_mfma_f32_16x16x32_bf16 v[64:67], v[170:173], v[232:235], v[64:67]
	v_mfma_f32_16x16x32_bf16 v[64:67], v[174:177], v[236:239], v[64:67]
	v_mfma_f32_16x16x32_bf16 v[68:71], v[166:169], v[236:239], v[68:71]
	v_mfma_f32_16x16x32_bf16 v[68:71], v[162:165], v[232:235], v[68:71]
	s_setprio 0
	s_barrier
	s_add_i32 s46, s66, s31
	v_lshl_add_u64 v[192:193], s[22:23], 0, v[80:81]
	s_mov_b32 m0, s46
	ds_read_b128 v[182:185], v144 offset:16384
	ds_read_b128 v[188:191], v144 offset:17408
	ds_read_b128 v[216:219], v144 offset:18432
	ds_read_b128 v[220:223], v144 offset:19456
	ds_read_b128 v[224:227], v144 offset:20480
	ds_read_b128 v[228:231], v144 offset:21504
	ds_read_b128 v[232:235], v144 offset:22528
	ds_read_b128 v[236:239], v144 offset:23552
	global_load_lds_dwordx4 v[192:193], off
	s_add_i32 m0, s46, 0x2000
	s_add_u32 s46, s22, 0x20000
	v_lshl_add_u64 v[202:203], s[22:23], 0, v[134:135]
	s_addc_u32 s47, s23, 0
	s_add_i32 s66, s67, s31
	global_load_lds_dwordx4 v[202:203], off
	v_lshl_add_u64 v[204:205], s[46:47], 0, v[80:81]
	s_mov_b32 m0, s66
	v_lshl_add_u64 v[206:207], s[50:51], 0, v[132:133]
	global_load_lds_dwordx4 v[204:205], off
	v_lshl_add_u64 v[204:205], s[46:47], 0, v[134:135]
	s_add_i32 m0, s66, 0x2000
	s_nop 0
	global_load_lds_dwordx4 v[204:205], off
	v_lshl_add_u64 v[204:205], s[50:51], 0, v[130:131]
	s_mov_b32 m0, s33
	s_nop 0
	global_load_lds_dwordx4 v[204:205], off
	s_mov_b32 m0, s35
	s_nop 0
	global_load_lds_dwordx4 v[206:207], off
	s_waitcnt vmcnt(8)
	s_waitcnt lgkmcnt(0)
	s_barrier
; #define PG8_STAGE(bufoff, gbase, voff) do { _Pragma("unroll") for (int _i = 0; _i < 2; ++_i) \
;         __builtin_amdgcn_global_load_lds((const unsigned*)((const char*)(gbase) + (voff)[_i]), (PG8_LAS unsigned*)(lds + (bufoff) + ldsw + _i * 8192), 16, 0, 0); } while (0)
; #define PG8_LDA(dst, b, h) do { _Pragma("unroll") for (int m = 0; m < 4; ++m) _Pragma("unroll") for (int k = 0; k < 2; ++k) dst[m][k] = *(const PG8_LAS bf16x8*)(lds + PG8_SA(b, h) + aoff + m * 2048 + k * 1024); } while (0)
; #define PG8_LDB(dst, b, h) do { _Pragma("unroll") for (int n = 0; n < 2; ++n) _Pragma("unroll") for (int k = 0; k < 2; ++k) dst[n][k] = *(const PG8_LAS bf16x8*)(lds + PG8_SB(b, h) + boff + n * 2048 + k * 1024); } while (0)
; #define PG8_MMA(ai, bj, At, Bt) do { __builtin_amdgcn_s_setprio(1); _Pragma("unroll") for (int m = 0; m < 4; ++m) _Pragma("unroll") for (int n = 0; n < 2; ++n) _Pragma("unroll") for (int k = 0; k < 2; ++k) \
;         acc[ai][bj][m][n] = __builtin_amdgcn_mfma_f32_16x16x32_bf16(Bt[n][k], At[m][k], acc[ai][bj][m][n], 0, 0, 0); __builtin_amdgcn_s_setprio(0); } while (0)
; #define PG8_WAIT_V(n) asm volatile("s_waitcnt vmcnt(" #n ")" ::: "memory")
; #define PG8_WAIT_L(n) asm volatile("s_waitcnt lgkmcnt(" #n ")" ::: "memory")
; #define PG8_BAR __builtin_amdgcn_s_barrier()
; #define PG8_SCHED __builtin_amdgcn_sched_barrier(0)
; template <class Epi, class Sched, bool ALIGN_EPI = false, bool SP2 = false>
; __device__ __forceinline__ void gemm_phase(PG8_LAS unsigned char* lds, const Gemm g, const Sched& S, const Epi& E) {
;     ...
;             PG8_WAIT_V(8); PG8_WAIT_L(0); PG8_BAR; PG8_MMA(1, 0, At, B0); PG8_MMA(1, 1, At, B1); PG8_BAR; PG8_SCHED;
;             PG8_LDB(B0, 1, 0); PG8_LDB(B1, 1, 1); PG8_SCHED; PG8_LDA(At, 1, 0); PG8_STAGE(PG8_SA(0, 1), a2 + hstepA, voffA);
;             PG8_WAIT_V(8); PG8_WAIT_L(0); PG8_BAR; PG8_MMA(0, 0, At, B0); PG8_MMA(0, 1, At, B1); PG8_BAR; PG8_SCHED;
	s_setprio 1
	s_waitcnt lgkmcnt(0)
	v_mfma_f32_16x16x32_bf16 v[60:63], v[146:149], v[182:185], v[60:63]
	v_mfma_f32_16x16x32_bf16 v[60:63], v[150:153], v[188:191], v[60:63]
	v_mfma_f32_16x16x32_bf16 v[56:59], v[158:161], v[188:191], v[56:59]
	v_mfma_f32_16x16x32_bf16 v[56:59], v[154:157], v[182:185], v[56:59]
	v_mfma_f32_16x16x32_bf16 v[48:51], v[154:157], v[216:219], v[48:51]
	v_mfma_f32_16x16x32_bf16 v[48:51], v[158:161], v[220:223], v[48:51]
	v_mfma_f32_16x16x32_bf16 v[52:55], v[150:153], v[220:223], v[52:55]
	v_mfma_f32_16x16x32_bf16 v[52:55], v[146:149], v[216:219], v[52:55]
	v_mfma_f32_16x16x32_bf16 v[36:39], v[146:149], v[224:227], v[36:39]
	v_mfma_f32_16x16x32_bf16 v[36:39], v[150:153], v[228:231], v[36:39]
	v_mfma_f32_16x16x32_bf16 v[32:35], v[158:161], v[228:231], v[32:35]
	v_mfma_f32_16x16x32_bf16 v[32:35], v[154:157], v[224:227], v[32:35]
	v_mfma_f32_16x16x32_bf16 v[16:19], v[154:157], v[232:235], v[16:19]
	v_mfma_f32_16x16x32_bf16 v[16:19], v[158:161], v[236:239], v[16:19]
	v_mfma_f32_16x16x32_bf16 v[20:23], v[150:153], v[236:239], v[20:23]
	v_mfma_f32_16x16x32_bf16 v[20:23], v[146:149], v[232:235], v[20:23]
	s_setprio 0
	s_setprio 1
	v_mfma_f32_16x16x32_bf16 v[44:47], v[162:165], v[182:185], v[44:47]
	v_mfma_f32_16x16x32_bf16 v[44:47], v[166:169], v[188:191], v[44:47]
	v_mfma_f32_16x16x32_bf16 v[40:43], v[174:177], v[188:191], v[40:43]
	v_mfma_f32_16x16x32_bf16 v[40:43], v[170:173], v[182:185], v[40:43]
	v_mfma_f32_16x16x32_bf16 v[24:27], v[170:173], v[216:219], v[24:27]
	v_mfma_f32_16x16x32_bf16 v[24:27], v[174:177], v[220:223], v[24:27]
	v_mfma_f32_16x16x32_bf16 v[28:31], v[166:169], v[220:223], v[28:31]
	v_mfma_f32_16x16x32_bf16 v[28:31], v[162:165], v[216:219], v[28:31]
	v_mfma_f32_16x16x32_bf16 v[12:15], v[162:165], v[224:227], v[12:15]
	v_mfma_f32_16x16x32_bf16 v[12:15], v[166:169], v[228:231], v[12:15]
	v_mfma_f32_16x16x32_bf16 v[8:11], v[174:177], v[228:231], v[8:11]
	v_mfma_f32_16x16x32_bf16 v[8:11], v[170:173], v[224:227], v[8:11]
	v_mfma_f32_16x16x32_bf16 v[0:3], v[170:173], v[232:235], v[0:3]
	v_mfma_f32_16x16x32_bf16 v[0:3], v[174:177], v[236:239], v[0:3]
	v_mfma_f32_16x16x32_bf16 v[4:7], v[166:169], v[236:239], v[4:7]
	v_mfma_f32_16x16x32_bf16 v[4:7], v[162:165], v[232:235], v[4:7]
	s_setprio 0
	s_barrier
	s_add_i32 s66, 0, 0x18000
	v_add_u32_e32 v145, s66, v143
	s_add_i32 s67, 0, 0x1c000
	ds_read_b128 v[146:149], v145
	ds_read_b128 v[150:153], v145 offset:1024
	ds_read_b128 v[154:157], v145 offset:2048
	ds_read_b128 v[158:161], v145 offset:3072
	v_add_u32_e32 v145, s67, v143
	ds_read_b128 v[162:165], v145
	ds_read_b128 v[166:169], v145 offset:1024
	ds_read_b128 v[170:173], v145 offset:2048
	ds_read_b128 v[174:177], v145 offset:3072
	s_add_u32 s46, s50, 0x30000
	s_addc_u32 s47, s51, 0
	s_mov_b32 m0, s36
	v_lshl_add_u64 v[240:241], s[46:47], 0, v[130:131]
	ds_read_b128 v[182:185], v144 offset:32768
	ds_read_b128 v[188:191], v144 offset:33792
	ds_read_b128 v[216:219], v144 offset:34816
	ds_read_b128 v[220:223], v144 offset:35840
	ds_read_b128 v[224:227], v144 offset:36864
	ds_read_b128 v[228:231], v144 offset:37888
	ds_read_b128 v[232:235], v144 offset:38912
	ds_read_b128 v[236:239], v144 offset:39936
	global_load_lds_dwordx4 v[240:241], off
	v_lshl_add_u64 v[240:241], s[46:47], 0, v[132:133]
	s_mov_b32 m0, s37
	s_nop 0
	global_load_lds_dwordx4 v[240:241], off
	s_waitcnt vmcnt(8)
	s_waitcnt lgkmcnt(0)
	s_barrier
	s_setprio 1
	s_waitcnt lgkmcnt(0)
	v_mfma_f32_16x16x32_bf16 v[126:129], v[146:149], v[182:185], v[126:129]
	v_mfma_f32_16x16x32_bf16 v[126:129], v[150:153], v[188:191], v[126:129]
	v_mfma_f32_16x16x32_bf16 v[122:125], v[158:161], v[188:191], v[122:125]
	v_mfma_f32_16x16x32_bf16 v[122:125], v[154:157], v[182:185], v[122:125]
	v_mfma_f32_16x16x32_bf16 v[114:117], v[154:157], v[216:219], v[114:117]
	v_mfma_f32_16x16x32_bf16 v[114:117], v[158:161], v[220:223], v[114:117]
	v_mfma_f32_16x16x32_bf16 v[118:121], v[150:153], v[220:223], v[118:121]
	v_mfma_f32_16x16x32_bf16 v[118:121], v[146:149], v[216:219], v[118:121]
	v_mfma_f32_16x16x32_bf16 v[102:105], v[146:149], v[224:227], v[102:105]
	v_mfma_f32_16x16x32_bf16 v[102:105], v[150:153], v[228:231], v[102:105]
	v_mfma_f32_16x16x32_bf16 v[98:101], v[158:161], v[228:231], v[98:101]
	v_mfma_f32_16x16x32_bf16 v[98:101], v[154:157], v[224:227], v[98:101]
	v_mfma_f32_16x16x32_bf16 v[82:85], v[154:157], v[232:235], v[82:85]
	v_mfma_f32_16x16x32_bf16 v[82:85], v[158:161], v[236:239], v[82:85]
	v_mfma_f32_16x16x32_bf16 v[86:89], v[150:153], v[236:239], v[86:89]
	v_mfma_f32_16x16x32_bf16 v[86:89], v[146:149], v[232:235], v[86:89]
	s_setprio 0
	s_setprio 1
	v_mfma_f32_16x16x32_bf16 v[110:113], v[162:165], v[182:185], v[110:113]
	v_mfma_f32_16x16x32_bf16 v[110:113], v[166:169], v[188:191], v[110:113]
	v_mfma_f32_16x16x32_bf16 v[106:109], v[174:177], v[188:191], v[106:109]
	v_mfma_f32_16x16x32_bf16 v[106:109], v[170:173], v[182:185], v[106:109]
	v_mfma_f32_16x16x32_bf16 v[90:93], v[170:173], v[216:219], v[90:93]
	v_mfma_f32_16x16x32_bf16 v[90:93], v[174:177], v[220:223], v[90:93]
	v_mfma_f32_16x16x32_bf16 v[94:97], v[166:169], v[220:223], v[94:97]
	v_mfma_f32_16x16x32_bf16 v[94:97], v[162:165], v[216:219], v[94:97]
	v_mfma_f32_16x16x32_bf16 v[76:79], v[162:165], v[224:227], v[76:79]
	v_mfma_f32_16x16x32_bf16 v[76:79], v[166:169], v[228:231], v[76:79]
	v_mfma_f32_16x16x32_bf16 v[72:75], v[174:177], v[228:231], v[72:75]
	v_mfma_f32_16x16x32_bf16 v[72:75], v[170:173], v[224:227], v[72:75]
	v_mfma_f32_16x16x32_bf16 v[64:67], v[170:173], v[232:235], v[64:67]
	v_mfma_f32_16x16x32_bf16 v[64:67], v[174:177], v[236:239], v[64:67]
	v_mfma_f32_16x16x32_bf16 v[68:71], v[166:169], v[236:239], v[68:71]
	v_mfma_f32_16x16x32_bf16 v[68:71], v[162:165], v[232:235], v[68:71]
	s_setprio 0
	s_barrier
; #define PG8_STAGE(bufoff, gbase, voff) do { _Pragma("unroll") for (int _i = 0; _i < 2; ++_i) \
;         __builtin_amdgcn_global_load_lds((const unsigned*)((const char*)(gbase) + (voff)[_i]), (PG8_LAS unsigned*)(lds + (bufoff) + ldsw + _i * 8192), 16, 0, 0); } while (0)
; #define PG8_LDA(dst, b, h) do { _Pragma("unroll") for (int m = 0; m < 4; ++m) _Pragma("unroll") for (int k = 0; k < 2; ++k) dst[m][k] = *(const PG8_LAS bf16x8*)(lds + PG8_SA(b, h) + aoff + m * 2048 + k * 1024); } while (0)
; #define PG8_MMA(ai, bj, At, Bt) do { __builtin_amdgcn_s_setprio(1); _Pragma("unroll") for (int m = 0; m < 4; ++m) _Pragma("unroll") for (int n = 0; n < 2; ++n) _Pragma("unroll") for (int k = 0; k < 2; ++k) \
;         acc[ai][bj][m][n] = __builtin_amdgcn_mfma_f32_16x16x32_bf16(Bt[n][k], At[m][k], acc[ai][bj][m][n], 0, 0, 0); __builtin_amdgcn_s_setprio(0); } while (0)
; #define PG8_WAIT_V(n) asm volatile("s_waitcnt vmcnt(" #n ")" ::: "memory")
; #define PG8_WAIT_L(n) asm volatile("s_waitcnt lgkmcnt(" #n ")" ::: "memory")
; #define PG8_BAR __builtin_amdgcn_s_barrier()
; #define PG8_SCHED __builtin_amdgcn_sched_barrier(0)
; template <class Epi, class Sched, bool ALIGN_EPI = false, bool SP2 = false>
; __device__ __forceinline__ void gemm_phase(PG8_LAS unsigned char* lds, const Gemm g, const Sched& S, const Epi& E) {
;     ...
;             PG8_LDA(At, 1, 1); PG8_STAGE(PG8_SB(1, 0), b3, voffB); PG8_STAGE(PG8_SB(1, 1), b3 + hstepB, voffB); PG8_STAGE(PG8_SA(1, 0), a3, voffA);
;             PG8_WAIT_V(8); PG8_WAIT_L(0); PG8_BAR; PG8_MMA(1, 0, At, B0); PG8_MMA(1, 1, At, B1); PG8_BAR; PG8_SCHED;
;     ...
;         if constexpr (ALIGN_EPI) { if (wr == 0) PG8_BAR; }
	s_add_i32 s46, s66, s31
	v_lshl_add_u64 v[192:193], v[192:193], 0, s[60:61]
	s_mov_b32 m0, s46
	ds_read_b128 v[182:185], v144 offset:49152
	ds_read_b128 v[188:191], v144 offset:50176
	ds_read_b128 v[216:219], v144 offset:51200
	ds_read_b128 v[220:223], v144 offset:52224
	ds_read_b128 v[224:227], v144 offset:53248
	ds_read_b128 v[228:231], v144 offset:54272
	ds_read_b128 v[232:235], v144 offset:55296
	ds_read_b128 v[236:239], v144 offset:56320
	global_load_lds_dwordx4 v[192:193], off
	s_add_i32 m0, s46, 0x2000
	s_add_u32 s22, s22, 0x20080
	v_lshl_add_u64 v[192:193], v[202:203], 0, s[60:61]
	s_addc_u32 s23, s23, 0
	s_add_i32 s46, s67, s31
	global_load_lds_dwordx4 v[192:193], off
	v_lshl_add_u64 v[192:193], s[22:23], 0, v[80:81]
	s_mov_b32 m0, s46
	s_nop 0
	global_load_lds_dwordx4 v[192:193], off
	v_lshl_add_u64 v[192:193], s[22:23], 0, v[134:135]
	s_add_i32 m0, s46, 0x2000
	s_nop 0
	global_load_lds_dwordx4 v[192:193], off
	v_lshl_add_u64 v[192:193], v[204:205], 0, s[60:61]
	s_mov_b32 m0, s53
	s_nop 0
	global_load_lds_dwordx4 v[192:193], off
	v_lshl_add_u64 v[192:193], v[206:207], 0, s[60:61]
	s_mov_b32 m0, s55
	s_nop 0
	global_load_lds_dwordx4 v[192:193], off
	s_waitcnt vmcnt(8)
	s_waitcnt lgkmcnt(0)
	s_barrier
	s_setprio 1
	s_waitcnt lgkmcnt(0)
	v_mfma_f32_16x16x32_bf16 v[60:63], v[146:149], v[182:185], v[60:63]
	v_mfma_f32_16x16x32_bf16 v[60:63], v[150:153], v[188:191], v[60:63]
	v_mfma_f32_16x16x32_bf16 v[56:59], v[158:161], v[188:191], v[56:59]
	v_mfma_f32_16x16x32_bf16 v[56:59], v[154:157], v[182:185], v[56:59]
	v_mfma_f32_16x16x32_bf16 v[48:51], v[154:157], v[216:219], v[48:51]
	v_mfma_f32_16x16x32_bf16 v[48:51], v[158:161], v[220:223], v[48:51]
	v_mfma_f32_16x16x32_bf16 v[52:55], v[150:153], v[220:223], v[52:55]
	v_mfma_f32_16x16x32_bf16 v[52:55], v[146:149], v[216:219], v[52:55]
	v_mfma_f32_16x16x32_bf16 v[36:39], v[146:149], v[224:227], v[36:39]
	v_mfma_f32_16x16x32_bf16 v[36:39], v[150:153], v[228:231], v[36:39]
	v_mfma_f32_16x16x32_bf16 v[32:35], v[158:161], v[228:231], v[32:35]
	v_mfma_f32_16x16x32_bf16 v[32:35], v[154:157], v[224:227], v[32:35]
	v_mfma_f32_16x16x32_bf16 v[16:19], v[154:157], v[232:235], v[16:19]
	v_mfma_f32_16x16x32_bf16 v[16:19], v[158:161], v[236:239], v[16:19]
	v_mfma_f32_16x16x32_bf16 v[20:23], v[150:153], v[236:239], v[20:23]
	v_mfma_f32_16x16x32_bf16 v[20:23], v[146:149], v[232:235], v[20:23]
	s_setprio 0
	s_setprio 1
	v_mfma_f32_16x16x32_bf16 v[44:47], v[162:165], v[182:185], v[44:47]
	v_mfma_f32_16x16x32_bf16 v[44:47], v[166:169], v[188:191], v[44:47]
	v_mfma_f32_16x16x32_bf16 v[40:43], v[174:177], v[188:191], v[40:43]
	v_mfma_f32_16x16x32_bf16 v[40:43], v[170:173], v[182:185], v[40:43]
	v_mfma_f32_16x16x32_bf16 v[24:27], v[170:173], v[216:219], v[24:27]
	v_mfma_f32_16x16x32_bf16 v[24:27], v[174:177], v[220:223], v[24:27]
	v_mfma_f32_16x16x32_bf16 v[28:31], v[166:169], v[220:223], v[28:31]
	v_mfma_f32_16x16x32_bf16 v[28:31], v[162:165], v[216:219], v[28:31]
	v_mfma_f32_16x16x32_bf16 v[12:15], v[162:165], v[224:227], v[12:15]
	v_mfma_f32_16x16x32_bf16 v[12:15], v[166:169], v[228:231], v[12:15]
	v_mfma_f32_16x16x32_bf16 v[8:11], v[174:177], v[228:231], v[8:11]
	v_mfma_f32_16x16x32_bf16 v[8:11], v[170:173], v[224:227], v[8:11]
	v_mfma_f32_16x16x32_bf16 v[0:3], v[170:173], v[232:235], v[0:3]
	v_mfma_f32_16x16x32_bf16 v[0:3], v[174:177], v[236:239], v[0:3]
	v_mfma_f32_16x16x32_bf16 v[4:7], v[166:169], v[236:239], v[4:7]
	v_mfma_f32_16x16x32_bf16 v[4:7], v[162:165], v[232:235], v[4:7]
	s_setprio 0
	s_barrier
	s_add_i32 s65, s65, 2
	s_add_u32 s63, s63, 0x100
	s_addc_u32 s64, s64, 0
	s_cmp_gt_u32 s65, 5
	s_mov_b64 s[46:47], s[48:49]
	s_cbranch_scc0 .LBB0_618
	s_and_b64 vcc, exec, s[20:21]
	s_cbranch_vccz .LBB0_621
	s_barrier

; #define PG8_STAGE(bufoff, gbase, voff) do { _Pragma("unroll") for (int _i = 0; _i < 2; ++_i) \
;         __builtin_amdgcn_global_load_lds((const unsigned*)((const char*)(gbase) + (voff)[_i]), (PG8_LAS unsigned*)(lds + (bufoff) + ldsw + _i * 8192), 16, 0, 0); } while (0)
; #define PG8_LDA(dst, b, h) do { _Pragma("unroll") for (int m = 0; m < 4; ++m) _Pragma("unroll") for (int k = 0; k < 2; ++k) dst[m][k] = *(const PG8_LAS bf16x8*)(lds + PG8_SA(b, h) + aoff + m * 2048 + k * 1024); } while (0)
; #define PG8_LDB(dst, b, h) do { _Pragma("unroll") for (int n = 0; n < 2; ++n) _Pragma("unroll") for (int k = 0; k < 2; ++k) dst[n][k] = *(const PG8_LAS bf16x8*)(lds + PG8_SB(b, h) + boff + n * 2048 + k * 1024); } while (0)
; #define PG8_MMA(ai, bj, At, Bt) do { __builtin_amdgcn_s_setprio(1); _Pragma("unroll") for (int m = 0; m < 4; ++m) _Pragma("unroll") for (int n = 0; n < 2; ++n) _Pragma("unroll") for (int k = 0; k < 2; ++k) \
;         acc[ai][bj][m][n] = __builtin_amdgcn_mfma_f32_16x16x32_bf16(Bt[n][k], At[m][k], acc[ai][bj][m][n], 0, 0, 0); __builtin_amdgcn_s_setprio(0); } while (0)
; #define PG8_BAR __builtin_amdgcn_s_barrier()
; template <class Epi, class Sched, bool ALIGN_EPI = false, bool SP2 = false>
; __device__ __forceinline__ void gemm_phase(PG8_LAS unsigned char* lds, const Gemm g, const Sched& S, const Epi& E) {
;     ...
;         for (int t = 0; t < nt; t += 2) {
;             if constexpr (Epi::MIDSCALE) { if (t == (nt >> 1)) E.mid(acc, cur, wr, fr); }
;             const bool last = (t == nt - 2);
;             const char* a1 = cA + (size_t)(t + 1) * kstep;
;             const char* a2 = last ? nA : cA + (size_t)(t + 2) * kstep; const char* b2 = last ? nB : cB + (size_t)(t + 2) * kstep;
;             const char* a3 = a2 + kstep; const char* b3 = b2 + kstep;
;             if (last && has_next) S.a_ready(nxt);
;             if constexpr (SP2) {
;             PG8_LDB(B0, 0, 0); PG8_LDB(B1, 0, 1); PG8_SCHED; PG8_LDA(At, 0, 0); PG8_STAGE(PG8_SA(1, 1), a1 + hstepA, voffA);
;             PG8_WAIT_V(8); PG8_WAIT_L(0); PG8_BAR; PG8_MMA(0, 0, At, B0); PG8_MMA(0, 1, At, B1); PG8_BAR; PG8_SCHED;
;             PG8_LDA(At, 0, 1); PG8_STAGE(PG8_SB(0, 0), b2, voffB); PG8_STAGE(PG8_SB(0, 1), b2 + hstepB, voffB); PG8_STAGE(PG8_SA(0, 0), a2, voffA);
;             PG8_WAIT_V(8); PG8_WAIT_L(0); PG8_BAR; PG8_MMA(1, 0, At, B0); PG8_MMA(1, 1, At, B1); PG8_BAR; PG8_SCHED;
.LBB0_868:
	s_add_u32 s20, s0, 0x100
	s_addc_u32 s21, s1, 0
	s_add_i32 s67, 0, 0x10000
	s_cmp_eq_u32 s37, 8
	s_cselect_b32 s51, s47, s21
	s_cselect_b32 s50, s46, s20
	v_add_u32_e32 v80, s67, v151
	s_cselect_b32 s23, s49, s36
	s_cselect_b32 s22, s48, s35
	s_add_i32 s68, 0, 0x14000
	ds_read_b128 v[142:145], v80
	ds_read_b128 v[146:149], v80 offset:1024
	ds_read_b128 v[156:159], v80 offset:2048
	ds_read_b128 v[160:163], v80 offset:3072
	v_add_u32_e32 v80, s68, v151
	ds_read_b128 v[164:167], v80
	ds_read_b128 v[168:171], v80 offset:1024
	ds_read_b128 v[172:175], v80 offset:2048
	ds_read_b128 v[182:185], v80 offset:3072
	v_lshl_add_u64 v[176:177], s[0:1], 0, v[138:139]
	s_add_i32 m0, s53, 0xc000
	ds_read_b128 v[188:191], v154
	ds_read_b128 v[216:219], v154 offset:1024
	ds_read_b128 v[220:223], v154 offset:2048
	ds_read_b128 v[224:227], v154 offset:3072
	ds_read_b128 v[228:231], v154 offset:4096
	ds_read_b128 v[232:235], v154 offset:5120
	ds_read_b128 v[236:239], v154 offset:6144
	ds_read_b128 v[240:243], v154 offset:7168
	global_load_lds_dwordx4 v[176:177], off
	v_lshl_add_u64 v[176:177], s[0:1], 0, v[140:141]
	s_add_i32 m0, s53, 0xe000
	s_nop 0
	global_load_lds_dwordx4 v[176:177], off
	s_waitcnt vmcnt(8)
	s_waitcnt lgkmcnt(0)
	s_barrier
	s_setprio 1
	s_waitcnt lgkmcnt(0)
	v_mfma_f32_16x16x32_bf16 v[126:129], v[142:145], v[188:191], v[126:129]
	v_mfma_f32_16x16x32_bf16 v[126:129], v[146:149], v[216:219], v[126:129]
	v_mfma_f32_16x16x32_bf16 v[122:125], v[160:163], v[216:219], v[122:125]
	v_mfma_f32_16x16x32_bf16 v[122:125], v[156:159], v[188:191], v[122:125]
	v_mfma_f32_16x16x32_bf16 v[106:109], v[156:159], v[220:223], v[106:109]
	v_mfma_f32_16x16x32_bf16 v[106:109], v[160:163], v[224:227], v[106:109]
	v_mfma_f32_16x16x32_bf16 v[110:113], v[146:149], v[224:227], v[110:113]
	v_mfma_f32_16x16x32_bf16 v[110:113], v[142:145], v[220:223], v[110:113]
	v_mfma_f32_16x16x32_bf16 v[94:97], v[142:145], v[228:231], v[94:97]
	v_mfma_f32_16x16x32_bf16 v[94:97], v[146:149], v[232:235], v[94:97]
	v_mfma_f32_16x16x32_bf16 v[90:93], v[160:163], v[232:235], v[90:93]
	v_mfma_f32_16x16x32_bf16 v[90:93], v[156:159], v[228:231], v[90:93]
	v_mfma_f32_16x16x32_bf16 v[72:75], v[156:159], v[236:239], v[72:75]
	v_mfma_f32_16x16x32_bf16 v[72:75], v[160:163], v[240:243], v[72:75]
	v_mfma_f32_16x16x32_bf16 v[76:79], v[146:149], v[240:243], v[76:79]
	v_mfma_f32_16x16x32_bf16 v[76:79], v[142:145], v[236:239], v[76:79]
	s_setprio 0
	s_setprio 1
	v_mfma_f32_16x16x32_bf16 v[118:121], v[164:167], v[188:191], v[118:121]
	v_mfma_f32_16x16x32_bf16 v[118:121], v[168:171], v[216:219], v[118:121]
	v_mfma_f32_16x16x32_bf16 v[114:117], v[182:185], v[216:219], v[114:117]
	v_mfma_f32_16x16x32_bf16 v[114:117], v[172:175], v[188:191], v[114:117]
	v_mfma_f32_16x16x32_bf16 v[98:101], v[172:175], v[220:223], v[98:101]
	v_mfma_f32_16x16x32_bf16 v[98:101], v[182:185], v[224:227], v[98:101]
	v_mfma_f32_16x16x32_bf16 v[102:105], v[168:171], v[224:227], v[102:105]
	v_mfma_f32_16x16x32_bf16 v[102:105], v[164:167], v[220:223], v[102:105]
	v_mfma_f32_16x16x32_bf16 v[86:89], v[164:167], v[228:231], v[86:89]
	v_mfma_f32_16x16x32_bf16 v[86:89], v[168:171], v[232:235], v[86:89]
	v_mfma_f32_16x16x32_bf16 v[82:85], v[182:185], v[232:235], v[82:85]
	v_mfma_f32_16x16x32_bf16 v[82:85], v[172:175], v[228:231], v[82:85]
	v_mfma_f32_16x16x32_bf16 v[64:67], v[172:175], v[236:239], v[64:67]
	v_mfma_f32_16x16x32_bf16 v[64:67], v[182:185], v[240:243], v[64:67]
	v_mfma_f32_16x16x32_bf16 v[68:71], v[168:171], v[240:243], v[68:71]
	v_mfma_f32_16x16x32_bf16 v[68:71], v[164:167], v[236:239], v[68:71]
	s_setprio 0
	s_barrier
	s_add_i32 s0, s67, s52
	v_lshl_add_u64 v[176:177], s[22:23], 0, v[132:133]
	s_mov_b32 m0, s0
	ds_read_b128 v[188:191], v154 offset:16384
	ds_read_b128 v[216:219], v154 offset:17408
	ds_read_b128 v[220:223], v154 offset:18432
	ds_read_b128 v[224:227], v154 offset:19456
	ds_read_b128 v[228:231], v154 offset:20480
	ds_read_b128 v[232:235], v154 offset:21504
	ds_read_b128 v[236:239], v154 offset:22528
	ds_read_b128 v[240:243], v154 offset:23552
	global_load_lds_dwordx4 v[176:177], off
	s_add_i32 m0, s0, 0x2000
	s_add_u32 s0, s22, 0x30000
	v_lshl_add_u64 v[192:193], s[22:23], 0, v[136:137]
	s_addc_u32 s1, s23, 0
	s_add_i32 s67, s68, s52
	global_load_lds_dwordx4 v[192:193], off
	v_lshl_add_u64 v[202:203], s[0:1], 0, v[132:133]
	s_mov_b32 m0, s67
	v_lshl_add_u64 v[204:205], s[50:51], 0, v[134:135]
	global_load_lds_dwordx4 v[202:203], off
	v_lshl_add_u64 v[202:203], s[0:1], 0, v[136:137]
	s_add_i32 m0, s67, 0x2000
	s_nop 0
	global_load_lds_dwordx4 v[202:203], off
	v_lshl_add_u64 v[202:203], s[50:51], 0, v[130:131]
	s_mov_b32 m0, s53
	s_nop 0
	global_load_lds_dwordx4 v[202:203], off
	s_mov_b32 m0, s55
	s_nop 0
	global_load_lds_dwordx4 v[204:205], off
	s_waitcnt vmcnt(8)
	s_waitcnt lgkmcnt(0)
	s_barrier
; #define PG8_STAGE(bufoff, gbase, voff) do { _Pragma("unroll") for (int _i = 0; _i < 2; ++_i) \
;         __builtin_amdgcn_global_load_lds((const unsigned*)((const char*)(gbase) + (voff)[_i]), (PG8_LAS unsigned*)(lds + (bufoff) + ldsw + _i * 8192), 16, 0, 0); } while (0)
; #define PG8_LDA(dst, b, h) do { _Pragma("unroll") for (int m = 0; m < 4; ++m) _Pragma("unroll") for (int k = 0; k < 2; ++k) dst[m][k] = *(const PG8_LAS bf16x8*)(lds + PG8_SA(b, h) + aoff + m * 2048 + k * 1024); } while (0)
; #define PG8_LDB(dst, b, h) do { _Pragma("unroll") for (int n = 0; n < 2; ++n) _Pragma("unroll") for (int k = 0; k < 2; ++k) dst[n][k] = *(const PG8_LAS bf16x8*)(lds + PG8_SB(b, h) + boff + n * 2048 + k * 1024); } while (0)
; #define PG8_MMA(ai, bj, At, Bt) do { __builtin_amdgcn_s_setprio(1); _Pragma("unroll") for (int m = 0; m < 4; ++m) _Pragma("unroll") for (int n = 0; n < 2; ++n) _Pragma("unroll") for (int k = 0; k < 2; ++k) \
;         acc[ai][bj][m][n] = __builtin_amdgcn_mfma_f32_16x16x32_bf16(Bt[n][k], At[m][k], acc[ai][bj][m][n], 0, 0, 0); __builtin_amdgcn_s_setprio(0); } while (0)
; #define PG8_WAIT_V(n) asm volatile("s_waitcnt vmcnt(" #n ")" ::: "memory")
; #define PG8_WAIT_L(n) asm volatile("s_waitcnt lgkmcnt(" #n ")" ::: "memory")
; #define PG8_BAR __builtin_amdgcn_s_barrier()
; #define PG8_SCHED __builtin_amdgcn_sched_barrier(0)
; template <class Epi, class Sched, bool ALIGN_EPI = false, bool SP2 = false>
; __device__ __forceinline__ void gemm_phase(PG8_LAS unsigned char* lds, const Gemm g, const Sched& S, const Epi& E) {
;     ...
;             PG8_WAIT_V(8); PG8_WAIT_L(0); PG8_BAR; PG8_MMA(1, 0, At, B0); PG8_MMA(1, 1, At, B1); PG8_BAR; PG8_SCHED;
;             PG8_LDB(B0, 1, 0); PG8_LDB(B1, 1, 1); PG8_SCHED; PG8_LDA(At, 1, 0); PG8_STAGE(PG8_SA(0, 1), a2 + hstepA, voffA);
;             PG8_WAIT_V(8); PG8_WAIT_L(0); PG8_BAR; PG8_MMA(0, 0, At, B0); PG8_MMA(0, 1, At, B1); PG8_BAR; PG8_SCHED;
	s_setprio 1
	s_waitcnt lgkmcnt(0)
	v_mfma_f32_16x16x32_bf16 v[60:63], v[142:145], v[188:191], v[60:63]
	v_mfma_f32_16x16x32_bf16 v[60:63], v[146:149], v[216:219], v[60:63]
	v_mfma_f32_16x16x32_bf16 v[56:59], v[160:163], v[216:219], v[56:59]
	v_mfma_f32_16x16x32_bf16 v[56:59], v[156:159], v[188:191], v[56:59]
	v_mfma_f32_16x16x32_bf16 v[40:43], v[156:159], v[220:223], v[40:43]
	v_mfma_f32_16x16x32_bf16 v[40:43], v[160:163], v[224:227], v[40:43]
	v_mfma_f32_16x16x32_bf16 v[44:47], v[146:149], v[224:227], v[44:47]
	v_mfma_f32_16x16x32_bf16 v[44:47], v[142:145], v[220:223], v[44:47]
	v_mfma_f32_16x16x32_bf16 v[28:31], v[142:145], v[228:231], v[28:31]
	v_mfma_f32_16x16x32_bf16 v[28:31], v[146:149], v[232:235], v[28:31]
	v_mfma_f32_16x16x32_bf16 v[24:27], v[160:163], v[232:235], v[24:27]
	v_mfma_f32_16x16x32_bf16 v[24:27], v[156:159], v[228:231], v[24:27]
	v_mfma_f32_16x16x32_bf16 v[8:11], v[156:159], v[236:239], v[8:11]
	v_mfma_f32_16x16x32_bf16 v[8:11], v[160:163], v[240:243], v[8:11]
	v_mfma_f32_16x16x32_bf16 v[12:15], v[146:149], v[240:243], v[12:15]
	v_mfma_f32_16x16x32_bf16 v[12:15], v[142:145], v[236:239], v[12:15]
	s_setprio 0
	s_setprio 1
	v_mfma_f32_16x16x32_bf16 v[52:55], v[164:167], v[188:191], v[52:55]
	v_mfma_f32_16x16x32_bf16 v[52:55], v[168:171], v[216:219], v[52:55]
	v_mfma_f32_16x16x32_bf16 v[48:51], v[182:185], v[216:219], v[48:51]
	v_mfma_f32_16x16x32_bf16 v[48:51], v[172:175], v[188:191], v[48:51]
	v_mfma_f32_16x16x32_bf16 v[32:35], v[172:175], v[220:223], v[32:35]
	v_mfma_f32_16x16x32_bf16 v[32:35], v[182:185], v[224:227], v[32:35]
	v_mfma_f32_16x16x32_bf16 v[36:39], v[168:171], v[224:227], v[36:39]
	v_mfma_f32_16x16x32_bf16 v[36:39], v[164:167], v[220:223], v[36:39]
	v_mfma_f32_16x16x32_bf16 v[20:23], v[164:167], v[228:231], v[20:23]
	v_mfma_f32_16x16x32_bf16 v[20:23], v[168:171], v[232:235], v[20:23]
	v_mfma_f32_16x16x32_bf16 v[16:19], v[182:185], v[232:235], v[16:19]
	v_mfma_f32_16x16x32_bf16 v[16:19], v[172:175], v[228:231], v[16:19]
	v_mfma_f32_16x16x32_bf16 v[0:3], v[172:175], v[236:239], v[0:3]
	v_mfma_f32_16x16x32_bf16 v[0:3], v[182:185], v[240:243], v[0:3]
	v_mfma_f32_16x16x32_bf16 v[4:7], v[168:171], v[240:243], v[4:7]
	v_mfma_f32_16x16x32_bf16 v[4:7], v[164:167], v[236:239], v[4:7]
	s_setprio 0
	s_barrier
	s_add_i32 s67, 0, 0x18000
	v_add_u32_e32 v80, s67, v151
	s_add_i32 s68, 0, 0x1c000
	ds_read_b128 v[142:145], v80
	ds_read_b128 v[146:149], v80 offset:1024
	ds_read_b128 v[156:159], v80 offset:2048
	ds_read_b128 v[160:163], v80 offset:3072
	v_add_u32_e32 v80, s68, v151
	ds_read_b128 v[164:167], v80
	ds_read_b128 v[168:171], v80 offset:1024
	ds_read_b128 v[172:175], v80 offset:2048
	ds_read_b128 v[182:185], v80 offset:3072
	s_add_u32 s0, s50, 0x30000
	s_addc_u32 s1, s51, 0
	s_mov_b32 m0, s56
	v_lshl_add_u64 v[206:207], s[0:1], 0, v[130:131]
	ds_read_b128 v[188:191], v154 offset:32768
	ds_read_b128 v[216:219], v154 offset:33792
	ds_read_b128 v[220:223], v154 offset:34816
	ds_read_b128 v[224:227], v154 offset:35840
	ds_read_b128 v[228:231], v154 offset:36864
	ds_read_b128 v[232:235], v154 offset:37888
	ds_read_b128 v[236:239], v154 offset:38912
	ds_read_b128 v[240:243], v154 offset:39936
	global_load_lds_dwordx4 v[206:207], off
	v_lshl_add_u64 v[206:207], s[0:1], 0, v[134:135]
	s_mov_b32 m0, s57
	s_nop 0
	global_load_lds_dwordx4 v[206:207], off
	s_waitcnt vmcnt(8)
	s_waitcnt lgkmcnt(0)
	s_barrier
	s_setprio 1
	s_waitcnt lgkmcnt(0)
	v_mfma_f32_16x16x32_bf16 v[126:129], v[142:145], v[188:191], v[126:129]
	v_mfma_f32_16x16x32_bf16 v[126:129], v[146:149], v[216:219], v[126:129]
	v_mfma_f32_16x16x32_bf16 v[122:125], v[160:163], v[216:219], v[122:125]
	v_mfma_f32_16x16x32_bf16 v[122:125], v[156:159], v[188:191], v[122:125]
	v_mfma_f32_16x16x32_bf16 v[106:109], v[156:159], v[220:223], v[106:109]
	v_mfma_f32_16x16x32_bf16 v[106:109], v[160:163], v[224:227], v[106:109]
	v_mfma_f32_16x16x32_bf16 v[110:113], v[146:149], v[224:227], v[110:113]
	v_mfma_f32_16x16x32_bf16 v[110:113], v[142:145], v[220:223], v[110:113]
	v_mfma_f32_16x16x32_bf16 v[94:97], v[142:145], v[228:231], v[94:97]
	v_mfma_f32_16x16x32_bf16 v[94:97], v[146:149], v[232:235], v[94:97]
	v_mfma_f32_16x16x32_bf16 v[90:93], v[160:163], v[232:235], v[90:93]
	v_mfma_f32_16x16x32_bf16 v[90:93], v[156:159], v[228:231], v[90:93]
	v_mfma_f32_16x16x32_bf16 v[72:75], v[156:159], v[236:239], v[72:75]
	v_mfma_f32_16x16x32_bf16 v[72:75], v[160:163], v[240:243], v[72:75]
	v_mfma_f32_16x16x32_bf16 v[76:79], v[146:149], v[240:243], v[76:79]
	v_mfma_f32_16x16x32_bf16 v[76:79], v[142:145], v[236:239], v[76:79]
	s_setprio 0
	s_setprio 1
	v_mfma_f32_16x16x32_bf16 v[118:121], v[164:167], v[188:191], v[118:121]
	v_mfma_f32_16x16x32_bf16 v[118:121], v[168:171], v[216:219], v[118:121]
	v_mfma_f32_16x16x32_bf16 v[114:117], v[182:185], v[216:219], v[114:117]
	v_mfma_f32_16x16x32_bf16 v[114:117], v[172:175], v[188:191], v[114:117]
	v_mfma_f32_16x16x32_bf16 v[98:101], v[172:175], v[220:223], v[98:101]
	v_mfma_f32_16x16x32_bf16 v[98:101], v[182:185], v[224:227], v[98:101]
	v_mfma_f32_16x16x32_bf16 v[102:105], v[168:171], v[224:227], v[102:105]
	v_mfma_f32_16x16x32_bf16 v[102:105], v[164:167], v[220:223], v[102:105]
	v_mfma_f32_16x16x32_bf16 v[86:89], v[164:167], v[228:231], v[86:89]
	v_mfma_f32_16x16x32_bf16 v[86:89], v[168:171], v[232:235], v[86:89]
	v_mfma_f32_16x16x32_bf16 v[82:85], v[182:185], v[232:235], v[82:85]
	v_mfma_f32_16x16x32_bf16 v[82:85], v[172:175], v[228:231], v[82:85]
	v_mfma_f32_16x16x32_bf16 v[64:67], v[172:175], v[236:239], v[64:67]
	v_mfma_f32_16x16x32_bf16 v[64:67], v[182:185], v[240:243], v[64:67]
	v_mfma_f32_16x16x32_bf16 v[68:71], v[168:171], v[240:243], v[68:71]
	v_mfma_f32_16x16x32_bf16 v[68:71], v[164:167], v[236:239], v[68:71]
	s_setprio 0
	s_barrier
; #define PG8_STAGE(bufoff, gbase, voff) do { _Pragma("unroll") for (int _i = 0; _i < 2; ++_i) \
;         __builtin_amdgcn_global_load_lds((const unsigned*)((const char*)(gbase) + (voff)[_i]), (PG8_LAS unsigned*)(lds + (bufoff) + ldsw + _i * 8192), 16, 0, 0); } while (0)
; #define PG8_LDA(dst, b, h) do { _Pragma("unroll") for (int m = 0; m < 4; ++m) _Pragma("unroll") for (int k = 0; k < 2; ++k) dst[m][k] = *(const PG8_LAS bf16x8*)(lds + PG8_SA(b, h) + aoff + m * 2048 + k * 1024); } while (0)
; #define PG8_MMA(ai, bj, At, Bt) do { __builtin_amdgcn_s_setprio(1); _Pragma("unroll") for (int m = 0; m < 4; ++m) _Pragma("unroll") for (int n = 0; n < 2; ++n) _Pragma("unroll") for (int k = 0; k < 2; ++k) \
;         acc[ai][bj][m][n] = __builtin_amdgcn_mfma_f32_16x16x32_bf16(Bt[n][k], At[m][k], acc[ai][bj][m][n], 0, 0, 0); __builtin_amdgcn_s_setprio(0); } while (0)
; #define PG8_WAIT_V(n) asm volatile("s_waitcnt vmcnt(" #n ")" ::: "memory")
; #define PG8_WAIT_L(n) asm volatile("s_waitcnt lgkmcnt(" #n ")" ::: "memory")
; #define PG8_BAR __builtin_amdgcn_s_barrier()
; #define PG8_SCHED __builtin_amdgcn_sched_barrier(0)
; template <class Epi, class Sched, bool ALIGN_EPI = false, bool SP2 = false>
; __device__ __forceinline__ void gemm_phase(PG8_LAS unsigned char* lds, const Gemm g, const Sched& S, const Epi& E) {
;     ...
;             PG8_LDA(At, 1, 1); PG8_STAGE(PG8_SB(1, 0), b3, voffB); PG8_STAGE(PG8_SB(1, 1), b3 + hstepB, voffB); PG8_STAGE(PG8_SA(1, 0), a3, voffA);
;             PG8_WAIT_V(8); PG8_WAIT_L(0); PG8_BAR; PG8_MMA(1, 0, At, B0); PG8_MMA(1, 1, At, B1); PG8_BAR; PG8_SCHED;
;     ...
;         if constexpr (ALIGN_EPI) { if (wr == 0) PG8_BAR; }
	s_add_i32 s0, s67, s52
	v_lshl_add_u64 v[176:177], v[176:177], 0, s[60:61]
	s_mov_b32 m0, s0
	ds_read_b128 v[188:191], v154 offset:49152
	ds_read_b128 v[216:219], v154 offset:50176
	ds_read_b128 v[220:223], v154 offset:51200
	ds_read_b128 v[224:227], v154 offset:52224
	ds_read_b128 v[228:231], v154 offset:53248
	ds_read_b128 v[232:235], v154 offset:54272
	ds_read_b128 v[236:239], v154 offset:55296
	ds_read_b128 v[240:243], v154 offset:56320
	global_load_lds_dwordx4 v[176:177], off
	s_add_i32 m0, s0, 0x2000
	s_add_u32 s0, s22, 0x30080
	v_lshl_add_u64 v[176:177], v[192:193], 0, s[60:61]
	s_addc_u32 s1, s23, 0
	s_add_i32 s22, s68, s52
	global_load_lds_dwordx4 v[176:177], off
	v_lshl_add_u64 v[176:177], s[0:1], 0, v[132:133]
	s_mov_b32 m0, s22
	s_nop 0
	global_load_lds_dwordx4 v[176:177], off
	v_lshl_add_u64 v[176:177], s[0:1], 0, v[136:137]
	s_add_i32 m0, s22, 0x2000
	s_nop 0
	global_load_lds_dwordx4 v[176:177], off
	v_lshl_add_u64 v[176:177], v[202:203], 0, s[60:61]
	s_mov_b32 m0, s62
	s_nop 0
	global_load_lds_dwordx4 v[176:177], off
	v_lshl_add_u64 v[176:177], v[204:205], 0, s[60:61]
	s_mov_b32 m0, s63
	s_nop 0
	global_load_lds_dwordx4 v[176:177], off
	s_waitcnt vmcnt(8)
	s_waitcnt lgkmcnt(0)
	s_barrier
	s_setprio 1
	s_waitcnt lgkmcnt(0)
	v_mfma_f32_16x16x32_bf16 v[60:63], v[142:145], v[188:191], v[60:63]
	v_mfma_f32_16x16x32_bf16 v[60:63], v[146:149], v[216:219], v[60:63]
	v_mfma_f32_16x16x32_bf16 v[56:59], v[160:163], v[216:219], v[56:59]
	v_mfma_f32_16x16x32_bf16 v[56:59], v[156:159], v[188:191], v[56:59]
	v_mfma_f32_16x16x32_bf16 v[40:43], v[156:159], v[220:223], v[40:43]
	v_mfma_f32_16x16x32_bf16 v[40:43], v[160:163], v[224:227], v[40:43]
	v_mfma_f32_16x16x32_bf16 v[44:47], v[146:149], v[224:227], v[44:47]
	v_mfma_f32_16x16x32_bf16 v[44:47], v[142:145], v[220:223], v[44:47]
	v_mfma_f32_16x16x32_bf16 v[28:31], v[142:145], v[228:231], v[28:31]
	v_mfma_f32_16x16x32_bf16 v[28:31], v[146:149], v[232:235], v[28:31]
	v_mfma_f32_16x16x32_bf16 v[24:27], v[160:163], v[232:235], v[24:27]
	v_mfma_f32_16x16x32_bf16 v[24:27], v[156:159], v[228:231], v[24:27]
	v_mfma_f32_16x16x32_bf16 v[8:11], v[156:159], v[236:239], v[8:11]
	v_mfma_f32_16x16x32_bf16 v[8:11], v[160:163], v[240:243], v[8:11]
	v_mfma_f32_16x16x32_bf16 v[12:15], v[146:149], v[240:243], v[12:15]
	v_mfma_f32_16x16x32_bf16 v[12:15], v[142:145], v[236:239], v[12:15]
	s_setprio 0
	s_setprio 1
	v_mfma_f32_16x16x32_bf16 v[52:55], v[164:167], v[188:191], v[52:55]
	v_mfma_f32_16x16x32_bf16 v[52:55], v[168:171], v[216:219], v[52:55]
	v_mfma_f32_16x16x32_bf16 v[48:51], v[182:185], v[216:219], v[48:51]
	v_mfma_f32_16x16x32_bf16 v[48:51], v[172:175], v[188:191], v[48:51]
	v_mfma_f32_16x16x32_bf16 v[32:35], v[172:175], v[220:223], v[32:35]
	v_mfma_f32_16x16x32_bf16 v[32:35], v[182:185], v[224:227], v[32:35]
	v_mfma_f32_16x16x32_bf16 v[36:39], v[168:171], v[224:227], v[36:39]
	v_mfma_f32_16x16x32_bf16 v[36:39], v[164:167], v[220:223], v[36:39]
	v_mfma_f32_16x16x32_bf16 v[20:23], v[164:167], v[228:231], v[20:23]
	v_mfma_f32_16x16x32_bf16 v[20:23], v[168:171], v[232:235], v[20:23]
	v_mfma_f32_16x16x32_bf16 v[16:19], v[182:185], v[232:235], v[16:19]
	v_mfma_f32_16x16x32_bf16 v[16:19], v[172:175], v[228:231], v[16:19]
	v_mfma_f32_16x16x32_bf16 v[0:3], v[172:175], v[236:239], v[0:3]
	v_mfma_f32_16x16x32_bf16 v[0:3], v[182:185], v[240:243], v[0:3]
	v_mfma_f32_16x16x32_bf16 v[4:7], v[168:171], v[240:243], v[4:7]
	v_mfma_f32_16x16x32_bf16 v[4:7], v[164:167], v[236:239], v[4:7]
	s_setprio 0
	s_barrier
	s_add_i32 s37, s37, 2
	s_add_u32 s35, s35, 0x100
	s_addc_u32 s36, s36, 0
	s_cmp_gt_u32 s37, 9
	s_mov_b64 s[0:1], s[20:21]
	s_cbranch_scc0 .LBB0_868
	s_and_b64 vcc, exec, s[44:45]
	s_cbranch_vccz .LBB0_871
	s_barrier

; #define PG8_STAGE(bufoff, gbase, voff) do { _Pragma("unroll") for (int _i = 0; _i < 2; ++_i) \
;         __builtin_amdgcn_global_load_lds((const unsigned*)((const char*)(gbase) + (voff)[_i]), (PG8_LAS unsigned*)(lds + (bufoff) + ldsw + _i * 8192), 16, 0, 0); } while (0)
; #define PG8_LDA(dst, b, h) do { _Pragma("unroll") for (int m = 0; m < 4; ++m) _Pragma("unroll") for (int k = 0; k < 2; ++k) dst[m][k] = *(const PG8_LAS bf16x8*)(lds + PG8_SA(b, h) + aoff + m * 2048 + k * 1024); } while (0)
; #define PG8_LDB(dst, b, h) do { _Pragma("unroll") for (int n = 0; n < 2; ++n) _Pragma("unroll") for (int k = 0; k < 2; ++k) dst[n][k] = *(const PG8_LAS bf16x8*)(lds + PG8_SB(b, h) + boff + n * 2048 + k * 1024); } while (0)
; #define PG8_MMA(ai, bj, At, Bt) do { __builtin_amdgcn_s_setprio(1); _Pragma("unroll") for (int m = 0; m < 4; ++m) _Pragma("unroll") for (int n = 0; n < 2; ++n) _Pragma("unroll") for (int k = 0; k < 2; ++k) \
;         acc[ai][bj][m][n] = __builtin_amdgcn_mfma_f32_16x16x32_bf16(Bt[n][k], At[m][k], acc[ai][bj][m][n], 0, 0, 0); __builtin_amdgcn_s_setprio(0); } while (0)
; #define PG8_BAR __builtin_amdgcn_s_barrier()
; template <class Epi, class Sched, bool ALIGN_EPI = false, bool SP2 = false>
; __device__ __forceinline__ void gemm_phase(PG8_LAS unsigned char* lds, const Gemm g, const Sched& S, const Epi& E) {
;     ...
;         for (int t = 0; t < nt; t += 2) {
;             if constexpr (Epi::MIDSCALE) { if (t == (nt >> 1)) E.mid(acc, cur, wr, fr); }
;             const bool last = (t == nt - 2);
;             const char* a1 = cA + (size_t)(t + 1) * kstep;
;             const char* a2 = last ? nA : cA + (size_t)(t + 2) * kstep; const char* b2 = last ? nB : cB + (size_t)(t + 2) * kstep;
;             const char* a3 = a2 + kstep; const char* b3 = b2 + kstep;
;             if (last && has_next) S.a_ready(nxt);
;             if constexpr (SP2) {
;             PG8_LDB(B0, 0, 0); PG8_LDB(B1, 0, 1); PG8_SCHED; PG8_LDA(At, 0, 0); PG8_STAGE(PG8_SA(1, 1), a1 + hstepA, voffA);
;             PG8_WAIT_V(8); PG8_WAIT_L(0); PG8_BAR; PG8_MMA(0, 0, At, B0); PG8_MMA(0, 1, At, B1); PG8_BAR; PG8_SCHED;
;             PG8_LDA(At, 0, 1); PG8_STAGE(PG8_SB(0, 0), b2, voffB); PG8_STAGE(PG8_SB(0, 1), b2 + hstepB, voffB); PG8_STAGE(PG8_SA(0, 0), a2, voffA);
;             PG8_WAIT_V(8); PG8_WAIT_L(0); PG8_BAR; PG8_MMA(1, 0, At, B0); PG8_MMA(1, 1, At, B1); PG8_BAR; PG8_SCHED;
.LBB0_952:
	s_add_u32 s20, s0, 0xfffc0080
	s_addc_u32 s21, s1, -1
	s_add_i32 s51, 0, 0x10000
	s_cmp_eq_u32 s49, 12
	s_cselect_b32 s23, s28, s21
	s_cselect_b32 s22, s33, s20
	v_add_u32_e32 v148, s51, v152
	s_cselect_b32 s21, s35, s47
	s_cselect_b32 s20, s36, s37
	s_add_i32 s53, 0, 0x14000
	ds_read_b128 v[140:143], v148
	ds_read_b128 v[144:147], v148 offset:1024
	ds_read_b128 v[154:157], v148 offset:2048
	ds_read_b128 v[158:161], v148 offset:3072
	v_add_u32_e32 v148, s53, v152
	ds_read_b128 v[162:165], v148
	ds_read_b128 v[166:169], v148 offset:1024
	ds_read_b128 v[170:173], v148 offset:2048
	ds_read_b128 v[174:177], v148 offset:3072
	v_lshl_add_u64 v[148:149], s[0:1], 0, v[136:137]
	s_add_i32 m0, s56, 0xc000
	ds_read_b128 v[182:185], v153
	ds_read_b128 v[188:191], v153 offset:1024
	ds_read_b128 v[216:219], v153 offset:2048
	ds_read_b128 v[220:223], v153 offset:3072
	ds_read_b128 v[224:227], v153 offset:4096
	ds_read_b128 v[228:231], v153 offset:5120
	ds_read_b128 v[232:235], v153 offset:6144
	ds_read_b128 v[236:239], v153 offset:7168
	global_load_lds_dwordx4 v[148:149], off
	v_lshl_add_u64 v[148:149], s[0:1], 0, v[138:139]
	s_add_i32 m0, s56, 0xe000
	s_nop 0
	global_load_lds_dwordx4 v[148:149], off
	s_waitcnt vmcnt(8)
	s_waitcnt lgkmcnt(0)
	s_barrier
	s_setprio 1
	s_waitcnt lgkmcnt(0)
	v_mfma_f32_16x16x32_bf16 v[126:129], v[140:143], v[182:185], v[126:129]
	v_mfma_f32_16x16x32_bf16 v[126:129], v[144:147], v[188:191], v[126:129]
	v_mfma_f32_16x16x32_bf16 v[122:125], v[158:161], v[188:191], v[122:125]
	v_mfma_f32_16x16x32_bf16 v[122:125], v[154:157], v[182:185], v[122:125]
	v_mfma_f32_16x16x32_bf16 v[106:109], v[154:157], v[216:219], v[106:109]
	v_mfma_f32_16x16x32_bf16 v[106:109], v[158:161], v[220:223], v[106:109]
	v_mfma_f32_16x16x32_bf16 v[110:113], v[144:147], v[220:223], v[110:113]
	v_mfma_f32_16x16x32_bf16 v[110:113], v[140:143], v[216:219], v[110:113]
	v_mfma_f32_16x16x32_bf16 v[94:97], v[140:143], v[224:227], v[94:97]
	v_mfma_f32_16x16x32_bf16 v[94:97], v[144:147], v[228:231], v[94:97]
	v_mfma_f32_16x16x32_bf16 v[90:93], v[158:161], v[228:231], v[90:93]
	v_mfma_f32_16x16x32_bf16 v[90:93], v[154:157], v[224:227], v[90:93]
	v_mfma_f32_16x16x32_bf16 v[72:75], v[154:157], v[232:235], v[72:75]
	v_mfma_f32_16x16x32_bf16 v[72:75], v[158:161], v[236:239], v[72:75]
	v_mfma_f32_16x16x32_bf16 v[76:79], v[144:147], v[236:239], v[76:79]
	v_mfma_f32_16x16x32_bf16 v[76:79], v[140:143], v[232:235], v[76:79]
	s_setprio 0
	s_setprio 1
	v_mfma_f32_16x16x32_bf16 v[118:121], v[162:165], v[182:185], v[118:121]
	v_mfma_f32_16x16x32_bf16 v[118:121], v[166:169], v[188:191], v[118:121]
	v_mfma_f32_16x16x32_bf16 v[114:117], v[174:177], v[188:191], v[114:117]
	v_mfma_f32_16x16x32_bf16 v[114:117], v[170:173], v[182:185], v[114:117]
	v_mfma_f32_16x16x32_bf16 v[98:101], v[170:173], v[216:219], v[98:101]
	v_mfma_f32_16x16x32_bf16 v[98:101], v[174:177], v[220:223], v[98:101]
	v_mfma_f32_16x16x32_bf16 v[102:105], v[166:169], v[220:223], v[102:105]
	v_mfma_f32_16x16x32_bf16 v[102:105], v[162:165], v[216:219], v[102:105]
	v_mfma_f32_16x16x32_bf16 v[86:89], v[162:165], v[224:227], v[86:89]
	v_mfma_f32_16x16x32_bf16 v[86:89], v[166:169], v[228:231], v[86:89]
	v_mfma_f32_16x16x32_bf16 v[82:85], v[174:177], v[228:231], v[82:85]
	v_mfma_f32_16x16x32_bf16 v[82:85], v[170:173], v[224:227], v[82:85]
	v_mfma_f32_16x16x32_bf16 v[64:67], v[170:173], v[232:235], v[64:67]
	v_mfma_f32_16x16x32_bf16 v[64:67], v[174:177], v[236:239], v[64:67]
	v_mfma_f32_16x16x32_bf16 v[68:71], v[166:169], v[236:239], v[68:71]
	v_mfma_f32_16x16x32_bf16 v[68:71], v[162:165], v[232:235], v[68:71]
	s_setprio 0
	s_barrier
	s_add_i32 s51, s51, s55
	v_lshl_add_u64 v[148:149], s[20:21], 0, v[80:81]
	s_mov_b32 m0, s51
	ds_read_b128 v[182:185], v153 offset:16384
	ds_read_b128 v[188:191], v153 offset:17408
	ds_read_b128 v[216:219], v153 offset:18432
	ds_read_b128 v[220:223], v153 offset:19456
	ds_read_b128 v[224:227], v153 offset:20480
	ds_read_b128 v[228:231], v153 offset:21504
	ds_read_b128 v[232:235], v153 offset:22528
	ds_read_b128 v[236:239], v153 offset:23552
	global_load_lds_dwordx4 v[148:149], off
	s_add_i32 m0, s51, 0x2000
	s_add_u32 s72, s20, 0x40000
	v_lshl_add_u64 v[192:193], s[20:21], 0, v[130:131]
	s_addc_u32 s73, s21, 0
	s_add_i32 s51, s53, s55
	global_load_lds_dwordx4 v[192:193], off
	v_lshl_add_u64 v[202:203], s[72:73], 0, v[80:81]
	s_mov_b32 m0, s51
	v_lshl_add_u64 v[204:205], s[22:23], 0, v[132:133]
	global_load_lds_dwordx4 v[202:203], off
	v_lshl_add_u64 v[202:203], s[72:73], 0, v[130:131]
	s_add_i32 m0, s51, 0x2000
	s_nop 0
	global_load_lds_dwordx4 v[202:203], off
	v_lshl_add_u64 v[202:203], s[22:23], 0, v[134:135]
	s_mov_b32 m0, s56
	s_nop 0
	global_load_lds_dwordx4 v[202:203], off
	s_mov_b32 m0, s57
	s_nop 0
	global_load_lds_dwordx4 v[204:205], off
	s_waitcnt vmcnt(8)
	s_waitcnt lgkmcnt(0)
	s_barrier
; #define PG8_STAGE(bufoff, gbase, voff) do { _Pragma("unroll") for (int _i = 0; _i < 2; ++_i) \
;         __builtin_amdgcn_global_load_lds((const unsigned*)((const char*)(gbase) + (voff)[_i]), (PG8_LAS unsigned*)(lds + (bufoff) + ldsw + _i * 8192), 16, 0, 0); } while (0)
; #define PG8_LDA(dst, b, h) do { _Pragma("unroll") for (int m = 0; m < 4; ++m) _Pragma("unroll") for (int k = 0; k < 2; ++k) dst[m][k] = *(const PG8_LAS bf16x8*)(lds + PG8_SA(b, h) + aoff + m * 2048 + k * 1024); } while (0)
; #define PG8_LDB(dst, b, h) do { _Pragma("unroll") for (int n = 0; n < 2; ++n) _Pragma("unroll") for (int k = 0; k < 2; ++k) dst[n][k] = *(const PG8_LAS bf16x8*)(lds + PG8_SB(b, h) + boff + n * 2048 + k * 1024); } while (0)
; #define PG8_MMA(ai, bj, At, Bt) do { __builtin_amdgcn_s_setprio(1); _Pragma("unroll") for (int m = 0; m < 4; ++m) _Pragma("unroll") for (int n = 0; n < 2; ++n) _Pragma("unroll") for (int k = 0; k < 2; ++k) \
;         acc[ai][bj][m][n] = __builtin_amdgcn_mfma_f32_16x16x32_bf16(Bt[n][k], At[m][k], acc[ai][bj][m][n], 0, 0, 0); __builtin_amdgcn_s_setprio(0); } while (0)
; #define PG8_WAIT_V(n) asm volatile("s_waitcnt vmcnt(" #n ")" ::: "memory")
; #define PG8_WAIT_L(n) asm volatile("s_waitcnt lgkmcnt(" #n ")" ::: "memory")
; #define PG8_BAR __builtin_amdgcn_s_barrier()
; #define PG8_SCHED __builtin_amdgcn_sched_barrier(0)
; template <class Epi, class Sched, bool ALIGN_EPI = false, bool SP2 = false>
; __device__ __forceinline__ void gemm_phase(PG8_LAS unsigned char* lds, const Gemm g, const Sched& S, const Epi& E) {
;     ...
;             PG8_WAIT_V(8); PG8_WAIT_L(0); PG8_BAR; PG8_MMA(1, 0, At, B0); PG8_MMA(1, 1, At, B1); PG8_BAR; PG8_SCHED;
;             PG8_LDB(B0, 1, 0); PG8_LDB(B1, 1, 1); PG8_SCHED; PG8_LDA(At, 1, 0); PG8_STAGE(PG8_SA(0, 1), a2 + hstepA, voffA);
;             PG8_WAIT_V(8); PG8_WAIT_L(0); PG8_BAR; PG8_MMA(0, 0, At, B0); PG8_MMA(0, 1, At, B1); PG8_BAR; PG8_SCHED;
	s_setprio 1
	s_waitcnt lgkmcnt(0)
	v_mfma_f32_16x16x32_bf16 v[60:63], v[140:143], v[182:185], v[60:63]
	v_mfma_f32_16x16x32_bf16 v[60:63], v[144:147], v[188:191], v[60:63]
	v_mfma_f32_16x16x32_bf16 v[56:59], v[158:161], v[188:191], v[56:59]
	v_mfma_f32_16x16x32_bf16 v[56:59], v[154:157], v[182:185], v[56:59]
	v_mfma_f32_16x16x32_bf16 v[40:43], v[154:157], v[216:219], v[40:43]
	v_mfma_f32_16x16x32_bf16 v[40:43], v[158:161], v[220:223], v[40:43]
	v_mfma_f32_16x16x32_bf16 v[44:47], v[144:147], v[220:223], v[44:47]
	v_mfma_f32_16x16x32_bf16 v[44:47], v[140:143], v[216:219], v[44:47]
	v_mfma_f32_16x16x32_bf16 v[28:31], v[140:143], v[224:227], v[28:31]
	v_mfma_f32_16x16x32_bf16 v[28:31], v[144:147], v[228:231], v[28:31]
	v_mfma_f32_16x16x32_bf16 v[24:27], v[158:161], v[228:231], v[24:27]
	v_mfma_f32_16x16x32_bf16 v[24:27], v[154:157], v[224:227], v[24:27]
	v_mfma_f32_16x16x32_bf16 v[8:11], v[154:157], v[232:235], v[8:11]
	v_mfma_f32_16x16x32_bf16 v[8:11], v[158:161], v[236:239], v[8:11]
	v_mfma_f32_16x16x32_bf16 v[12:15], v[144:147], v[236:239], v[12:15]
	v_mfma_f32_16x16x32_bf16 v[12:15], v[140:143], v[232:235], v[12:15]
	s_setprio 0
	s_setprio 1
	v_mfma_f32_16x16x32_bf16 v[52:55], v[162:165], v[182:185], v[52:55]
	v_mfma_f32_16x16x32_bf16 v[52:55], v[166:169], v[188:191], v[52:55]
	v_mfma_f32_16x16x32_bf16 v[48:51], v[174:177], v[188:191], v[48:51]
	v_mfma_f32_16x16x32_bf16 v[48:51], v[170:173], v[182:185], v[48:51]
	v_mfma_f32_16x16x32_bf16 v[32:35], v[170:173], v[216:219], v[32:35]
	v_mfma_f32_16x16x32_bf16 v[32:35], v[174:177], v[220:223], v[32:35]
	v_mfma_f32_16x16x32_bf16 v[36:39], v[166:169], v[220:223], v[36:39]
	v_mfma_f32_16x16x32_bf16 v[36:39], v[162:165], v[216:219], v[36:39]
	v_mfma_f32_16x16x32_bf16 v[20:23], v[162:165], v[224:227], v[20:23]
	v_mfma_f32_16x16x32_bf16 v[20:23], v[166:169], v[228:231], v[20:23]
	v_mfma_f32_16x16x32_bf16 v[16:19], v[174:177], v[228:231], v[16:19]
	v_mfma_f32_16x16x32_bf16 v[16:19], v[170:173], v[224:227], v[16:19]
	v_mfma_f32_16x16x32_bf16 v[0:3], v[170:173], v[232:235], v[0:3]
	v_mfma_f32_16x16x32_bf16 v[0:3], v[174:177], v[236:239], v[0:3]
	v_mfma_f32_16x16x32_bf16 v[4:7], v[166:169], v[236:239], v[4:7]
	v_mfma_f32_16x16x32_bf16 v[4:7], v[162:165], v[232:235], v[4:7]
	s_setprio 0
	s_barrier
	s_add_i32 s51, 0, 0x18000
	s_add_i32 s53, 0, 0x1c000
	v_add_u32_e32 v158, s51, v152
	v_add_u32_e32 v174, s53, v152
	ds_read_b128 v[140:143], v158
	ds_read_b128 v[144:147], v158 offset:1024
	ds_read_b128 v[154:157], v158 offset:2048
	ds_read_b128 v[158:161], v158 offset:3072
	ds_read_b128 v[162:165], v174
	ds_read_b128 v[166:169], v174 offset:1024
	ds_read_b128 v[170:173], v174 offset:2048
	ds_read_b128 v[174:177], v174 offset:3072
	s_add_u32 s22, s22, 0x40000
	s_addc_u32 s23, s23, 0
	s_mov_b32 m0, s62
	v_lshl_add_u64 v[206:207], s[22:23], 0, v[134:135]
	ds_read_b128 v[182:185], v153 offset:32768
	ds_read_b128 v[188:191], v153 offset:33792
	ds_read_b128 v[216:219], v153 offset:34816
	ds_read_b128 v[220:223], v153 offset:35840
	ds_read_b128 v[224:227], v153 offset:36864
	ds_read_b128 v[228:231], v153 offset:37888
	ds_read_b128 v[232:235], v153 offset:38912
	ds_read_b128 v[236:239], v153 offset:39936
	global_load_lds_dwordx4 v[206:207], off
	v_lshl_add_u64 v[206:207], s[22:23], 0, v[132:133]
	s_mov_b32 m0, s63
	s_nop 0
	global_load_lds_dwordx4 v[206:207], off
	s_waitcnt vmcnt(8)
	s_waitcnt lgkmcnt(0)
	s_barrier
	s_setprio 1
	s_waitcnt lgkmcnt(0)
	v_mfma_f32_16x16x32_bf16 v[126:129], v[140:143], v[182:185], v[126:129]
	v_mfma_f32_16x16x32_bf16 v[126:129], v[144:147], v[188:191], v[126:129]
	v_mfma_f32_16x16x32_bf16 v[122:125], v[158:161], v[188:191], v[122:125]
	v_mfma_f32_16x16x32_bf16 v[122:125], v[154:157], v[182:185], v[122:125]
	v_mfma_f32_16x16x32_bf16 v[106:109], v[154:157], v[216:219], v[106:109]
	v_mfma_f32_16x16x32_bf16 v[106:109], v[158:161], v[220:223], v[106:109]
	v_mfma_f32_16x16x32_bf16 v[110:113], v[144:147], v[220:223], v[110:113]
	v_mfma_f32_16x16x32_bf16 v[110:113], v[140:143], v[216:219], v[110:113]
	v_mfma_f32_16x16x32_bf16 v[94:97], v[140:143], v[224:227], v[94:97]
	v_mfma_f32_16x16x32_bf16 v[94:97], v[144:147], v[228:231], v[94:97]
	v_mfma_f32_16x16x32_bf16 v[90:93], v[158:161], v[228:231], v[90:93]
	v_mfma_f32_16x16x32_bf16 v[90:93], v[154:157], v[224:227], v[90:93]
	v_mfma_f32_16x16x32_bf16 v[72:75], v[154:157], v[232:235], v[72:75]
	v_mfma_f32_16x16x32_bf16 v[72:75], v[158:161], v[236:239], v[72:75]
	v_mfma_f32_16x16x32_bf16 v[76:79], v[144:147], v[236:239], v[76:79]
	v_mfma_f32_16x16x32_bf16 v[76:79], v[140:143], v[232:235], v[76:79]
	s_setprio 0
	s_setprio 1
	v_mfma_f32_16x16x32_bf16 v[118:121], v[162:165], v[182:185], v[118:121]
	v_mfma_f32_16x16x32_bf16 v[118:121], v[166:169], v[188:191], v[118:121]
	v_mfma_f32_16x16x32_bf16 v[114:117], v[174:177], v[188:191], v[114:117]
	v_mfma_f32_16x16x32_bf16 v[114:117], v[170:173], v[182:185], v[114:117]
	v_mfma_f32_16x16x32_bf16 v[98:101], v[170:173], v[216:219], v[98:101]
	v_mfma_f32_16x16x32_bf16 v[98:101], v[174:177], v[220:223], v[98:101]
	v_mfma_f32_16x16x32_bf16 v[102:105], v[166:169], v[220:223], v[102:105]
	v_mfma_f32_16x16x32_bf16 v[102:105], v[162:165], v[216:219], v[102:105]
	v_mfma_f32_16x16x32_bf16 v[86:89], v[162:165], v[224:227], v[86:89]
	v_mfma_f32_16x16x32_bf16 v[86:89], v[166:169], v[228:231], v[86:89]
	v_mfma_f32_16x16x32_bf16 v[82:85], v[174:177], v[228:231], v[82:85]
	v_mfma_f32_16x16x32_bf16 v[82:85], v[170:173], v[224:227], v[82:85]
	v_mfma_f32_16x16x32_bf16 v[64:67], v[170:173], v[232:235], v[64:67]
	v_mfma_f32_16x16x32_bf16 v[64:67], v[174:177], v[236:239], v[64:67]
	v_mfma_f32_16x16x32_bf16 v[68:71], v[166:169], v[236:239], v[68:71]
	v_mfma_f32_16x16x32_bf16 v[68:71], v[162:165], v[232:235], v[68:71]
	s_setprio 0
	s_barrier
; #define PG8_STAGE(bufoff, gbase, voff) do { _Pragma("unroll") for (int _i = 0; _i < 2; ++_i) \
;         __builtin_amdgcn_global_load_lds((const unsigned*)((const char*)(gbase) + (voff)[_i]), (PG8_LAS unsigned*)(lds + (bufoff) + ldsw + _i * 8192), 16, 0, 0); } while (0)
; #define PG8_LDA(dst, b, h) do { _Pragma("unroll") for (int m = 0; m < 4; ++m) _Pragma("unroll") for (int k = 0; k < 2; ++k) dst[m][k] = *(const PG8_LAS bf16x8*)(lds + PG8_SA(b, h) + aoff + m * 2048 + k * 1024); } while (0)
; #define PG8_MMA(ai, bj, At, Bt) do { __builtin_amdgcn_s_setprio(1); _Pragma("unroll") for (int m = 0; m < 4; ++m) _Pragma("unroll") for (int n = 0; n < 2; ++n) _Pragma("unroll") for (int k = 0; k < 2; ++k) \
;         acc[ai][bj][m][n] = __builtin_amdgcn_mfma_f32_16x16x32_bf16(Bt[n][k], At[m][k], acc[ai][bj][m][n], 0, 0, 0); __builtin_amdgcn_s_setprio(0); } while (0)
; #define PG8_WAIT_V(n) asm volatile("s_waitcnt vmcnt(" #n ")" ::: "memory")
; #define PG8_WAIT_L(n) asm volatile("s_waitcnt lgkmcnt(" #n ")" ::: "memory")
; #define PG8_BAR __builtin_amdgcn_s_barrier()
; #define PG8_SCHED __builtin_amdgcn_sched_barrier(0)
; template <class Epi, class Sched, bool ALIGN_EPI = false, bool SP2 = false>
; __device__ __forceinline__ void gemm_phase(PG8_LAS unsigned char* lds, const Gemm g, const Sched& S, const Epi& E) {
;     ...
;             PG8_LDA(At, 1, 1); PG8_STAGE(PG8_SB(1, 0), b3, voffB); PG8_STAGE(PG8_SB(1, 1), b3 + hstepB, voffB); PG8_STAGE(PG8_SA(1, 0), a3, voffA);
;             PG8_WAIT_V(8); PG8_WAIT_L(0); PG8_BAR; PG8_MMA(1, 0, At, B0); PG8_MMA(1, 1, At, B1); PG8_BAR; PG8_SCHED;
;     ...
;         if constexpr (ALIGN_EPI) { if (wr == 0) PG8_BAR; }
	s_add_i32 s22, s51, s55
	v_lshl_add_u64 v[148:149], v[148:149], 0, s[60:61]
	s_mov_b32 m0, s22
	ds_read_b128 v[182:185], v153 offset:49152
	ds_read_b128 v[188:191], v153 offset:50176
	ds_read_b128 v[216:219], v153 offset:51200
	ds_read_b128 v[220:223], v153 offset:52224
	ds_read_b128 v[224:227], v153 offset:53248
	ds_read_b128 v[228:231], v153 offset:54272
	ds_read_b128 v[232:235], v153 offset:55296
	ds_read_b128 v[236:239], v153 offset:56320
	global_load_lds_dwordx4 v[148:149], off
	s_add_i32 m0, s22, 0x2000
	s_add_u32 s20, s20, 0x40080
	v_lshl_add_u64 v[148:149], v[192:193], 0, s[60:61]
	s_addc_u32 s21, s21, 0
	s_add_i32 s22, s53, s55
	global_load_lds_dwordx4 v[148:149], off
	v_lshl_add_u64 v[148:149], s[20:21], 0, v[80:81]
	s_mov_b32 m0, s22
	s_nop 0
	global_load_lds_dwordx4 v[148:149], off
	v_lshl_add_u64 v[148:149], s[20:21], 0, v[130:131]
	s_add_i32 m0, s22, 0x2000
	s_nop 0
	global_load_lds_dwordx4 v[148:149], off
	v_lshl_add_u64 v[148:149], v[202:203], 0, s[60:61]
	s_mov_b32 m0, s66
	s_nop 0
	global_load_lds_dwordx4 v[148:149], off
	v_lshl_add_u64 v[148:149], v[204:205], 0, s[60:61]
	s_mov_b32 m0, s67
	s_nop 0
	global_load_lds_dwordx4 v[148:149], off
	s_waitcnt vmcnt(8)
	s_waitcnt lgkmcnt(0)
	s_barrier
	s_setprio 1
	s_waitcnt lgkmcnt(0)
	v_mfma_f32_16x16x32_bf16 v[60:63], v[140:143], v[182:185], v[60:63]
	v_mfma_f32_16x16x32_bf16 v[60:63], v[144:147], v[188:191], v[60:63]
	v_mfma_f32_16x16x32_bf16 v[56:59], v[158:161], v[188:191], v[56:59]
	v_mfma_f32_16x16x32_bf16 v[56:59], v[154:157], v[182:185], v[56:59]
	v_mfma_f32_16x16x32_bf16 v[40:43], v[154:157], v[216:219], v[40:43]
	v_mfma_f32_16x16x32_bf16 v[40:43], v[158:161], v[220:223], v[40:43]
	v_mfma_f32_16x16x32_bf16 v[44:47], v[144:147], v[220:223], v[44:47]
	v_mfma_f32_16x16x32_bf16 v[44:47], v[140:143], v[216:219], v[44:47]
	v_mfma_f32_16x16x32_bf16 v[28:31], v[140:143], v[224:227], v[28:31]
	v_mfma_f32_16x16x32_bf16 v[28:31], v[144:147], v[228:231], v[28:31]
	v_mfma_f32_16x16x32_bf16 v[24:27], v[158:161], v[228:231], v[24:27]
	v_mfma_f32_16x16x32_bf16 v[24:27], v[154:157], v[224:227], v[24:27]
	v_mfma_f32_16x16x32_bf16 v[8:11], v[154:157], v[232:235], v[8:11]
	v_mfma_f32_16x16x32_bf16 v[8:11], v[158:161], v[236:239], v[8:11]
	v_mfma_f32_16x16x32_bf16 v[12:15], v[144:147], v[236:239], v[12:15]
	v_mfma_f32_16x16x32_bf16 v[12:15], v[140:143], v[232:235], v[12:15]
	s_setprio 0
	s_setprio 1
	v_mfma_f32_16x16x32_bf16 v[52:55], v[162:165], v[182:185], v[52:55]
	v_mfma_f32_16x16x32_bf16 v[52:55], v[166:169], v[188:191], v[52:55]
	v_mfma_f32_16x16x32_bf16 v[48:51], v[174:177], v[188:191], v[48:51]
	v_mfma_f32_16x16x32_bf16 v[48:51], v[170:173], v[182:185], v[48:51]
	v_mfma_f32_16x16x32_bf16 v[32:35], v[170:173], v[216:219], v[32:35]
	v_mfma_f32_16x16x32_bf16 v[32:35], v[174:177], v[220:223], v[32:35]
	v_mfma_f32_16x16x32_bf16 v[36:39], v[166:169], v[220:223], v[36:39]
	v_mfma_f32_16x16x32_bf16 v[36:39], v[162:165], v[216:219], v[36:39]
	v_mfma_f32_16x16x32_bf16 v[20:23], v[162:165], v[224:227], v[20:23]
	v_mfma_f32_16x16x32_bf16 v[20:23], v[166:169], v[228:231], v[20:23]
	v_mfma_f32_16x16x32_bf16 v[16:19], v[174:177], v[228:231], v[16:19]
	v_mfma_f32_16x16x32_bf16 v[16:19], v[170:173], v[224:227], v[16:19]
	v_mfma_f32_16x16x32_bf16 v[0:3], v[170:173], v[232:235], v[0:3]
	v_mfma_f32_16x16x32_bf16 v[0:3], v[174:177], v[236:239], v[0:3]
	v_mfma_f32_16x16x32_bf16 v[4:7], v[166:169], v[236:239], v[4:7]
	v_mfma_f32_16x16x32_bf16 v[4:7], v[162:165], v[232:235], v[4:7]
	s_setprio 0
	s_barrier
	s_add_i32 s49, s49, 2
	s_add_u32 s0, s0, 0x100
	s_addc_u32 s1, s1, 0
	s_add_u32 s37, s37, 0x100
	s_addc_u32 s47, s47, 0
	s_cmp_gt_u32 s49, 13
	s_cbranch_scc0 .LBB0_952
	s_and_b64 vcc, exec, s[78:79]
	s_cbranch_vccz .LBB0_955
	s_barrier

; #define PG8_STAGE(bufoff, gbase, voff) do { _Pragma("unroll") for (int _i = 0; _i < 2; ++_i) \
;         __builtin_amdgcn_global_load_lds((const unsigned*)((const char*)(gbase) + (voff)[_i]), (PG8_LAS unsigned*)(lds + (bufoff) + ldsw + _i * 8192), 16, 0, 0); } while (0)
; #define PG8_LDA(dst, b, h) do { _Pragma("unroll") for (int m = 0; m < 4; ++m) _Pragma("unroll") for (int k = 0; k < 2; ++k) dst[m][k] = *(const PG8_LAS bf16x8*)(lds + PG8_SA(b, h) + aoff + m * 2048 + k * 1024); } while (0)
; #define PG8_LDB(dst, b, h) do { _Pragma("unroll") for (int n = 0; n < 2; ++n) _Pragma("unroll") for (int k = 0; k < 2; ++k) dst[n][k] = *(const PG8_LAS bf16x8*)(lds + PG8_SB(b, h) + boff + n * 2048 + k * 1024); } while (0)
; #define PG8_MMA(ai, bj, At, Bt) do { __builtin_amdgcn_s_setprio(1); _Pragma("unroll") for (int m = 0; m < 4; ++m) _Pragma("unroll") for (int n = 0; n < 2; ++n) _Pragma("unroll") for (int k = 0; k < 2; ++k) \
;         acc[ai][bj][m][n] = __builtin_amdgcn_mfma_f32_16x16x32_bf16(Bt[n][k], At[m][k], acc[ai][bj][m][n], 0, 0, 0); __builtin_amdgcn_s_setprio(0); } while (0)
; #define PG8_BAR __builtin_amdgcn_s_barrier()
; template <class Epi, class Sched, bool ALIGN_EPI = false, bool SP2 = false>
; __device__ __forceinline__ void gemm_phase(PG8_LAS unsigned char* lds, const Gemm g, const Sched& S, const Epi& E) {
;     ...
;         for (int t = 0; t < nt; t += 2) {
;             if constexpr (Epi::MIDSCALE) { if (t == (nt >> 1)) E.mid(acc, cur, wr, fr); }
;             const bool last = (t == nt - 2);
;             const char* a1 = cA + (size_t)(t + 1) * kstep;
;             const char* a2 = last ? nA : cA + (size_t)(t + 2) * kstep; const char* b2 = last ? nB : cB + (size_t)(t + 2) * kstep;
;             const char* a3 = a2 + kstep; const char* b3 = b2 + kstep;
;             if (last && has_next) S.a_ready(nxt);
;             if constexpr (SP2) {
;             PG8_LDB(B0, 0, 0); PG8_LDB(B1, 0, 1); PG8_SCHED; PG8_LDA(At, 0, 0); PG8_STAGE(PG8_SA(1, 1), a1 + hstepA, voffA);
;             PG8_WAIT_V(8); PG8_WAIT_L(0); PG8_BAR; PG8_MMA(0, 0, At, B0); PG8_MMA(0, 1, At, B1); PG8_BAR; PG8_SCHED;
;             PG8_LDA(At, 0, 1); PG8_STAGE(PG8_SB(0, 0), b2, voffB); PG8_STAGE(PG8_SB(0, 1), b2 + hstepB, voffB); PG8_STAGE(PG8_SA(0, 0), a2, voffA);
;             PG8_WAIT_V(8); PG8_WAIT_L(0); PG8_BAR; PG8_MMA(1, 0, At, B0); PG8_MMA(1, 1, At, B1); PG8_BAR; PG8_SCHED;
.LBB0_1030:
	s_add_u32 s22, s20, s62
	s_addc_u32 s23, s21, s63
	s_add_u32 s22, s22, 0x100
	s_addc_u32 s23, s23, 0
	s_add_u32 s75, s72, s62
	s_addc_u32 s76, s73, s63
	s_add_i32 s77, 0, 0x10000
	s_cmpk_eq_i32 s62, 0xf00
	s_cselect_b32 s57, s47, s23
	s_cselect_b32 s56, s49, s22
	v_add_u32_e32 v80, s77, v150
	s_cselect_b32 s23, s45, s76
	s_cselect_b32 s22, s71, s75
	s_add_i32 s75, 0, 0x14000
	ds_read_b128 v[154:157], v80
	ds_read_b128 v[158:161], v80 offset:1024
	ds_read_b128 v[162:165], v80 offset:2048
	ds_read_b128 v[166:169], v80 offset:3072
	v_add_u32_e32 v80, s75, v150
	ds_read_b128 v[170:173], v80
	ds_read_b128 v[174:177], v80 offset:1024
	ds_read_b128 v[182:185], v80 offset:2048
	ds_read_b128 v[188:191], v80 offset:3072
	v_lshl_add_u64 v[82:83], v[144:145], 0, s[62:63]
	s_add_i32 m0, s33, 0xc000
	ds_read_b128 v[216:219], v152
	ds_read_b128 v[220:223], v152 offset:1024
	ds_read_b128 v[224:227], v152 offset:2048
	ds_read_b128 v[228:231], v152 offset:3072
	ds_read_b128 v[232:235], v152 offset:4096
	ds_read_b128 v[236:239], v152 offset:5120
	ds_read_b128 v[240:243], v152 offset:6144
	ds_read_b128 v[244:247], v152 offset:7168
	global_load_lds_dwordx4 v[82:83], off
	v_lshl_add_u64 v[82:83], v[146:147], 0, s[62:63]
	s_add_i32 m0, s33, 0xe000
	s_nop 0
	global_load_lds_dwordx4 v[82:83], off
	s_waitcnt vmcnt(8)
	s_waitcnt lgkmcnt(0)
	s_barrier
	s_setprio 1
	s_waitcnt lgkmcnt(0)
	v_mfma_f32_16x16x32_bf16 v[128:131], v[154:157], v[216:219], v[128:131]
	v_mfma_f32_16x16x32_bf16 v[128:131], v[158:161], v[220:223], v[128:131]
	v_mfma_f32_16x16x32_bf16 v[124:127], v[162:165], v[216:219], v[124:127]
	v_mfma_f32_16x16x32_bf16 v[124:127], v[166:169], v[220:223], v[124:127]
	v_mfma_f32_16x16x32_bf16 v[112:115], v[154:157], v[224:227], v[112:115]
	v_mfma_f32_16x16x32_bf16 v[112:115], v[158:161], v[228:231], v[112:115]
	v_mfma_f32_16x16x32_bf16 v[108:111], v[162:165], v[224:227], v[108:111]
	v_mfma_f32_16x16x32_bf16 v[108:111], v[166:169], v[228:231], v[108:111]
	v_mfma_f32_16x16x32_bf16 v[96:99], v[154:157], v[232:235], v[96:99]
	v_mfma_f32_16x16x32_bf16 v[96:99], v[158:161], v[236:239], v[96:99]
	v_mfma_f32_16x16x32_bf16 v[92:95], v[162:165], v[232:235], v[92:95]
	v_mfma_f32_16x16x32_bf16 v[92:95], v[166:169], v[236:239], v[92:95]
	v_mfma_f32_16x16x32_bf16 v[76:79], v[154:157], v[240:243], v[76:79]
	v_mfma_f32_16x16x32_bf16 v[76:79], v[158:161], v[244:247], v[76:79]
	v_mfma_f32_16x16x32_bf16 v[72:75], v[162:165], v[240:243], v[72:75]
	v_mfma_f32_16x16x32_bf16 v[72:75], v[166:169], v[244:247], v[72:75]
	s_setprio 0
	s_setprio 1
	v_mfma_f32_16x16x32_bf16 v[120:123], v[170:173], v[216:219], v[120:123]
	v_mfma_f32_16x16x32_bf16 v[120:123], v[174:177], v[220:223], v[120:123]
	v_mfma_f32_16x16x32_bf16 v[116:119], v[182:185], v[216:219], v[116:119]
	v_mfma_f32_16x16x32_bf16 v[116:119], v[188:191], v[220:223], v[116:119]
	v_mfma_f32_16x16x32_bf16 v[104:107], v[170:173], v[224:227], v[104:107]
	v_mfma_f32_16x16x32_bf16 v[104:107], v[174:177], v[228:231], v[104:107]
	v_mfma_f32_16x16x32_bf16 v[100:103], v[182:185], v[224:227], v[100:103]
	v_mfma_f32_16x16x32_bf16 v[100:103], v[188:191], v[228:231], v[100:103]
	v_mfma_f32_16x16x32_bf16 v[88:91], v[170:173], v[232:235], v[88:91]
	v_mfma_f32_16x16x32_bf16 v[88:91], v[174:177], v[236:239], v[88:91]
	v_mfma_f32_16x16x32_bf16 v[82:85], v[182:185], v[232:235], v[84:87]
	v_mfma_f32_16x16x32_bf16 v[82:85], v[188:191], v[236:239], v[82:85]
	v_mfma_f32_16x16x32_bf16 v[68:71], v[170:173], v[240:243], v[68:71]
	v_mfma_f32_16x16x32_bf16 v[68:71], v[174:177], v[244:247], v[68:71]
	v_mfma_f32_16x16x32_bf16 v[64:67], v[182:185], v[240:243], v[64:67]
	v_mfma_f32_16x16x32_bf16 v[64:67], v[188:191], v[244:247], v[64:67]
	s_setprio 0
	s_barrier
	s_add_i32 s76, s77, s31
	v_lshl_add_u64 v[192:193], s[22:23], 0, v[136:137]
	s_mov_b32 m0, s76
	ds_read_b128 v[216:219], v152 offset:16384
	ds_read_b128 v[220:223], v152 offset:17408
	ds_read_b128 v[224:227], v152 offset:18432
	ds_read_b128 v[228:231], v152 offset:19456
	ds_read_b128 v[232:235], v152 offset:20480
	ds_read_b128 v[236:239], v152 offset:21504
	ds_read_b128 v[240:243], v152 offset:22528
	ds_read_b128 v[244:247], v152 offset:23552
	global_load_lds_dwordx4 v[192:193], off
	s_add_i32 m0, s76, 0x2000
	s_add_u32 s76, s22, 0x80000
	v_lshl_add_u64 v[202:203], s[22:23], 0, v[132:133]
	s_addc_u32 s77, s23, 0
	s_add_i32 s75, s75, s31
	global_load_lds_dwordx4 v[202:203], off
	v_lshl_add_u64 v[86:87], s[76:77], 0, v[136:137]
	s_mov_b32 m0, s75
	v_lshl_add_u64 v[204:205], s[56:57], 0, v[138:139]
	global_load_lds_dwordx4 v[86:87], off
	v_lshl_add_u64 v[86:87], s[76:77], 0, v[132:133]
	s_add_i32 m0, s75, 0x2000
	v_lshl_add_u64 v[206:207], s[56:57], 0, v[134:135]
	global_load_lds_dwordx4 v[86:87], off
	s_mov_b32 m0, s33
	s_nop 0
	global_load_lds_dwordx4 v[204:205], off
	s_mov_b32 m0, s35
	s_nop 0
	global_load_lds_dwordx4 v[206:207], off
	s_waitcnt vmcnt(8)
	s_waitcnt lgkmcnt(0)
	s_barrier
; #define PG8_STAGE(bufoff, gbase, voff) do { _Pragma("unroll") for (int _i = 0; _i < 2; ++_i) \
;         __builtin_amdgcn_global_load_lds((const unsigned*)((const char*)(gbase) + (voff)[_i]), (PG8_LAS unsigned*)(lds + (bufoff) + ldsw + _i * 8192), 16, 0, 0); } while (0)
; #define PG8_LDA(dst, b, h) do { _Pragma("unroll") for (int m = 0; m < 4; ++m) _Pragma("unroll") for (int k = 0; k < 2; ++k) dst[m][k] = *(const PG8_LAS bf16x8*)(lds + PG8_SA(b, h) + aoff + m * 2048 + k * 1024); } while (0)
; #define PG8_LDB(dst, b, h) do { _Pragma("unroll") for (int n = 0; n < 2; ++n) _Pragma("unroll") for (int k = 0; k < 2; ++k) dst[n][k] = *(const PG8_LAS bf16x8*)(lds + PG8_SB(b, h) + boff + n * 2048 + k * 1024); } while (0)
; #define PG8_MMA(ai, bj, At, Bt) do { __builtin_amdgcn_s_setprio(1); _Pragma("unroll") for (int m = 0; m < 4; ++m) _Pragma("unroll") for (int n = 0; n < 2; ++n) _Pragma("unroll") for (int k = 0; k < 2; ++k) \
;         acc[ai][bj][m][n] = __builtin_amdgcn_mfma_f32_16x16x32_bf16(Bt[n][k], At[m][k], acc[ai][bj][m][n], 0, 0, 0); __builtin_amdgcn_s_setprio(0); } while (0)
; #define PG8_WAIT_V(n) asm volatile("s_waitcnt vmcnt(" #n ")" ::: "memory")
; #define PG8_WAIT_L(n) asm volatile("s_waitcnt lgkmcnt(" #n ")" ::: "memory")
; #define PG8_BAR __builtin_amdgcn_s_barrier()
; #define PG8_SCHED __builtin_amdgcn_sched_barrier(0)
; template <class Epi, class Sched, bool ALIGN_EPI = false, bool SP2 = false>
; __device__ __forceinline__ void gemm_phase(PG8_LAS unsigned char* lds, const Gemm g, const Sched& S, const Epi& E) {
;     ...
;             PG8_WAIT_V(8); PG8_WAIT_L(0); PG8_BAR; PG8_MMA(1, 0, At, B0); PG8_MMA(1, 1, At, B1); PG8_BAR; PG8_SCHED;
;             PG8_LDB(B0, 1, 0); PG8_LDB(B1, 1, 1); PG8_SCHED; PG8_LDA(At, 1, 0); PG8_STAGE(PG8_SA(0, 1), a2 + hstepA, voffA);
;             PG8_WAIT_V(8); PG8_WAIT_L(0); PG8_BAR; PG8_MMA(0, 0, At, B0); PG8_MMA(0, 1, At, B1); PG8_BAR; PG8_SCHED;
	s_setprio 1
	s_waitcnt lgkmcnt(0)
	v_mfma_f32_16x16x32_bf16 v[60:63], v[154:157], v[216:219], v[60:63]
	v_mfma_f32_16x16x32_bf16 v[60:63], v[158:161], v[220:223], v[60:63]
	v_mfma_f32_16x16x32_bf16 v[56:59], v[162:165], v[216:219], v[56:59]
	v_mfma_f32_16x16x32_bf16 v[56:59], v[166:169], v[220:223], v[56:59]
	v_mfma_f32_16x16x32_bf16 v[44:47], v[154:157], v[224:227], v[44:47]
	v_mfma_f32_16x16x32_bf16 v[44:47], v[158:161], v[228:231], v[44:47]
	v_mfma_f32_16x16x32_bf16 v[40:43], v[162:165], v[224:227], v[40:43]
	v_mfma_f32_16x16x32_bf16 v[40:43], v[166:169], v[228:231], v[40:43]
	v_mfma_f32_16x16x32_bf16 v[28:31], v[154:157], v[232:235], v[28:31]
	v_mfma_f32_16x16x32_bf16 v[28:31], v[158:161], v[236:239], v[28:31]
	v_mfma_f32_16x16x32_bf16 v[24:27], v[162:165], v[232:235], v[24:27]
	v_mfma_f32_16x16x32_bf16 v[24:27], v[166:169], v[236:239], v[24:27]
	v_mfma_f32_16x16x32_bf16 v[12:15], v[154:157], v[240:243], v[12:15]
	v_mfma_f32_16x16x32_bf16 v[12:15], v[158:161], v[244:247], v[12:15]
	v_mfma_f32_16x16x32_bf16 v[8:11], v[162:165], v[240:243], v[8:11]
	v_mfma_f32_16x16x32_bf16 v[8:11], v[166:169], v[244:247], v[8:11]
	s_setprio 0
	s_setprio 1
	v_mfma_f32_16x16x32_bf16 v[52:55], v[170:173], v[216:219], v[52:55]
	v_mfma_f32_16x16x32_bf16 v[52:55], v[174:177], v[220:223], v[52:55]
	v_mfma_f32_16x16x32_bf16 v[48:51], v[182:185], v[216:219], v[48:51]
	v_mfma_f32_16x16x32_bf16 v[48:51], v[188:191], v[220:223], v[48:51]
	v_mfma_f32_16x16x32_bf16 v[36:39], v[170:173], v[224:227], v[36:39]
	v_mfma_f32_16x16x32_bf16 v[36:39], v[174:177], v[228:231], v[36:39]
	v_mfma_f32_16x16x32_bf16 v[32:35], v[182:185], v[224:227], v[32:35]
	v_mfma_f32_16x16x32_bf16 v[32:35], v[188:191], v[228:231], v[32:35]
	v_mfma_f32_16x16x32_bf16 v[20:23], v[170:173], v[232:235], v[20:23]
	v_mfma_f32_16x16x32_bf16 v[20:23], v[174:177], v[236:239], v[20:23]
	v_mfma_f32_16x16x32_bf16 v[16:19], v[182:185], v[232:235], v[16:19]
	v_mfma_f32_16x16x32_bf16 v[16:19], v[188:191], v[236:239], v[16:19]
	v_mfma_f32_16x16x32_bf16 v[4:7], v[170:173], v[240:243], v[4:7]
	v_mfma_f32_16x16x32_bf16 v[4:7], v[174:177], v[244:247], v[4:7]
	v_mfma_f32_16x16x32_bf16 v[0:3], v[182:185], v[240:243], v[0:3]
	v_mfma_f32_16x16x32_bf16 v[0:3], v[188:191], v[244:247], v[0:3]
	s_setprio 0
	s_barrier
	s_add_i32 s75, 0, 0x18000
	v_add_u32_e32 v80, s75, v150
	s_add_i32 s76, 0, 0x1c000
	ds_read_b128 v[154:157], v80
	ds_read_b128 v[158:161], v80 offset:1024
	ds_read_b128 v[162:165], v80 offset:2048
	ds_read_b128 v[166:169], v80 offset:3072
	v_add_u32_e32 v80, s76, v150
	ds_read_b128 v[170:173], v80
	ds_read_b128 v[174:177], v80 offset:1024
	ds_read_b128 v[182:185], v80 offset:2048
	ds_read_b128 v[188:191], v80 offset:3072
	s_add_u32 s56, s56, 0x80000
	s_addc_u32 s57, s57, 0
	s_mov_b32 m0, s36
	v_lshl_add_u64 v[86:87], s[56:57], 0, v[138:139]
	ds_read_b128 v[216:219], v152 offset:32768
	ds_read_b128 v[220:223], v152 offset:33792
	ds_read_b128 v[224:227], v152 offset:34816
	ds_read_b128 v[228:231], v152 offset:35840
	ds_read_b128 v[232:235], v152 offset:36864
	ds_read_b128 v[236:239], v152 offset:37888
	ds_read_b128 v[240:243], v152 offset:38912
	ds_read_b128 v[244:247], v152 offset:39936
	global_load_lds_dwordx4 v[86:87], off
	v_lshl_add_u64 v[86:87], s[56:57], 0, v[134:135]
	s_mov_b32 m0, s37
	s_nop 0
	global_load_lds_dwordx4 v[86:87], off
	s_waitcnt vmcnt(8)
	s_waitcnt lgkmcnt(0)
	s_barrier
	s_setprio 1
	s_waitcnt lgkmcnt(0)
	v_mfma_f32_16x16x32_bf16 v[128:131], v[154:157], v[216:219], v[128:131]
	v_mfma_f32_16x16x32_bf16 v[128:131], v[158:161], v[220:223], v[128:131]
	v_mfma_f32_16x16x32_bf16 v[124:127], v[162:165], v[216:219], v[124:127]
	v_mfma_f32_16x16x32_bf16 v[124:127], v[166:169], v[220:223], v[124:127]
	v_mfma_f32_16x16x32_bf16 v[112:115], v[154:157], v[224:227], v[112:115]
	v_mfma_f32_16x16x32_bf16 v[112:115], v[158:161], v[228:231], v[112:115]
	v_mfma_f32_16x16x32_bf16 v[108:111], v[162:165], v[224:227], v[108:111]
	v_mfma_f32_16x16x32_bf16 v[108:111], v[166:169], v[228:231], v[108:111]
	v_mfma_f32_16x16x32_bf16 v[96:99], v[154:157], v[232:235], v[96:99]
	v_mfma_f32_16x16x32_bf16 v[96:99], v[158:161], v[236:239], v[96:99]
	v_mfma_f32_16x16x32_bf16 v[92:95], v[162:165], v[232:235], v[92:95]
	v_mfma_f32_16x16x32_bf16 v[92:95], v[166:169], v[236:239], v[92:95]
	v_mfma_f32_16x16x32_bf16 v[76:79], v[154:157], v[240:243], v[76:79]
	v_mfma_f32_16x16x32_bf16 v[76:79], v[158:161], v[244:247], v[76:79]
	v_mfma_f32_16x16x32_bf16 v[72:75], v[162:165], v[240:243], v[72:75]
	v_mfma_f32_16x16x32_bf16 v[72:75], v[166:169], v[244:247], v[72:75]
	s_setprio 0
	s_setprio 1
	v_mfma_f32_16x16x32_bf16 v[120:123], v[170:173], v[216:219], v[120:123]
	v_mfma_f32_16x16x32_bf16 v[120:123], v[174:177], v[220:223], v[120:123]
	v_mfma_f32_16x16x32_bf16 v[116:119], v[182:185], v[216:219], v[116:119]
	v_mfma_f32_16x16x32_bf16 v[116:119], v[188:191], v[220:223], v[116:119]
	v_mfma_f32_16x16x32_bf16 v[104:107], v[170:173], v[224:227], v[104:107]
	v_mfma_f32_16x16x32_bf16 v[104:107], v[174:177], v[228:231], v[104:107]
	v_mfma_f32_16x16x32_bf16 v[100:103], v[182:185], v[224:227], v[100:103]
	v_mfma_f32_16x16x32_bf16 v[100:103], v[188:191], v[228:231], v[100:103]
	v_mfma_f32_16x16x32_bf16 v[86:89], v[170:173], v[232:235], v[88:91]
	v_mfma_f32_16x16x32_bf16 v[88:91], v[174:177], v[236:239], v[86:89]
	v_mfma_f32_16x16x32_bf16 v[82:85], v[182:185], v[232:235], v[82:85]
	v_mfma_f32_16x16x32_bf16 v[84:87], v[188:191], v[236:239], v[82:85]
	v_mfma_f32_16x16x32_bf16 v[68:71], v[170:173], v[240:243], v[68:71]
	v_mfma_f32_16x16x32_bf16 v[68:71], v[174:177], v[244:247], v[68:71]
	v_mfma_f32_16x16x32_bf16 v[64:67], v[182:185], v[240:243], v[64:67]
	v_mfma_f32_16x16x32_bf16 v[64:67], v[188:191], v[244:247], v[64:67]
	s_setprio 0
	s_barrier
; #define PG8_STAGE(bufoff, gbase, voff) do { _Pragma("unroll") for (int _i = 0; _i < 2; ++_i) \
;         __builtin_amdgcn_global_load_lds((const unsigned*)((const char*)(gbase) + (voff)[_i]), (PG8_LAS unsigned*)(lds + (bufoff) + ldsw + _i * 8192), 16, 0, 0); } while (0)
; #define PG8_LDA(dst, b, h) do { _Pragma("unroll") for (int m = 0; m < 4; ++m) _Pragma("unroll") for (int k = 0; k < 2; ++k) dst[m][k] = *(const PG8_LAS bf16x8*)(lds + PG8_SA(b, h) + aoff + m * 2048 + k * 1024); } while (0)
; #define PG8_MMA(ai, bj, At, Bt) do { __builtin_amdgcn_s_setprio(1); _Pragma("unroll") for (int m = 0; m < 4; ++m) _Pragma("unroll") for (int n = 0; n < 2; ++n) _Pragma("unroll") for (int k = 0; k < 2; ++k) \
;         acc[ai][bj][m][n] = __builtin_amdgcn_mfma_f32_16x16x32_bf16(Bt[n][k], At[m][k], acc[ai][bj][m][n], 0, 0, 0); __builtin_amdgcn_s_setprio(0); } while (0)
; #define PG8_WAIT_V(n) asm volatile("s_waitcnt vmcnt(" #n ")" ::: "memory")
; #define PG8_WAIT_L(n) asm volatile("s_waitcnt lgkmcnt(" #n ")" ::: "memory")
; #define PG8_BAR __builtin_amdgcn_s_barrier()
; #define PG8_SCHED __builtin_amdgcn_sched_barrier(0)
; template <class Epi, class Sched, bool ALIGN_EPI = false, bool SP2 = false>
; __device__ __forceinline__ void gemm_phase(PG8_LAS unsigned char* lds, const Gemm g, const Sched& S, const Epi& E) {
;     ...
;             PG8_LDA(At, 1, 1); PG8_STAGE(PG8_SB(1, 0), b3, voffB); PG8_STAGE(PG8_SB(1, 1), b3 + hstepB, voffB); PG8_STAGE(PG8_SA(1, 0), a3, voffA);
;             PG8_WAIT_V(8); PG8_WAIT_L(0); PG8_BAR; PG8_MMA(1, 0, At, B0); PG8_MMA(1, 1, At, B1); PG8_BAR; PG8_SCHED;
	s_add_i32 s56, s75, s31
	v_lshl_add_u64 v[82:83], v[192:193], 0, s[60:61]
	s_mov_b32 m0, s56
	ds_read_b128 v[216:219], v152 offset:49152
	ds_read_b128 v[220:223], v152 offset:50176
	ds_read_b128 v[224:227], v152 offset:51200
	ds_read_b128 v[228:231], v152 offset:52224
	ds_read_b128 v[232:235], v152 offset:53248
	ds_read_b128 v[236:239], v152 offset:54272
	ds_read_b128 v[240:243], v152 offset:55296
	ds_read_b128 v[244:247], v152 offset:56320
	global_load_lds_dwordx4 v[82:83], off
	s_add_i32 m0, s56, 0x2000
	s_add_u32 s22, s22, 0x80080
	v_lshl_add_u64 v[82:83], v[202:203], 0, s[60:61]
	s_addc_u32 s23, s23, 0
	s_add_i32 s56, s76, s31
	global_load_lds_dwordx4 v[82:83], off
	v_lshl_add_u64 v[82:83], s[22:23], 0, v[136:137]
	s_mov_b32 m0, s56
	s_nop 0
	global_load_lds_dwordx4 v[82:83], off
	v_lshl_add_u64 v[82:83], s[22:23], 0, v[132:133]
	s_add_i32 m0, s56, 0x2000
	s_nop 0
	global_load_lds_dwordx4 v[82:83], off
	v_lshl_add_u64 v[82:83], v[204:205], 0, s[60:61]
	s_mov_b32 m0, s64
	s_nop 0
	global_load_lds_dwordx4 v[82:83], off
	v_lshl_add_u64 v[82:83], v[206:207], 0, s[60:61]
	s_mov_b32 m0, s65
	s_nop 0
	global_load_lds_dwordx4 v[82:83], off
	s_waitcnt vmcnt(8)
	s_waitcnt lgkmcnt(0)
	s_barrier
	s_setprio 1
	s_waitcnt lgkmcnt(0)
	v_mfma_f32_16x16x32_bf16 v[60:63], v[154:157], v[216:219], v[60:63]
	v_mfma_f32_16x16x32_bf16 v[60:63], v[158:161], v[220:223], v[60:63]
	v_mfma_f32_16x16x32_bf16 v[56:59], v[162:165], v[216:219], v[56:59]
	v_mfma_f32_16x16x32_bf16 v[56:59], v[166:169], v[220:223], v[56:59]
	v_mfma_f32_16x16x32_bf16 v[44:47], v[154:157], v[224:227], v[44:47]
	v_mfma_f32_16x16x32_bf16 v[44:47], v[158:161], v[228:231], v[44:47]
	v_mfma_f32_16x16x32_bf16 v[40:43], v[162:165], v[224:227], v[40:43]
	v_mfma_f32_16x16x32_bf16 v[40:43], v[166:169], v[228:231], v[40:43]
	v_mfma_f32_16x16x32_bf16 v[28:31], v[154:157], v[232:235], v[28:31]
	v_mfma_f32_16x16x32_bf16 v[28:31], v[158:161], v[236:239], v[28:31]
	v_mfma_f32_16x16x32_bf16 v[24:27], v[162:165], v[232:235], v[24:27]
	v_mfma_f32_16x16x32_bf16 v[24:27], v[166:169], v[236:239], v[24:27]
	v_mfma_f32_16x16x32_bf16 v[12:15], v[154:157], v[240:243], v[12:15]
	v_mfma_f32_16x16x32_bf16 v[12:15], v[158:161], v[244:247], v[12:15]
	v_mfma_f32_16x16x32_bf16 v[8:11], v[162:165], v[240:243], v[8:11]
	v_mfma_f32_16x16x32_bf16 v[8:11], v[166:169], v[244:247], v[8:11]
	s_setprio 0
	s_setprio 1
	v_mfma_f32_16x16x32_bf16 v[52:55], v[170:173], v[216:219], v[52:55]
	v_mfma_f32_16x16x32_bf16 v[52:55], v[174:177], v[220:223], v[52:55]
	v_mfma_f32_16x16x32_bf16 v[48:51], v[182:185], v[216:219], v[48:51]
	v_mfma_f32_16x16x32_bf16 v[48:51], v[188:191], v[220:223], v[48:51]
	v_mfma_f32_16x16x32_bf16 v[36:39], v[170:173], v[224:227], v[36:39]
	v_mfma_f32_16x16x32_bf16 v[36:39], v[174:177], v[228:231], v[36:39]
	v_mfma_f32_16x16x32_bf16 v[32:35], v[182:185], v[224:227], v[32:35]
	v_mfma_f32_16x16x32_bf16 v[32:35], v[188:191], v[228:231], v[32:35]
	v_mfma_f32_16x16x32_bf16 v[20:23], v[170:173], v[232:235], v[20:23]
	v_mfma_f32_16x16x32_bf16 v[20:23], v[174:177], v[236:239], v[20:23]
	v_mfma_f32_16x16x32_bf16 v[16:19], v[182:185], v[232:235], v[16:19]
	v_mfma_f32_16x16x32_bf16 v[16:19], v[188:191], v[236:239], v[16:19]
	v_mfma_f32_16x16x32_bf16 v[4:7], v[170:173], v[240:243], v[4:7]
	v_mfma_f32_16x16x32_bf16 v[4:7], v[174:177], v[244:247], v[4:7]
	v_mfma_f32_16x16x32_bf16 v[0:3], v[182:185], v[240:243], v[0:3]
	v_mfma_f32_16x16x32_bf16 v[0:3], v[188:191], v[244:247], v[0:3]
	s_setprio 0
	s_barrier
	s_add_i32 s74, s74, 2
	s_add_u32 s62, s62, 0x100
	s_addc_u32 s63, s63, 0
	s_cmp_gt_u32 s74, 29
	s_cbranch_scc1 .LBB0_1033

; #define PG8_STAGE(bufoff, gbase, voff) do { _Pragma("unroll") for (int _i = 0; _i < 2; ++_i) \
;         __builtin_amdgcn_global_load_lds((const unsigned*)((const char*)(gbase) + (voff)[_i]), (PG8_LAS unsigned*)(lds + (bufoff) + ldsw + _i * 8192), 16, 0, 0); } while (0)
; #define PG8_LDA(dst, b, h) do { _Pragma("unroll") for (int m = 0; m < 4; ++m) _Pragma("unroll") for (int k = 0; k < 2; ++k) dst[m][k] = *(const PG8_LAS bf16x8*)(lds + PG8_SA(b, h) + aoff + m * 2048 + k * 1024); } while (0)
; #define PG8_LDB(dst, b, h) do { _Pragma("unroll") for (int n = 0; n < 2; ++n) _Pragma("unroll") for (int k = 0; k < 2; ++k) dst[n][k] = *(const PG8_LAS bf16x8*)(lds + PG8_SB(b, h) + boff + n * 2048 + k * 1024); } while (0)
; #define PG8_MMA(ai, bj, At, Bt) do { __builtin_amdgcn_s_setprio(1); _Pragma("unroll") for (int m = 0; m < 4; ++m) _Pragma("unroll") for (int n = 0; n < 2; ++n) _Pragma("unroll") for (int k = 0; k < 2; ++k) \
;         acc[ai][bj][m][n] = __builtin_amdgcn_mfma_f32_16x16x32_bf16(Bt[n][k], At[m][k], acc[ai][bj][m][n], 0, 0, 0); __builtin_amdgcn_s_setprio(0); } while (0)
; #define PG8_BAR __builtin_amdgcn_s_barrier()
; template <class Epi, class Sched, bool ALIGN_EPI = false, bool SP2 = false>
; __device__ __forceinline__ void gemm_phase(PG8_LAS unsigned char* lds, const Gemm g, const Sched& S, const Epi& E) {
;     ...
;         for (int t = 0; t < nt; t += 2) {
;             if constexpr (Epi::MIDSCALE) { if (t == (nt >> 1)) E.mid(acc, cur, wr, fr); }
;             const bool last = (t == nt - 2);
;             const char* a1 = cA + (size_t)(t + 1) * kstep;
;             const char* a2 = last ? nA : cA + (size_t)(t + 2) * kstep; const char* b2 = last ? nB : cB + (size_t)(t + 2) * kstep;
;             const char* a3 = a2 + kstep; const char* b3 = b2 + kstep;
;             if (last && has_next) S.a_ready(nxt);
;             if constexpr (SP2) {
;             PG8_LDB(B0, 0, 0); PG8_LDB(B1, 0, 1); PG8_SCHED; PG8_LDA(At, 0, 0); PG8_STAGE(PG8_SA(1, 1), a1 + hstepA, voffA);
;             PG8_WAIT_V(8); PG8_WAIT_L(0); PG8_BAR; PG8_MMA(0, 0, At, B0); PG8_MMA(0, 1, At, B1); PG8_BAR; PG8_SCHED;
;             PG8_LDA(At, 0, 1); PG8_STAGE(PG8_SB(0, 0), b2, voffB); PG8_STAGE(PG8_SB(0, 1), b2 + hstepB, voffB); PG8_STAGE(PG8_SA(0, 0), a2, voffA);
;             PG8_WAIT_V(8); PG8_WAIT_L(0); PG8_BAR; PG8_MMA(1, 0, At, B0); PG8_MMA(1, 1, At, B1); PG8_BAR; PG8_SCHED;
.LBB0_1088:
	s_add_u32 s43, s52, s22
	s_addc_u32 s45, s53, 0
	s_add_u32 s23, s43, 0x100
	s_addc_u32 s66, s45, 0
	s_and_b64 s[56:57], s[64:65], exec
	s_cselect_b32 s57, s47, s66
	s_cselect_b32 s56, s46, s23
	s_add_u32 s22, s20, s22
	s_addc_u32 s23, s21, 0
	s_add_u32 s66, s22, 0x100
	s_addc_u32 s67, s23, 0
	s_add_i32 s84, 0, 0x10000
	s_and_b64 s[22:23], s[64:65], exec
	s_cselect_b32 s67, s49, s67
	s_cselect_b32 s66, s48, s66
	s_add_i32 s65, 0, 0x14000
	s_add_u32 s70, s43, 0x80080
	s_addc_u32 s71, s45, 0
	s_add_i32 s83, s84, s31
	s_add_i32 m0, s33, 0xc000
	s_add_i32 s86, s33, 0xe000
	s_add_i32 s80, s83, 0x2000
	s_add_u32 s68, s66, 0x80000
	v_add_u32_e32 v152, s84, v138
	v_add_u32_e32 v168, s65, v138
	s_addc_u32 s69, s67, 0
	s_add_i32 s82, s65, s31
	ds_read_b128 v[140:143], v152
	ds_read_b128 v[144:147], v152 offset:1024
	ds_read_b128 v[148:151], v152 offset:2048
	ds_read_b128 v[152:155], v152 offset:3072
	ds_read_b128 v[156:159], v168
	ds_read_b128 v[160:163], v168 offset:1024
	ds_read_b128 v[164:167], v168 offset:2048
	ds_read_b128 v[168:171], v168 offset:3072
	s_add_i32 s81, s82, 0x2000
	s_add_i32 s79, 0, 0x18000
	s_add_i32 s78, 0, 0x1c000
	s_add_u32 s22, s56, 0x80000
	s_addc_u32 s23, s57, 0
	s_add_i32 s45, s79, s31
	s_add_i32 s43, s45, 0x2000
	s_add_u32 s64, s66, 0x80080
	s_addc_u32 s65, s67, 0
	s_add_i32 s85, s78, s31
	s_add_i32 s84, s85, 0x2000
	v_lshl_add_u64 v[176:177], s[70:71], 0, v[134:135]
	ds_read_b128 v[172:175], v139
	ds_read_b128 v[182:185], v139 offset:1024
	ds_read_b128 v[188:191], v139 offset:2048
	ds_read_b128 v[216:219], v139 offset:3072
	ds_read_b128 v[220:223], v139 offset:4096
	ds_read_b128 v[224:227], v139 offset:5120
	ds_read_b128 v[228:231], v139 offset:6144
	ds_read_b128 v[232:235], v139 offset:7168
	global_load_lds_dwordx4 v[176:177], off
	v_lshl_add_u64 v[176:177], s[70:71], 0, v[132:133]
	s_mov_b32 m0, s86
	s_nop 0
	global_load_lds_dwordx4 v[176:177], off
	s_waitcnt vmcnt(8)
	s_waitcnt lgkmcnt(0)
	s_barrier
	s_setprio 1
	s_waitcnt lgkmcnt(0)
	v_mfma_f32_16x16x32_bf16 v[126:129], v[140:143], v[172:175], v[126:129]
	v_mfma_f32_16x16x32_bf16 v[126:129], v[144:147], v[182:185], v[126:129]
	v_mfma_f32_16x16x32_bf16 v[122:125], v[152:155], v[182:185], v[122:125]
	v_mfma_f32_16x16x32_bf16 v[122:125], v[148:151], v[172:175], v[122:125]
	v_mfma_f32_16x16x32_bf16 v[114:117], v[148:151], v[188:191], v[114:117]
	v_mfma_f32_16x16x32_bf16 v[114:117], v[152:155], v[216:219], v[114:117]
	v_mfma_f32_16x16x32_bf16 v[118:121], v[144:147], v[216:219], v[118:121]
	v_mfma_f32_16x16x32_bf16 v[118:121], v[140:143], v[188:191], v[118:121]
	v_mfma_f32_16x16x32_bf16 v[106:109], v[140:143], v[220:223], v[106:109]
	v_mfma_f32_16x16x32_bf16 v[106:109], v[144:147], v[224:227], v[106:109]
	v_mfma_f32_16x16x32_bf16 v[98:101], v[152:155], v[224:227], v[98:101]
	v_mfma_f32_16x16x32_bf16 v[98:101], v[148:151], v[220:223], v[98:101]
	v_mfma_f32_16x16x32_bf16 v[82:85], v[148:151], v[228:231], v[82:85]
	v_mfma_f32_16x16x32_bf16 v[82:85], v[152:155], v[232:235], v[82:85]
	v_mfma_f32_16x16x32_bf16 v[90:93], v[144:147], v[232:235], v[90:93]
	v_mfma_f32_16x16x32_bf16 v[90:93], v[140:143], v[228:231], v[90:93]
	s_setprio 0
	s_setprio 1
	v_mfma_f32_16x16x32_bf16 v[110:113], v[156:159], v[172:175], v[110:113]
	v_mfma_f32_16x16x32_bf16 v[110:113], v[160:163], v[182:185], v[110:113]
	v_mfma_f32_16x16x32_bf16 v[102:105], v[168:171], v[182:185], v[102:105]
	v_mfma_f32_16x16x32_bf16 v[102:105], v[164:167], v[172:175], v[102:105]
	v_mfma_f32_16x16x32_bf16 v[86:89], v[164:167], v[188:191], v[86:89]
	v_mfma_f32_16x16x32_bf16 v[86:89], v[168:171], v[216:219], v[86:89]
	v_mfma_f32_16x16x32_bf16 v[94:97], v[160:163], v[216:219], v[94:97]
	v_mfma_f32_16x16x32_bf16 v[94:97], v[156:159], v[188:191], v[94:97]
	v_mfma_f32_16x16x32_bf16 v[76:79], v[156:159], v[220:223], v[76:79]
	v_mfma_f32_16x16x32_bf16 v[76:79], v[160:163], v[224:227], v[76:79]
	v_mfma_f32_16x16x32_bf16 v[72:75], v[168:171], v[224:227], v[72:75]
	v_mfma_f32_16x16x32_bf16 v[72:75], v[164:167], v[220:223], v[72:75]
	v_mfma_f32_16x16x32_bf16 v[64:67], v[164:167], v[228:231], v[64:67]
	v_mfma_f32_16x16x32_bf16 v[64:67], v[168:171], v[232:235], v[64:67]
	v_mfma_f32_16x16x32_bf16 v[68:71], v[160:163], v[232:235], v[68:71]
	v_mfma_f32_16x16x32_bf16 v[68:71], v[156:159], v[228:231], v[68:71]
	s_setprio 0
	s_barrier
	s_mov_b32 m0, s83
	v_lshl_add_u64 v[176:177], s[66:67], 0, v[80:81]
	ds_read_b128 v[172:175], v139 offset:16384
	ds_read_b128 v[182:185], v139 offset:17408
	ds_read_b128 v[188:191], v139 offset:18432
	ds_read_b128 v[216:219], v139 offset:19456
	ds_read_b128 v[220:223], v139 offset:20480
	ds_read_b128 v[224:227], v139 offset:21504
	ds_read_b128 v[228:231], v139 offset:22528
	ds_read_b128 v[232:235], v139 offset:23552
	global_load_lds_dwordx4 v[176:177], off
	v_lshl_add_u64 v[192:193], s[66:67], 0, v[130:131]
	s_mov_b32 m0, s80
	v_lshl_add_u64 v[202:203], s[68:69], 0, v[80:81]
	global_load_lds_dwordx4 v[192:193], off
	s_mov_b32 m0, s82
	v_lshl_add_u64 v[204:205], s[56:57], 0, v[132:133]
	global_load_lds_dwordx4 v[202:203], off
	v_lshl_add_u64 v[202:203], s[68:69], 0, v[130:131]
	s_mov_b32 m0, s81
	s_nop 0
	global_load_lds_dwordx4 v[202:203], off
	v_lshl_add_u64 v[202:203], s[56:57], 0, v[134:135]
	s_mov_b32 m0, s33
	s_nop 0
	global_load_lds_dwordx4 v[202:203], off
	s_mov_b32 m0, s35
	s_nop 0
	global_load_lds_dwordx4 v[204:205], off
	s_waitcnt vmcnt(8)
	s_waitcnt lgkmcnt(0)
	s_barrier
; #define PG8_STAGE(bufoff, gbase, voff) do { _Pragma("unroll") for (int _i = 0; _i < 2; ++_i) \
;         __builtin_amdgcn_global_load_lds((const unsigned*)((const char*)(gbase) + (voff)[_i]), (PG8_LAS unsigned*)(lds + (bufoff) + ldsw + _i * 8192), 16, 0, 0); } while (0)
; #define PG8_LDA(dst, b, h) do { _Pragma("unroll") for (int m = 0; m < 4; ++m) _Pragma("unroll") for (int k = 0; k < 2; ++k) dst[m][k] = *(const PG8_LAS bf16x8*)(lds + PG8_SA(b, h) + aoff + m * 2048 + k * 1024); } while (0)
; #define PG8_LDB(dst, b, h) do { _Pragma("unroll") for (int n = 0; n < 2; ++n) _Pragma("unroll") for (int k = 0; k < 2; ++k) dst[n][k] = *(const PG8_LAS bf16x8*)(lds + PG8_SB(b, h) + boff + n * 2048 + k * 1024); } while (0)
; #define PG8_MMA(ai, bj, At, Bt) do { __builtin_amdgcn_s_setprio(1); _Pragma("unroll") for (int m = 0; m < 4; ++m) _Pragma("unroll") for (int n = 0; n < 2; ++n) _Pragma("unroll") for (int k = 0; k < 2; ++k) \
;         acc[ai][bj][m][n] = __builtin_amdgcn_mfma_f32_16x16x32_bf16(Bt[n][k], At[m][k], acc[ai][bj][m][n], 0, 0, 0); __builtin_amdgcn_s_setprio(0); } while (0)
; #define PG8_WAIT_V(n) asm volatile("s_waitcnt vmcnt(" #n ")" ::: "memory")
; #define PG8_WAIT_L(n) asm volatile("s_waitcnt lgkmcnt(" #n ")" ::: "memory")
; #define PG8_BAR __builtin_amdgcn_s_barrier()
; #define PG8_SCHED __builtin_amdgcn_sched_barrier(0)
; template <class Epi, class Sched, bool ALIGN_EPI = false, bool SP2 = false>
; __device__ __forceinline__ void gemm_phase(PG8_LAS unsigned char* lds, const Gemm g, const Sched& S, const Epi& E) {
;     ...
;             PG8_WAIT_V(8); PG8_WAIT_L(0); PG8_BAR; PG8_MMA(1, 0, At, B0); PG8_MMA(1, 1, At, B1); PG8_BAR; PG8_SCHED;
;             PG8_LDB(B0, 1, 0); PG8_LDB(B1, 1, 1); PG8_SCHED; PG8_LDA(At, 1, 0); PG8_STAGE(PG8_SA(0, 1), a2 + hstepA, voffA);
;             PG8_WAIT_V(8); PG8_WAIT_L(0); PG8_BAR; PG8_MMA(0, 0, At, B0); PG8_MMA(0, 1, At, B1); PG8_BAR; PG8_SCHED;
	s_setprio 1
	s_waitcnt lgkmcnt(0)
	v_mfma_f32_16x16x32_bf16 v[60:63], v[140:143], v[172:175], v[60:63]
	v_mfma_f32_16x16x32_bf16 v[60:63], v[144:147], v[182:185], v[60:63]
	v_mfma_f32_16x16x32_bf16 v[56:59], v[152:155], v[182:185], v[56:59]
	v_mfma_f32_16x16x32_bf16 v[56:59], v[148:151], v[172:175], v[56:59]
	v_mfma_f32_16x16x32_bf16 v[48:51], v[148:151], v[188:191], v[48:51]
	v_mfma_f32_16x16x32_bf16 v[48:51], v[152:155], v[216:219], v[48:51]
	v_mfma_f32_16x16x32_bf16 v[52:55], v[144:147], v[216:219], v[52:55]
	v_mfma_f32_16x16x32_bf16 v[52:55], v[140:143], v[188:191], v[52:55]
	v_mfma_f32_16x16x32_bf16 v[36:39], v[140:143], v[220:223], v[36:39]
	v_mfma_f32_16x16x32_bf16 v[36:39], v[144:147], v[224:227], v[36:39]
	v_mfma_f32_16x16x32_bf16 v[32:35], v[152:155], v[224:227], v[32:35]
	v_mfma_f32_16x16x32_bf16 v[32:35], v[148:151], v[220:223], v[32:35]
	v_mfma_f32_16x16x32_bf16 v[16:19], v[148:151], v[228:231], v[16:19]
	v_mfma_f32_16x16x32_bf16 v[16:19], v[152:155], v[232:235], v[16:19]
	v_mfma_f32_16x16x32_bf16 v[20:23], v[144:147], v[232:235], v[20:23]
	v_mfma_f32_16x16x32_bf16 v[20:23], v[140:143], v[228:231], v[20:23]
	s_setprio 0
	s_setprio 1
	v_mfma_f32_16x16x32_bf16 v[44:47], v[156:159], v[172:175], v[44:47]
	v_mfma_f32_16x16x32_bf16 v[44:47], v[160:163], v[182:185], v[44:47]
	v_mfma_f32_16x16x32_bf16 v[40:43], v[168:171], v[182:185], v[40:43]
	v_mfma_f32_16x16x32_bf16 v[40:43], v[164:167], v[172:175], v[40:43]
	v_mfma_f32_16x16x32_bf16 v[24:27], v[164:167], v[188:191], v[24:27]
	v_mfma_f32_16x16x32_bf16 v[24:27], v[168:171], v[216:219], v[24:27]
	v_mfma_f32_16x16x32_bf16 v[28:31], v[160:163], v[216:219], v[28:31]
	v_mfma_f32_16x16x32_bf16 v[28:31], v[156:159], v[188:191], v[28:31]
	v_mfma_f32_16x16x32_bf16 v[12:15], v[156:159], v[220:223], v[12:15]
	v_mfma_f32_16x16x32_bf16 v[12:15], v[160:163], v[224:227], v[12:15]
	v_mfma_f32_16x16x32_bf16 v[8:11], v[168:171], v[224:227], v[8:11]
	v_mfma_f32_16x16x32_bf16 v[8:11], v[164:167], v[220:223], v[8:11]
	v_mfma_f32_16x16x32_bf16 v[0:3], v[164:167], v[228:231], v[0:3]
	v_mfma_f32_16x16x32_bf16 v[0:3], v[168:171], v[232:235], v[0:3]
	v_mfma_f32_16x16x32_bf16 v[4:7], v[160:163], v[232:235], v[4:7]
	v_mfma_f32_16x16x32_bf16 v[4:7], v[156:159], v[228:231], v[4:7]
	s_setprio 0
	s_barrier
	v_add_u32_e32 v152, s79, v138
	v_add_u32_e32 v168, s78, v138
	ds_read_b128 v[140:143], v152
	ds_read_b128 v[144:147], v152 offset:1024
	ds_read_b128 v[148:151], v152 offset:2048
	ds_read_b128 v[152:155], v152 offset:3072
	ds_read_b128 v[156:159], v168
	ds_read_b128 v[160:163], v168 offset:1024
	ds_read_b128 v[164:167], v168 offset:2048
	ds_read_b128 v[168:171], v168 offset:3072
	s_mov_b32 m0, s36
	v_lshl_add_u64 v[206:207], s[22:23], 0, v[134:135]
	ds_read_b128 v[172:175], v139 offset:32768
	ds_read_b128 v[182:185], v139 offset:33792
	ds_read_b128 v[188:191], v139 offset:34816
	ds_read_b128 v[216:219], v139 offset:35840
	ds_read_b128 v[220:223], v139 offset:36864
	ds_read_b128 v[224:227], v139 offset:37888
	ds_read_b128 v[228:231], v139 offset:38912
	ds_read_b128 v[232:235], v139 offset:39936
	global_load_lds_dwordx4 v[206:207], off
	v_lshl_add_u64 v[206:207], s[22:23], 0, v[132:133]
	s_mov_b32 m0, s37
	s_nop 0
	global_load_lds_dwordx4 v[206:207], off
	s_waitcnt vmcnt(8)
	s_waitcnt lgkmcnt(0)
	s_barrier
	s_setprio 1
	s_waitcnt lgkmcnt(0)
	v_mfma_f32_16x16x32_bf16 v[126:129], v[140:143], v[172:175], v[126:129]
	v_mfma_f32_16x16x32_bf16 v[126:129], v[144:147], v[182:185], v[126:129]
	v_mfma_f32_16x16x32_bf16 v[122:125], v[152:155], v[182:185], v[122:125]
	v_mfma_f32_16x16x32_bf16 v[122:125], v[148:151], v[172:175], v[122:125]
	v_mfma_f32_16x16x32_bf16 v[114:117], v[148:151], v[188:191], v[114:117]
	v_mfma_f32_16x16x32_bf16 v[114:117], v[152:155], v[216:219], v[114:117]
	v_mfma_f32_16x16x32_bf16 v[118:121], v[144:147], v[216:219], v[118:121]
	v_mfma_f32_16x16x32_bf16 v[118:121], v[140:143], v[188:191], v[118:121]
	v_mfma_f32_16x16x32_bf16 v[106:109], v[140:143], v[220:223], v[106:109]
	v_mfma_f32_16x16x32_bf16 v[106:109], v[144:147], v[224:227], v[106:109]
	v_mfma_f32_16x16x32_bf16 v[98:101], v[152:155], v[224:227], v[98:101]
	v_mfma_f32_16x16x32_bf16 v[98:101], v[148:151], v[220:223], v[98:101]
	v_mfma_f32_16x16x32_bf16 v[82:85], v[148:151], v[228:231], v[82:85]
	v_mfma_f32_16x16x32_bf16 v[82:85], v[152:155], v[232:235], v[82:85]
	v_mfma_f32_16x16x32_bf16 v[90:93], v[144:147], v[232:235], v[90:93]
	v_mfma_f32_16x16x32_bf16 v[90:93], v[140:143], v[228:231], v[90:93]
	s_setprio 0
	s_setprio 1
	v_mfma_f32_16x16x32_bf16 v[110:113], v[156:159], v[172:175], v[110:113]
	v_mfma_f32_16x16x32_bf16 v[110:113], v[160:163], v[182:185], v[110:113]
	v_mfma_f32_16x16x32_bf16 v[102:105], v[168:171], v[182:185], v[102:105]
	v_mfma_f32_16x16x32_bf16 v[102:105], v[164:167], v[172:175], v[102:105]
	v_mfma_f32_16x16x32_bf16 v[86:89], v[164:167], v[188:191], v[86:89]
	v_mfma_f32_16x16x32_bf16 v[86:89], v[168:171], v[216:219], v[86:89]
	v_mfma_f32_16x16x32_bf16 v[94:97], v[160:163], v[216:219], v[94:97]
	v_mfma_f32_16x16x32_bf16 v[94:97], v[156:159], v[188:191], v[94:97]
	v_mfma_f32_16x16x32_bf16 v[76:79], v[156:159], v[220:223], v[76:79]
	v_mfma_f32_16x16x32_bf16 v[76:79], v[160:163], v[224:227], v[76:79]
	v_mfma_f32_16x16x32_bf16 v[72:75], v[168:171], v[224:227], v[72:75]
	v_mfma_f32_16x16x32_bf16 v[72:75], v[164:167], v[220:223], v[72:75]
	v_mfma_f32_16x16x32_bf16 v[64:67], v[164:167], v[228:231], v[64:67]
	v_mfma_f32_16x16x32_bf16 v[64:67], v[168:171], v[232:235], v[64:67]
	v_mfma_f32_16x16x32_bf16 v[68:71], v[160:163], v[232:235], v[68:71]
	v_mfma_f32_16x16x32_bf16 v[68:71], v[156:159], v[228:231], v[68:71]
	s_setprio 0
	s_barrier
; #define PG8_STAGE(bufoff, gbase, voff) do { _Pragma("unroll") for (int _i = 0; _i < 2; ++_i) \
;         __builtin_amdgcn_global_load_lds((const unsigned*)((const char*)(gbase) + (voff)[_i]), (PG8_LAS unsigned*)(lds + (bufoff) + ldsw + _i * 8192), 16, 0, 0); } while (0)
; #define PG8_LDA(dst, b, h) do { _Pragma("unroll") for (int m = 0; m < 4; ++m) _Pragma("unroll") for (int k = 0; k < 2; ++k) dst[m][k] = *(const PG8_LAS bf16x8*)(lds + PG8_SA(b, h) + aoff + m * 2048 + k * 1024); } while (0)
; #define PG8_MMA(ai, bj, At, Bt) do { __builtin_amdgcn_s_setprio(1); _Pragma("unroll") for (int m = 0; m < 4; ++m) _Pragma("unroll") for (int n = 0; n < 2; ++n) _Pragma("unroll") for (int k = 0; k < 2; ++k) \
;         acc[ai][bj][m][n] = __builtin_amdgcn_mfma_f32_16x16x32_bf16(Bt[n][k], At[m][k], acc[ai][bj][m][n], 0, 0, 0); __builtin_amdgcn_s_setprio(0); } while (0)
; #define PG8_WAIT_V(n) asm volatile("s_waitcnt vmcnt(" #n ")" ::: "memory")
; #define PG8_WAIT_L(n) asm volatile("s_waitcnt lgkmcnt(" #n ")" ::: "memory")
; #define PG8_BAR __builtin_amdgcn_s_barrier()
; #define PG8_SCHED __builtin_amdgcn_sched_barrier(0)
; template <class Epi, class Sched, bool ALIGN_EPI = false, bool SP2 = false>
; __device__ __forceinline__ void gemm_phase(PG8_LAS unsigned char* lds, const Gemm g, const Sched& S, const Epi& E) {
;     ...
;             PG8_LDA(At, 1, 1); PG8_STAGE(PG8_SB(1, 0), b3, voffB); PG8_STAGE(PG8_SB(1, 1), b3 + hstepB, voffB); PG8_STAGE(PG8_SA(1, 0), a3, voffA);
;             PG8_WAIT_V(8); PG8_WAIT_L(0); PG8_BAR; PG8_MMA(1, 0, At, B0); PG8_MMA(1, 1, At, B1); PG8_BAR; PG8_SCHED;
;     ...
;         if constexpr (ALIGN_EPI) { if (wr == 0) PG8_BAR; }
	s_mov_b32 m0, s45
	v_lshl_add_u64 v[176:177], v[176:177], 0, s[60:61]
	ds_read_b128 v[172:175], v139 offset:49152
	ds_read_b128 v[182:185], v139 offset:50176
	ds_read_b128 v[188:191], v139 offset:51200
	ds_read_b128 v[216:219], v139 offset:52224
	ds_read_b128 v[220:223], v139 offset:53248
	ds_read_b128 v[224:227], v139 offset:54272
	ds_read_b128 v[228:231], v139 offset:55296
	ds_read_b128 v[232:235], v139 offset:56320
	global_load_lds_dwordx4 v[176:177], off
	v_lshl_add_u64 v[176:177], v[192:193], 0, s[60:61]
	s_mov_b32 m0, s43
	s_nop 0
	global_load_lds_dwordx4 v[176:177], off
	v_lshl_add_u64 v[176:177], s[64:65], 0, v[80:81]
	s_mov_b32 m0, s85
	s_nop 0
	global_load_lds_dwordx4 v[176:177], off
	v_lshl_add_u64 v[176:177], s[64:65], 0, v[130:131]
	s_mov_b32 m0, s84
	s_nop 0
	global_load_lds_dwordx4 v[176:177], off
	v_lshl_add_u64 v[176:177], v[202:203], 0, s[60:61]
	s_mov_b32 m0, s55
	s_nop 0
	global_load_lds_dwordx4 v[176:177], off
	v_lshl_add_u64 v[176:177], v[204:205], 0, s[60:61]
	s_mov_b32 m0, s72
	s_nop 0
	global_load_lds_dwordx4 v[176:177], off
	s_waitcnt vmcnt(8)
	s_waitcnt lgkmcnt(0)
	s_barrier
	s_setprio 1
	s_waitcnt lgkmcnt(0)
	v_mfma_f32_16x16x32_bf16 v[60:63], v[140:143], v[172:175], v[60:63]
	v_mfma_f32_16x16x32_bf16 v[60:63], v[144:147], v[182:185], v[60:63]
	v_mfma_f32_16x16x32_bf16 v[56:59], v[152:155], v[182:185], v[56:59]
	v_mfma_f32_16x16x32_bf16 v[56:59], v[148:151], v[172:175], v[56:59]
	v_mfma_f32_16x16x32_bf16 v[48:51], v[148:151], v[188:191], v[48:51]
	v_mfma_f32_16x16x32_bf16 v[48:51], v[152:155], v[216:219], v[48:51]
	v_mfma_f32_16x16x32_bf16 v[52:55], v[144:147], v[216:219], v[52:55]
	v_mfma_f32_16x16x32_bf16 v[52:55], v[140:143], v[188:191], v[52:55]
	v_mfma_f32_16x16x32_bf16 v[36:39], v[140:143], v[220:223], v[36:39]
	v_mfma_f32_16x16x32_bf16 v[36:39], v[144:147], v[224:227], v[36:39]
	v_mfma_f32_16x16x32_bf16 v[32:35], v[152:155], v[224:227], v[32:35]
	v_mfma_f32_16x16x32_bf16 v[32:35], v[148:151], v[220:223], v[32:35]
	v_mfma_f32_16x16x32_bf16 v[16:19], v[148:151], v[228:231], v[16:19]
	v_mfma_f32_16x16x32_bf16 v[16:19], v[152:155], v[232:235], v[16:19]
	v_mfma_f32_16x16x32_bf16 v[20:23], v[144:147], v[232:235], v[20:23]
	v_mfma_f32_16x16x32_bf16 v[20:23], v[140:143], v[228:231], v[20:23]
	s_setprio 0
	s_setprio 1
	v_mfma_f32_16x16x32_bf16 v[44:47], v[156:159], v[172:175], v[44:47]
	v_mfma_f32_16x16x32_bf16 v[44:47], v[160:163], v[182:185], v[44:47]
	v_mfma_f32_16x16x32_bf16 v[40:43], v[168:171], v[182:185], v[40:43]
	v_mfma_f32_16x16x32_bf16 v[40:43], v[164:167], v[172:175], v[40:43]
	v_mfma_f32_16x16x32_bf16 v[24:27], v[164:167], v[188:191], v[24:27]
	v_mfma_f32_16x16x32_bf16 v[24:27], v[168:171], v[216:219], v[24:27]
	v_mfma_f32_16x16x32_bf16 v[28:31], v[160:163], v[216:219], v[28:31]
	v_mfma_f32_16x16x32_bf16 v[28:31], v[156:159], v[188:191], v[28:31]
	v_mfma_f32_16x16x32_bf16 v[12:15], v[156:159], v[220:223], v[12:15]
	v_mfma_f32_16x16x32_bf16 v[12:15], v[160:163], v[224:227], v[12:15]
	v_mfma_f32_16x16x32_bf16 v[8:11], v[168:171], v[224:227], v[8:11]
	v_mfma_f32_16x16x32_bf16 v[8:11], v[164:167], v[220:223], v[8:11]
	v_mfma_f32_16x16x32_bf16 v[0:3], v[164:167], v[228:231], v[0:3]
	v_mfma_f32_16x16x32_bf16 v[0:3], v[168:171], v[232:235], v[0:3]
	v_mfma_f32_16x16x32_bf16 v[4:7], v[160:163], v[232:235], v[4:7]
	v_mfma_f32_16x16x32_bf16 v[4:7], v[156:159], v[228:231], v[4:7]
	s_setprio 0
	s_barrier
	s_movk_i32 s22, 0x100
	s_andn2_b64 vcc, exec, s[62:63]
	s_mov_b64 s[64:65], -1
	s_mov_b64 s[62:63], 0
	s_cbranch_vccz .LBB0_1088
	s_and_b64 vcc, exec, s[40:41]
	s_cbranch_vccz .LBB0_1091
	s_barrier

; #define PG8_STAGE(bufoff, gbase, voff) do { _Pragma("unroll") for (int _i = 0; _i < 2; ++_i) \
;         __builtin_amdgcn_global_load_lds((const unsigned*)((const char*)(gbase) + (voff)[_i]), (PG8_LAS unsigned*)(lds + (bufoff) + ldsw + _i * 8192), 16, 0, 0); } while (0)
; #define PG8_LDA(dst, b, h) do { _Pragma("unroll") for (int m = 0; m < 4; ++m) _Pragma("unroll") for (int k = 0; k < 2; ++k) dst[m][k] = *(const PG8_LAS bf16x8*)(lds + PG8_SA(b, h) + aoff + m * 2048 + k * 1024); } while (0)
; #define PG8_LDB(dst, b, h) do { _Pragma("unroll") for (int n = 0; n < 2; ++n) _Pragma("unroll") for (int k = 0; k < 2; ++k) dst[n][k] = *(const PG8_LAS bf16x8*)(lds + PG8_SB(b, h) + boff + n * 2048 + k * 1024); } while (0)
; #define PG8_MMA(ai, bj, At, Bt) do { __builtin_amdgcn_s_setprio(1); _Pragma("unroll") for (int m = 0; m < 4; ++m) _Pragma("unroll") for (int n = 0; n < 2; ++n) _Pragma("unroll") for (int k = 0; k < 2; ++k) \
;         acc[ai][bj][m][n] = __builtin_amdgcn_mfma_f32_16x16x32_bf16(Bt[n][k], At[m][k], acc[ai][bj][m][n], 0, 0, 0); __builtin_amdgcn_s_setprio(0); } while (0)
; #define PG8_BAR __builtin_amdgcn_s_barrier()
; template <class Epi, class Sched, bool ALIGN_EPI = false, bool SP2 = false>
; __device__ __forceinline__ void gemm_phase(PG8_LAS unsigned char* lds, const Gemm g, const Sched& S, const Epi& E) {
;     ...
;         for (int t = 0; t < nt; t += 2) {
;             if constexpr (Epi::MIDSCALE) { if (t == (nt >> 1)) E.mid(acc, cur, wr, fr); }
;             const bool last = (t == nt - 2);
;             const char* a1 = cA + (size_t)(t + 1) * kstep;
;             const char* a2 = last ? nA : cA + (size_t)(t + 2) * kstep; const char* b2 = last ? nB : cB + (size_t)(t + 2) * kstep;
;             const char* a3 = a2 + kstep; const char* b3 = b2 + kstep;
;             if (last && has_next) S.a_ready(nxt);
;             if constexpr (SP2) {
;             PG8_LDB(B0, 0, 0); PG8_LDB(B1, 0, 1); PG8_SCHED; PG8_LDA(At, 0, 0); PG8_STAGE(PG8_SA(1, 1), a1 + hstepA, voffA);
;             PG8_WAIT_V(8); PG8_WAIT_L(0); PG8_BAR; PG8_MMA(0, 0, At, B0); PG8_MMA(0, 1, At, B1); PG8_BAR; PG8_SCHED;
;             PG8_LDA(At, 0, 1); PG8_STAGE(PG8_SB(0, 0), b2, voffB); PG8_STAGE(PG8_SB(0, 1), b2 + hstepB, voffB); PG8_STAGE(PG8_SA(0, 0), a2, voffA);
;             PG8_WAIT_V(8); PG8_WAIT_L(0); PG8_BAR; PG8_MMA(1, 0, At, B0); PG8_MMA(1, 1, At, B1); PG8_BAR; PG8_SCHED;
.LBB0_1183:
	s_add_u32 s68, vcc_lo, 0xfff80080
	s_addc_u32 s69, vcc_hi, -1
	s_add_i32 s82, 0, 0x10000
	s_cmp_eq_u32 s81, 28
	s_cselect_b32 s71, s41, s69
	s_cselect_b32 s70, s67, s68
	v_add_u32_e32 v146, s82, v151
	s_cselect_b32 s69, s65, s80
	s_cselect_b32 s68, s78, s79
	s_add_i32 s84, 0, 0x14000
	ds_read_b128 v[142:145], v146
	ds_read_b128 v[156:159], v146 offset:1024
	ds_read_b128 v[160:163], v146 offset:2048
	ds_read_b128 v[164:167], v146 offset:3072
	v_add_u32_e32 v146, s84, v151
	ds_read_b128 v[168:171], v146
	ds_read_b128 v[172:175], v146 offset:1024
	ds_read_b128 v[182:185], v146 offset:2048
	ds_read_b128 v[188:191], v146 offset:3072
	v_lshl_add_u64 v[176:177], vcc, 0, v[138:139]
	s_add_i32 m0, s45, 0xc000
	ds_read_b128 v[216:219], v154
	ds_read_b128 v[220:223], v154 offset:1024
	ds_read_b128 v[224:227], v154 offset:2048
	ds_read_b128 v[228:231], v154 offset:3072
	ds_read_b128 v[232:235], v154 offset:4096
	ds_read_b128 v[236:239], v154 offset:5120
	ds_read_b128 v[240:243], v154 offset:6144
	ds_read_b128 v[244:247], v154 offset:7168
	global_load_lds_dwordx4 v[176:177], off
	v_lshl_add_u64 v[176:177], vcc, 0, v[140:141]
	s_add_i32 m0, s45, 0xe000
	s_nop 0
	global_load_lds_dwordx4 v[176:177], off
	s_waitcnt vmcnt(8)
	s_waitcnt lgkmcnt(0)
	s_barrier
	s_setprio 1
	s_waitcnt lgkmcnt(0)
	v_mfma_f32_16x16x32_bf16 v[126:129], v[142:145], v[216:219], v[126:129]
	v_mfma_f32_16x16x32_bf16 v[126:129], v[156:159], v[220:223], v[126:129]
	v_mfma_f32_16x16x32_bf16 v[122:125], v[164:167], v[220:223], v[122:125]
	v_mfma_f32_16x16x32_bf16 v[122:125], v[160:163], v[216:219], v[122:125]
	v_mfma_f32_16x16x32_bf16 v[106:109], v[160:163], v[224:227], v[106:109]
	v_mfma_f32_16x16x32_bf16 v[106:109], v[164:167], v[228:231], v[106:109]
	v_mfma_f32_16x16x32_bf16 v[110:113], v[156:159], v[228:231], v[110:113]
	v_mfma_f32_16x16x32_bf16 v[110:113], v[142:145], v[224:227], v[110:113]
	v_mfma_f32_16x16x32_bf16 v[94:97], v[142:145], v[232:235], v[94:97]
	v_mfma_f32_16x16x32_bf16 v[94:97], v[156:159], v[236:239], v[94:97]
	v_mfma_f32_16x16x32_bf16 v[90:93], v[164:167], v[236:239], v[90:93]
	v_mfma_f32_16x16x32_bf16 v[90:93], v[160:163], v[232:235], v[90:93]
	v_mfma_f32_16x16x32_bf16 v[72:75], v[160:163], v[240:243], v[72:75]
	v_mfma_f32_16x16x32_bf16 v[72:75], v[164:167], v[244:247], v[72:75]
	v_mfma_f32_16x16x32_bf16 v[76:79], v[156:159], v[244:247], v[76:79]
	v_mfma_f32_16x16x32_bf16 v[76:79], v[142:145], v[240:243], v[76:79]
	s_setprio 0
	s_setprio 1
	v_mfma_f32_16x16x32_bf16 v[118:121], v[168:171], v[216:219], v[118:121]
	v_mfma_f32_16x16x32_bf16 v[118:121], v[172:175], v[220:223], v[118:121]
	v_mfma_f32_16x16x32_bf16 v[114:117], v[188:191], v[220:223], v[114:117]
	v_mfma_f32_16x16x32_bf16 v[114:117], v[182:185], v[216:219], v[114:117]
	v_mfma_f32_16x16x32_bf16 v[98:101], v[182:185], v[224:227], v[98:101]
	v_mfma_f32_16x16x32_bf16 v[98:101], v[188:191], v[228:231], v[98:101]
	v_mfma_f32_16x16x32_bf16 v[102:105], v[172:175], v[228:231], v[102:105]
	v_mfma_f32_16x16x32_bf16 v[102:105], v[168:171], v[224:227], v[102:105]
	v_mfma_f32_16x16x32_bf16 v[86:89], v[168:171], v[232:235], v[86:89]
	v_mfma_f32_16x16x32_bf16 v[86:89], v[172:175], v[236:239], v[86:89]
	v_mfma_f32_16x16x32_bf16 v[82:85], v[188:191], v[236:239], v[82:85]
	v_mfma_f32_16x16x32_bf16 v[82:85], v[182:185], v[232:235], v[82:85]
	v_mfma_f32_16x16x32_bf16 v[64:67], v[182:185], v[240:243], v[64:67]
	v_mfma_f32_16x16x32_bf16 v[64:67], v[188:191], v[244:247], v[64:67]
	v_mfma_f32_16x16x32_bf16 v[68:71], v[172:175], v[244:247], v[68:71]
	v_mfma_f32_16x16x32_bf16 v[68:71], v[168:171], v[240:243], v[68:71]
	s_setprio 0
	s_barrier
	s_add_i32 s82, s82, s33
	v_lshl_add_u64 v[176:177], s[68:69], 0, v[132:133]
	s_mov_b32 m0, s82
	ds_read_b128 v[216:219], v154 offset:16384
	ds_read_b128 v[220:223], v154 offset:17408
	ds_read_b128 v[224:227], v154 offset:18432
	ds_read_b128 v[228:231], v154 offset:19456
	ds_read_b128 v[232:235], v154 offset:20480
	ds_read_b128 v[236:239], v154 offset:21504
	ds_read_b128 v[240:243], v154 offset:22528
	ds_read_b128 v[244:247], v154 offset:23552
	global_load_lds_dwordx4 v[176:177], off
	s_add_i32 m0, s82, 0x2000
	s_add_u32 s82, s68, 0x80000
	v_lshl_add_u64 v[192:193], s[68:69], 0, v[136:137]
	s_addc_u32 s83, s69, 0
	s_add_i32 s84, s84, s33
	global_load_lds_dwordx4 v[192:193], off
	v_lshl_add_u64 v[202:203], s[82:83], 0, v[132:133]
	s_mov_b32 m0, s84
	v_lshl_add_u64 v[204:205], s[70:71], 0, v[134:135]
	global_load_lds_dwordx4 v[202:203], off
	v_lshl_add_u64 v[202:203], s[82:83], 0, v[136:137]
	s_add_i32 m0, s84, 0x2000
	s_nop 0
	global_load_lds_dwordx4 v[202:203], off
	v_lshl_add_u64 v[202:203], s[70:71], 0, v[130:131]
	s_mov_b32 m0, s45
	s_nop 0
	global_load_lds_dwordx4 v[202:203], off
	s_mov_b32 m0, s49
	s_nop 0
	global_load_lds_dwordx4 v[204:205], off
	s_waitcnt vmcnt(8)
	s_waitcnt lgkmcnt(0)
	s_barrier
; #define PG8_STAGE(bufoff, gbase, voff) do { _Pragma("unroll") for (int _i = 0; _i < 2; ++_i) \
;         __builtin_amdgcn_global_load_lds((const unsigned*)((const char*)(gbase) + (voff)[_i]), (PG8_LAS unsigned*)(lds + (bufoff) + ldsw + _i * 8192), 16, 0, 0); } while (0)
; #define PG8_LDA(dst, b, h) do { _Pragma("unroll") for (int m = 0; m < 4; ++m) _Pragma("unroll") for (int k = 0; k < 2; ++k) dst[m][k] = *(const PG8_LAS bf16x8*)(lds + PG8_SA(b, h) + aoff + m * 2048 + k * 1024); } while (0)
; #define PG8_LDB(dst, b, h) do { _Pragma("unroll") for (int n = 0; n < 2; ++n) _Pragma("unroll") for (int k = 0; k < 2; ++k) dst[n][k] = *(const PG8_LAS bf16x8*)(lds + PG8_SB(b, h) + boff + n * 2048 + k * 1024); } while (0)
; #define PG8_MMA(ai, bj, At, Bt) do { __builtin_amdgcn_s_setprio(1); _Pragma("unroll") for (int m = 0; m < 4; ++m) _Pragma("unroll") for (int n = 0; n < 2; ++n) _Pragma("unroll") for (int k = 0; k < 2; ++k) \
;         acc[ai][bj][m][n] = __builtin_amdgcn_mfma_f32_16x16x32_bf16(Bt[n][k], At[m][k], acc[ai][bj][m][n], 0, 0, 0); __builtin_amdgcn_s_setprio(0); } while (0)
; #define PG8_WAIT_V(n) asm volatile("s_waitcnt vmcnt(" #n ")" ::: "memory")
; #define PG8_WAIT_L(n) asm volatile("s_waitcnt lgkmcnt(" #n ")" ::: "memory")
; #define PG8_BAR __builtin_amdgcn_s_barrier()
; #define PG8_SCHED __builtin_amdgcn_sched_barrier(0)
; template <class Epi, class Sched, bool ALIGN_EPI = false, bool SP2 = false>
; __device__ __forceinline__ void gemm_phase(PG8_LAS unsigned char* lds, const Gemm g, const Sched& S, const Epi& E) {
;     ...
;             PG8_WAIT_V(8); PG8_WAIT_L(0); PG8_BAR; PG8_MMA(1, 0, At, B0); PG8_MMA(1, 1, At, B1); PG8_BAR; PG8_SCHED;
;             PG8_LDB(B0, 1, 0); PG8_LDB(B1, 1, 1); PG8_SCHED; PG8_LDA(At, 1, 0); PG8_STAGE(PG8_SA(0, 1), a2 + hstepA, voffA);
;             PG8_WAIT_V(8); PG8_WAIT_L(0); PG8_BAR; PG8_MMA(0, 0, At, B0); PG8_MMA(0, 1, At, B1); PG8_BAR; PG8_SCHED;
	s_setprio 1
	s_waitcnt lgkmcnt(0)
	v_mfma_f32_16x16x32_bf16 v[60:63], v[142:145], v[216:219], v[60:63]
	v_mfma_f32_16x16x32_bf16 v[60:63], v[156:159], v[220:223], v[60:63]
	v_mfma_f32_16x16x32_bf16 v[56:59], v[164:167], v[220:223], v[56:59]
	v_mfma_f32_16x16x32_bf16 v[56:59], v[160:163], v[216:219], v[56:59]
	v_mfma_f32_16x16x32_bf16 v[40:43], v[160:163], v[224:227], v[40:43]
	v_mfma_f32_16x16x32_bf16 v[40:43], v[164:167], v[228:231], v[40:43]
	v_mfma_f32_16x16x32_bf16 v[48:51], v[156:159], v[228:231], v[48:51]
	v_mfma_f32_16x16x32_bf16 v[48:51], v[142:145], v[224:227], v[48:51]
	v_mfma_f32_16x16x32_bf16 v[32:35], v[142:145], v[232:235], v[32:35]
	v_mfma_f32_16x16x32_bf16 v[32:35], v[156:159], v[236:239], v[32:35]
	v_mfma_f32_16x16x32_bf16 v[24:27], v[164:167], v[236:239], v[24:27]
	v_mfma_f32_16x16x32_bf16 v[24:27], v[160:163], v[232:235], v[24:27]
	v_mfma_f32_16x16x32_bf16 v[8:11], v[160:163], v[240:243], v[8:11]
	v_mfma_f32_16x16x32_bf16 v[8:11], v[164:167], v[244:247], v[8:11]
	v_mfma_f32_16x16x32_bf16 v[12:15], v[156:159], v[244:247], v[12:15]
	v_mfma_f32_16x16x32_bf16 v[12:15], v[142:145], v[240:243], v[12:15]
	s_setprio 0
	s_setprio 1
	v_mfma_f32_16x16x32_bf16 v[52:55], v[168:171], v[216:219], v[52:55]
	v_mfma_f32_16x16x32_bf16 v[52:55], v[172:175], v[220:223], v[52:55]
	v_mfma_f32_16x16x32_bf16 v[44:47], v[188:191], v[220:223], v[44:47]
	v_mfma_f32_16x16x32_bf16 v[44:47], v[182:185], v[216:219], v[44:47]
	v_mfma_f32_16x16x32_bf16 v[28:31], v[182:185], v[224:227], v[28:31]
	v_mfma_f32_16x16x32_bf16 v[28:31], v[188:191], v[228:231], v[28:31]
	v_mfma_f32_16x16x32_bf16 v[36:39], v[172:175], v[228:231], v[36:39]
	v_mfma_f32_16x16x32_bf16 v[36:39], v[168:171], v[224:227], v[36:39]
	v_mfma_f32_16x16x32_bf16 v[20:23], v[168:171], v[232:235], v[20:23]
	v_mfma_f32_16x16x32_bf16 v[20:23], v[172:175], v[236:239], v[20:23]
	v_mfma_f32_16x16x32_bf16 v[16:19], v[188:191], v[236:239], v[16:19]
	v_mfma_f32_16x16x32_bf16 v[16:19], v[182:185], v[232:235], v[16:19]
	v_mfma_f32_16x16x32_bf16 v[0:3], v[182:185], v[240:243], v[0:3]
	v_mfma_f32_16x16x32_bf16 v[0:3], v[188:191], v[244:247], v[0:3]
	v_mfma_f32_16x16x32_bf16 v[4:7], v[172:175], v[244:247], v[4:7]
	v_mfma_f32_16x16x32_bf16 v[4:7], v[168:171], v[240:243], v[4:7]
	s_setprio 0
	s_barrier
	s_add_i32 s82, 0, 0x18000
	v_add_u32_e32 v146, s82, v151
	s_add_i32 s83, 0, 0x1c000
	ds_read_b128 v[142:145], v146
	ds_read_b128 v[156:159], v146 offset:1024
	ds_read_b128 v[160:163], v146 offset:2048
	ds_read_b128 v[164:167], v146 offset:3072
	v_add_u32_e32 v146, s83, v151
	ds_read_b128 v[168:171], v146
	ds_read_b128 v[172:175], v146 offset:1024
	ds_read_b128 v[182:185], v146 offset:2048
	ds_read_b128 v[188:191], v146 offset:3072
	s_add_u32 s70, s70, 0x80000
	s_addc_u32 s71, s71, 0
	s_mov_b32 m0, s72
	v_lshl_add_u64 v[206:207], s[70:71], 0, v[130:131]
	ds_read_b128 v[216:219], v154 offset:32768
	ds_read_b128 v[220:223], v154 offset:33792
	ds_read_b128 v[224:227], v154 offset:34816
	ds_read_b128 v[228:231], v154 offset:35840
	ds_read_b128 v[232:235], v154 offset:36864
	ds_read_b128 v[236:239], v154 offset:37888
	ds_read_b128 v[240:243], v154 offset:38912
	ds_read_b128 v[244:247], v154 offset:39936
	global_load_lds_dwordx4 v[206:207], off
	v_lshl_add_u64 v[206:207], s[70:71], 0, v[134:135]
	s_mov_b32 m0, s73
	s_nop 0
	global_load_lds_dwordx4 v[206:207], off
	s_waitcnt vmcnt(8)
	s_waitcnt lgkmcnt(0)
	s_barrier
	s_setprio 1
	s_waitcnt lgkmcnt(0)
	v_mfma_f32_16x16x32_bf16 v[126:129], v[142:145], v[216:219], v[126:129]
	v_mfma_f32_16x16x32_bf16 v[126:129], v[156:159], v[220:223], v[126:129]
	v_mfma_f32_16x16x32_bf16 v[122:125], v[164:167], v[220:223], v[122:125]
	v_mfma_f32_16x16x32_bf16 v[122:125], v[160:163], v[216:219], v[122:125]
	v_mfma_f32_16x16x32_bf16 v[106:109], v[160:163], v[224:227], v[106:109]
	v_mfma_f32_16x16x32_bf16 v[106:109], v[164:167], v[228:231], v[106:109]
	v_mfma_f32_16x16x32_bf16 v[110:113], v[156:159], v[228:231], v[110:113]
	v_mfma_f32_16x16x32_bf16 v[110:113], v[142:145], v[224:227], v[110:113]
	v_mfma_f32_16x16x32_bf16 v[94:97], v[142:145], v[232:235], v[94:97]
	v_mfma_f32_16x16x32_bf16 v[94:97], v[156:159], v[236:239], v[94:97]
	v_mfma_f32_16x16x32_bf16 v[90:93], v[164:167], v[236:239], v[90:93]
	v_mfma_f32_16x16x32_bf16 v[90:93], v[160:163], v[232:235], v[90:93]
	v_mfma_f32_16x16x32_bf16 v[72:75], v[160:163], v[240:243], v[72:75]
	v_mfma_f32_16x16x32_bf16 v[72:75], v[164:167], v[244:247], v[72:75]
	v_mfma_f32_16x16x32_bf16 v[76:79], v[156:159], v[244:247], v[76:79]
	v_mfma_f32_16x16x32_bf16 v[76:79], v[142:145], v[240:243], v[76:79]
	s_setprio 0
	s_setprio 1
	v_mfma_f32_16x16x32_bf16 v[118:121], v[168:171], v[216:219], v[118:121]
	v_mfma_f32_16x16x32_bf16 v[118:121], v[172:175], v[220:223], v[118:121]
	v_mfma_f32_16x16x32_bf16 v[114:117], v[188:191], v[220:223], v[114:117]
	v_mfma_f32_16x16x32_bf16 v[114:117], v[182:185], v[216:219], v[114:117]
	v_mfma_f32_16x16x32_bf16 v[98:101], v[182:185], v[224:227], v[98:101]
	v_mfma_f32_16x16x32_bf16 v[98:101], v[188:191], v[228:231], v[98:101]
	v_mfma_f32_16x16x32_bf16 v[102:105], v[172:175], v[228:231], v[102:105]
	v_mfma_f32_16x16x32_bf16 v[102:105], v[168:171], v[224:227], v[102:105]
	v_mfma_f32_16x16x32_bf16 v[86:89], v[168:171], v[232:235], v[86:89]
	v_mfma_f32_16x16x32_bf16 v[86:89], v[172:175], v[236:239], v[86:89]
	v_mfma_f32_16x16x32_bf16 v[82:85], v[188:191], v[236:239], v[82:85]
	v_mfma_f32_16x16x32_bf16 v[82:85], v[182:185], v[232:235], v[82:85]
	v_mfma_f32_16x16x32_bf16 v[64:67], v[182:185], v[240:243], v[64:67]
	v_mfma_f32_16x16x32_bf16 v[64:67], v[188:191], v[244:247], v[64:67]
	v_mfma_f32_16x16x32_bf16 v[68:71], v[172:175], v[244:247], v[68:71]
	v_mfma_f32_16x16x32_bf16 v[68:71], v[168:171], v[240:243], v[68:71]
	s_setprio 0
	s_barrier
; #define PG8_STAGE(bufoff, gbase, voff) do { _Pragma("unroll") for (int _i = 0; _i < 2; ++_i) \
;         __builtin_amdgcn_global_load_lds((const unsigned*)((const char*)(gbase) + (voff)[_i]), (PG8_LAS unsigned*)(lds + (bufoff) + ldsw + _i * 8192), 16, 0, 0); } while (0)
; #define PG8_LDA(dst, b, h) do { _Pragma("unroll") for (int m = 0; m < 4; ++m) _Pragma("unroll") for (int k = 0; k < 2; ++k) dst[m][k] = *(const PG8_LAS bf16x8*)(lds + PG8_SA(b, h) + aoff + m * 2048 + k * 1024); } while (0)
; #define PG8_MMA(ai, bj, At, Bt) do { __builtin_amdgcn_s_setprio(1); _Pragma("unroll") for (int m = 0; m < 4; ++m) _Pragma("unroll") for (int n = 0; n < 2; ++n) _Pragma("unroll") for (int k = 0; k < 2; ++k) \
;         acc[ai][bj][m][n] = __builtin_amdgcn_mfma_f32_16x16x32_bf16(Bt[n][k], At[m][k], acc[ai][bj][m][n], 0, 0, 0); __builtin_amdgcn_s_setprio(0); } while (0)
; #define PG8_WAIT_V(n) asm volatile("s_waitcnt vmcnt(" #n ")" ::: "memory")
; #define PG8_WAIT_L(n) asm volatile("s_waitcnt lgkmcnt(" #n ")" ::: "memory")
; #define PG8_BAR __builtin_amdgcn_s_barrier()
; #define PG8_SCHED __builtin_amdgcn_sched_barrier(0)
; template <class Epi, class Sched, bool ALIGN_EPI = false, bool SP2 = false>
; __device__ __forceinline__ void gemm_phase(PG8_LAS unsigned char* lds, const Gemm g, const Sched& S, const Epi& E) {
;     ...
;             PG8_LDA(At, 1, 1); PG8_STAGE(PG8_SB(1, 0), b3, voffB); PG8_STAGE(PG8_SB(1, 1), b3 + hstepB, voffB); PG8_STAGE(PG8_SA(1, 0), a3, voffA);
;             PG8_WAIT_V(8); PG8_WAIT_L(0); PG8_BAR; PG8_MMA(1, 0, At, B0); PG8_MMA(1, 1, At, B1); PG8_BAR; PG8_SCHED;
;     ...
;         if constexpr (ALIGN_EPI) { if (wr == 0) PG8_BAR; }
	s_add_i32 s70, s82, s33
	v_lshl_add_u64 v[176:177], v[176:177], 0, s[60:61]
	s_mov_b32 m0, s70
	ds_read_b128 v[216:219], v154 offset:49152
	ds_read_b128 v[220:223], v154 offset:50176
	ds_read_b128 v[224:227], v154 offset:51200
	ds_read_b128 v[228:231], v154 offset:52224
	ds_read_b128 v[232:235], v154 offset:53248
	ds_read_b128 v[236:239], v154 offset:54272
	ds_read_b128 v[240:243], v154 offset:55296
	ds_read_b128 v[244:247], v154 offset:56320
	global_load_lds_dwordx4 v[176:177], off
	s_add_i32 m0, s70, 0x2000
	s_add_u32 s68, s68, 0x80080
	v_lshl_add_u64 v[176:177], v[192:193], 0, s[60:61]
	s_addc_u32 s69, s69, 0
	s_add_i32 s70, s83, s33
	global_load_lds_dwordx4 v[176:177], off
	v_lshl_add_u64 v[176:177], s[68:69], 0, v[132:133]
	s_mov_b32 m0, s70
	s_nop 0
	global_load_lds_dwordx4 v[176:177], off
	v_lshl_add_u64 v[176:177], s[68:69], 0, v[136:137]
	s_add_i32 m0, s70, 0x2000
	s_nop 0
	global_load_lds_dwordx4 v[176:177], off
	v_lshl_add_u64 v[176:177], v[202:203], 0, s[60:61]
	s_mov_b32 m0, s75
	s_nop 0
	global_load_lds_dwordx4 v[176:177], off
	v_lshl_add_u64 v[176:177], v[204:205], 0, s[60:61]
	s_mov_b32 m0, s76
	s_nop 0
	global_load_lds_dwordx4 v[176:177], off
	s_waitcnt vmcnt(8)
	s_waitcnt lgkmcnt(0)
	s_barrier
	s_setprio 1
	s_waitcnt lgkmcnt(0)
	v_mfma_f32_16x16x32_bf16 v[60:63], v[142:145], v[216:219], v[60:63]
	v_mfma_f32_16x16x32_bf16 v[60:63], v[156:159], v[220:223], v[60:63]
	v_mfma_f32_16x16x32_bf16 v[56:59], v[164:167], v[220:223], v[56:59]
	v_mfma_f32_16x16x32_bf16 v[56:59], v[160:163], v[216:219], v[56:59]
	v_mfma_f32_16x16x32_bf16 v[40:43], v[160:163], v[224:227], v[40:43]
	v_mfma_f32_16x16x32_bf16 v[40:43], v[164:167], v[228:231], v[40:43]
	v_mfma_f32_16x16x32_bf16 v[48:51], v[156:159], v[228:231], v[48:51]
	v_mfma_f32_16x16x32_bf16 v[48:51], v[142:145], v[224:227], v[48:51]
	v_mfma_f32_16x16x32_bf16 v[32:35], v[142:145], v[232:235], v[32:35]
	v_mfma_f32_16x16x32_bf16 v[32:35], v[156:159], v[236:239], v[32:35]
	v_mfma_f32_16x16x32_bf16 v[24:27], v[164:167], v[236:239], v[24:27]
	v_mfma_f32_16x16x32_bf16 v[24:27], v[160:163], v[232:235], v[24:27]
	v_mfma_f32_16x16x32_bf16 v[8:11], v[160:163], v[240:243], v[8:11]
	v_mfma_f32_16x16x32_bf16 v[8:11], v[164:167], v[244:247], v[8:11]
	v_mfma_f32_16x16x32_bf16 v[12:15], v[156:159], v[244:247], v[12:15]
	v_mfma_f32_16x16x32_bf16 v[12:15], v[142:145], v[240:243], v[12:15]
	s_setprio 0
	s_setprio 1
	v_mfma_f32_16x16x32_bf16 v[52:55], v[168:171], v[216:219], v[52:55]
	v_mfma_f32_16x16x32_bf16 v[52:55], v[172:175], v[220:223], v[52:55]
	v_mfma_f32_16x16x32_bf16 v[44:47], v[188:191], v[220:223], v[44:47]
	v_mfma_f32_16x16x32_bf16 v[44:47], v[182:185], v[216:219], v[44:47]
	v_mfma_f32_16x16x32_bf16 v[28:31], v[182:185], v[224:227], v[28:31]
	v_mfma_f32_16x16x32_bf16 v[28:31], v[188:191], v[228:231], v[28:31]
	v_mfma_f32_16x16x32_bf16 v[36:39], v[172:175], v[228:231], v[36:39]
	v_mfma_f32_16x16x32_bf16 v[36:39], v[168:171], v[224:227], v[36:39]
	v_mfma_f32_16x16x32_bf16 v[20:23], v[168:171], v[232:235], v[20:23]
	v_mfma_f32_16x16x32_bf16 v[20:23], v[172:175], v[236:239], v[20:23]
	v_mfma_f32_16x16x32_bf16 v[16:19], v[188:191], v[236:239], v[16:19]
	v_mfma_f32_16x16x32_bf16 v[16:19], v[182:185], v[232:235], v[16:19]
	v_mfma_f32_16x16x32_bf16 v[0:3], v[182:185], v[240:243], v[0:3]
	v_mfma_f32_16x16x32_bf16 v[0:3], v[188:191], v[244:247], v[0:3]
	v_mfma_f32_16x16x32_bf16 v[4:7], v[172:175], v[244:247], v[4:7]
	v_mfma_f32_16x16x32_bf16 v[4:7], v[168:171], v[240:243], v[4:7]
	s_setprio 0
	s_barrier
	s_add_i32 s81, s81, 2
	s_add_u32 vcc_lo, vcc_lo, 0x100
	s_addc_u32 vcc_hi, vcc_hi, 0
	s_add_u32 s79, s79, 0x100
	s_addc_u32 s80, s80, 0
	s_cmp_gt_u32 s81, 29
	s_cbranch_scc0 .LBB0_1183
	s_and_b64 vcc, exec, s[62:63]
	s_cbranch_vccz .LBB0_1186
	s_barrier

; #define PG8_STAGE(bufoff, gbase, voff) do { _Pragma("unroll") for (int _i = 0; _i < 2; ++_i) \
;         __builtin_amdgcn_global_load_lds((const unsigned*)((const char*)(gbase) + (voff)[_i]), (PG8_LAS unsigned*)(lds + (bufoff) + ldsw + _i * 8192), 16, 0, 0); } while (0)
; #define PG8_LDA(dst, b, h) do { _Pragma("unroll") for (int m = 0; m < 4; ++m) _Pragma("unroll") for (int k = 0; k < 2; ++k) dst[m][k] = *(const PG8_LAS bf16x8*)(lds + PG8_SA(b, h) + aoff + m * 2048 + k * 1024); } while (0)
; #define PG8_LDB(dst, b, h) do { _Pragma("unroll") for (int n = 0; n < 2; ++n) _Pragma("unroll") for (int k = 0; k < 2; ++k) dst[n][k] = *(const PG8_LAS bf16x8*)(lds + PG8_SB(b, h) + boff + n * 2048 + k * 1024); } while (0)
; #define PG8_MMA(ai, bj, At, Bt) do { __builtin_amdgcn_s_setprio(1); _Pragma("unroll") for (int m = 0; m < 4; ++m) _Pragma("unroll") for (int n = 0; n < 2; ++n) _Pragma("unroll") for (int k = 0; k < 2; ++k) \
;         acc[ai][bj][m][n] = __builtin_amdgcn_mfma_f32_16x16x32_bf16(Bt[n][k], At[m][k], acc[ai][bj][m][n], 0, 0, 0); __builtin_amdgcn_s_setprio(0); } while (0)
; #define PG8_WAIT_V(n) asm volatile("s_waitcnt vmcnt(" #n ")" ::: "memory")
; #define PG8_WAIT_L(n) asm volatile("s_waitcnt lgkmcnt(" #n ")" ::: "memory")
; #define PG8_BAR __builtin_amdgcn_s_barrier()
; #define PG8_SCHED __builtin_amdgcn_sched_barrier(0)
; template <class Epi, class Sched, bool ALIGN_EPI = false, bool SP2 = false>
; __device__ __forceinline__ void gemm_phase(PG8_LAS unsigned char* lds, const Gemm g, const Sched& S, const Epi& E) {
;     ...
;             const bool last = (t == nt - 2);
;             const char* a1 = cA + (size_t)(t + 1) * kstep;
;             const char* a2 = last ? nA : cA + (size_t)(t + 2) * kstep; const char* b2 = last ? nB : cB + (size_t)(t + 2) * kstep;
;             const char* a3 = a2 + kstep; const char* b3 = b2 + kstep;
;             if (last && has_next) S.a_ready(nxt);
;             if constexpr (SP2) {
;             PG8_LDB(B0, 0, 0); PG8_LDB(B1, 0, 1); PG8_SCHED; PG8_LDA(At, 0, 0); PG8_STAGE(PG8_SA(1, 1), a1 + hstepA, voffA);
;             PG8_WAIT_V(8); PG8_WAIT_L(0); PG8_BAR; PG8_MMA(0, 0, At, B0); PG8_MMA(0, 1, At, B1); PG8_BAR; PG8_SCHED;
;             PG8_LDA(At, 0, 1); PG8_STAGE(PG8_SB(0, 0), b2, voffB); PG8_STAGE(PG8_SB(0, 1), b2 + hstepB, voffB); PG8_STAGE(PG8_SA(0, 0), a2, voffA);
.LBB0_1367:
	s_add_u32 s22, s66, 0xffe00080
	s_addc_u32 s23, s67, -1
	s_add_i32 s74, 0, 0x10000
	s_cmp_eq_u32 s73, 12
	s_cselect_b32 s57, s53, s23
	s_cselect_b32 s56, s52, s22
	s_cselect_b32 s23, s63, s43
	s_cselect_b32 s22, s62, s41
	s_add_i32 s76, 0, 0x14000
	v_add_u32_e32 v156, s74, v142
	v_add_u32_e32 v172, s76, v142
	ds_read_b128 v[144:147], v156
	ds_read_b128 v[148:151], v156 offset:1024
	ds_read_b128 v[152:155], v156 offset:2048
	ds_read_b128 v[156:159], v156 offset:3072
	ds_read_b128 v[160:163], v172
	ds_read_b128 v[164:167], v172 offset:1024
	ds_read_b128 v[168:171], v172 offset:2048
	ds_read_b128 v[172:175], v172 offset:3072
	v_lshl_add_u64 v[176:177], s[66:67], 0, v[136:137]
	s_add_i32 m0, s35, 0xc000
	ds_read_b128 v[182:185], v143
	ds_read_b128 v[188:191], v143 offset:1024
	ds_read_b128 v[216:219], v143 offset:2048
	ds_read_b128 v[220:223], v143 offset:3072
	ds_read_b128 v[224:227], v143 offset:4096
	ds_read_b128 v[228:231], v143 offset:5120
	ds_read_b128 v[232:235], v143 offset:6144
	ds_read_b128 v[236:239], v143 offset:7168
	global_load_lds_dwordx4 v[176:177], off
	v_lshl_add_u64 v[176:177], s[66:67], 0, v[138:139]
	s_add_i32 m0, s35, 0xe000
	s_nop 0
	global_load_lds_dwordx4 v[176:177], off
	s_waitcnt vmcnt(8)
	s_waitcnt lgkmcnt(0)
	s_barrier
	s_setprio 1
	s_waitcnt lgkmcnt(0)
	v_mfma_f32_16x16x32_bf16 v[126:129], v[144:147], v[182:185], v[126:129]
	v_mfma_f32_16x16x32_bf16 v[126:129], v[148:151], v[188:191], v[126:129]
	v_mfma_f32_16x16x32_bf16 v[122:125], v[156:159], v[188:191], v[122:125]
	v_mfma_f32_16x16x32_bf16 v[122:125], v[152:155], v[182:185], v[122:125]
	v_mfma_f32_16x16x32_bf16 v[114:117], v[152:155], v[216:219], v[114:117]
	v_mfma_f32_16x16x32_bf16 v[114:117], v[156:159], v[220:223], v[114:117]
	v_mfma_f32_16x16x32_bf16 v[118:121], v[148:151], v[220:223], v[118:121]
	v_mfma_f32_16x16x32_bf16 v[118:121], v[144:147], v[216:219], v[118:121]
	v_mfma_f32_16x16x32_bf16 v[106:109], v[144:147], v[224:227], v[106:109]
	v_mfma_f32_16x16x32_bf16 v[106:109], v[148:151], v[228:231], v[106:109]
	v_mfma_f32_16x16x32_bf16 v[98:101], v[156:159], v[228:231], v[98:101]
	v_mfma_f32_16x16x32_bf16 v[98:101], v[152:155], v[224:227], v[98:101]
	v_mfma_f32_16x16x32_bf16 v[82:85], v[152:155], v[232:235], v[82:85]
	v_mfma_f32_16x16x32_bf16 v[82:85], v[156:159], v[236:239], v[82:85]
	v_mfma_f32_16x16x32_bf16 v[90:93], v[148:151], v[236:239], v[90:93]
	v_mfma_f32_16x16x32_bf16 v[90:93], v[144:147], v[232:235], v[90:93]
	s_setprio 0
	s_setprio 1
	v_mfma_f32_16x16x32_bf16 v[110:113], v[160:163], v[182:185], v[110:113]
	v_mfma_f32_16x16x32_bf16 v[110:113], v[164:167], v[188:191], v[110:113]
	v_mfma_f32_16x16x32_bf16 v[102:105], v[172:175], v[188:191], v[102:105]
	v_mfma_f32_16x16x32_bf16 v[102:105], v[168:171], v[182:185], v[102:105]
	v_mfma_f32_16x16x32_bf16 v[86:89], v[168:171], v[216:219], v[86:89]
	v_mfma_f32_16x16x32_bf16 v[86:89], v[172:175], v[220:223], v[86:89]
	v_mfma_f32_16x16x32_bf16 v[94:97], v[164:167], v[220:223], v[94:97]
	v_mfma_f32_16x16x32_bf16 v[94:97], v[160:163], v[216:219], v[94:97]
	v_mfma_f32_16x16x32_bf16 v[76:79], v[160:163], v[224:227], v[76:79]
	v_mfma_f32_16x16x32_bf16 v[76:79], v[164:167], v[228:231], v[76:79]
	v_mfma_f32_16x16x32_bf16 v[72:75], v[172:175], v[228:231], v[72:75]
	v_mfma_f32_16x16x32_bf16 v[72:75], v[168:171], v[224:227], v[72:75]
	v_mfma_f32_16x16x32_bf16 v[64:67], v[168:171], v[232:235], v[64:67]
	v_mfma_f32_16x16x32_bf16 v[64:67], v[172:175], v[236:239], v[64:67]
	v_mfma_f32_16x16x32_bf16 v[68:71], v[164:167], v[236:239], v[68:71]
	v_mfma_f32_16x16x32_bf16 v[68:71], v[160:163], v[232:235], v[68:71]
	s_setprio 0
	s_barrier
	s_add_i32 s74, s74, s33
	v_lshl_add_u64 v[176:177], s[22:23], 0, v[80:81]
	s_mov_b32 m0, s74
	ds_read_b128 v[182:185], v143 offset:16384
	ds_read_b128 v[188:191], v143 offset:17408
	ds_read_b128 v[216:219], v143 offset:18432
	ds_read_b128 v[220:223], v143 offset:19456
	ds_read_b128 v[224:227], v143 offset:20480
	ds_read_b128 v[228:231], v143 offset:21504
	ds_read_b128 v[232:235], v143 offset:22528
	ds_read_b128 v[236:239], v143 offset:23552
	global_load_lds_dwordx4 v[176:177], off
	s_add_i32 m0, s74, 0x2000
	s_add_u32 s74, s22, 0x200000
	v_lshl_add_u64 v[192:193], s[22:23], 0, v[130:131]
	s_addc_u32 s75, s23, 0
	s_add_i32 s76, s76, s33
	global_load_lds_dwordx4 v[192:193], off
	v_lshl_add_u64 v[202:203], s[74:75], 0, v[80:81]
	s_mov_b32 m0, s76
	v_lshl_add_u64 v[204:205], s[56:57], 0, v[132:133]
	global_load_lds_dwordx4 v[202:203], off
	v_lshl_add_u64 v[202:203], s[74:75], 0, v[130:131]
	s_add_i32 m0, s76, 0x2000
	s_nop 0
	global_load_lds_dwordx4 v[202:203], off
	v_lshl_add_u64 v[202:203], s[56:57], 0, v[134:135]
	s_mov_b32 m0, s35
	s_nop 0
	global_load_lds_dwordx4 v[202:203], off
	s_mov_b32 m0, s36
	s_nop 0
	global_load_lds_dwordx4 v[204:205], off
	s_waitcnt vmcnt(8)
	s_waitcnt lgkmcnt(0)
	s_barrier
; #define PG8_STAGE(bufoff, gbase, voff) do { _Pragma("unroll") for (int _i = 0; _i < 2; ++_i) \
;         __builtin_amdgcn_global_load_lds((const unsigned*)((const char*)(gbase) + (voff)[_i]), (PG8_LAS unsigned*)(lds + (bufoff) + ldsw + _i * 8192), 16, 0, 0); } while (0)
; #define PG8_LDA(dst, b, h) do { _Pragma("unroll") for (int m = 0; m < 4; ++m) _Pragma("unroll") for (int k = 0; k < 2; ++k) dst[m][k] = *(const PG8_LAS bf16x8*)(lds + PG8_SA(b, h) + aoff + m * 2048 + k * 1024); } while (0)
; #define PG8_LDB(dst, b, h) do { _Pragma("unroll") for (int n = 0; n < 2; ++n) _Pragma("unroll") for (int k = 0; k < 2; ++k) dst[n][k] = *(const PG8_LAS bf16x8*)(lds + PG8_SB(b, h) + boff + n * 2048 + k * 1024); } while (0)
; #define PG8_MMA(ai, bj, At, Bt) do { __builtin_amdgcn_s_setprio(1); _Pragma("unroll") for (int m = 0; m < 4; ++m) _Pragma("unroll") for (int n = 0; n < 2; ++n) _Pragma("unroll") for (int k = 0; k < 2; ++k) \
;         acc[ai][bj][m][n] = __builtin_amdgcn_mfma_f32_16x16x32_bf16(Bt[n][k], At[m][k], acc[ai][bj][m][n], 0, 0, 0); __builtin_amdgcn_s_setprio(0); } while (0)
; #define PG8_WAIT_V(n) asm volatile("s_waitcnt vmcnt(" #n ")" ::: "memory")
; #define PG8_WAIT_L(n) asm volatile("s_waitcnt lgkmcnt(" #n ")" ::: "memory")
; #define PG8_BAR __builtin_amdgcn_s_barrier()
; #define PG8_SCHED __builtin_amdgcn_sched_barrier(0)
; template <class Epi, class Sched, bool ALIGN_EPI = false, bool SP2 = false>
; __device__ __forceinline__ void gemm_phase(PG8_LAS unsigned char* lds, const Gemm g, const Sched& S, const Epi& E) {
;     ...
;             PG8_WAIT_V(8); PG8_WAIT_L(0); PG8_BAR; PG8_MMA(1, 0, At, B0); PG8_MMA(1, 1, At, B1); PG8_BAR; PG8_SCHED;
;             PG8_LDB(B0, 1, 0); PG8_LDB(B1, 1, 1); PG8_SCHED; PG8_LDA(At, 1, 0); PG8_STAGE(PG8_SA(0, 1), a2 + hstepA, voffA);
;             PG8_WAIT_V(8); PG8_WAIT_L(0); PG8_BAR; PG8_MMA(0, 0, At, B0); PG8_MMA(0, 1, At, B1); PG8_BAR; PG8_SCHED;
	s_setprio 1
	s_waitcnt lgkmcnt(0)
	v_mfma_f32_16x16x32_bf16 v[60:63], v[144:147], v[182:185], v[60:63]
	v_mfma_f32_16x16x32_bf16 v[60:63], v[148:151], v[188:191], v[60:63]
	v_mfma_f32_16x16x32_bf16 v[56:59], v[156:159], v[188:191], v[56:59]
	v_mfma_f32_16x16x32_bf16 v[56:59], v[152:155], v[182:185], v[56:59]
	v_mfma_f32_16x16x32_bf16 v[48:51], v[152:155], v[216:219], v[48:51]
	v_mfma_f32_16x16x32_bf16 v[48:51], v[156:159], v[220:223], v[48:51]
	v_mfma_f32_16x16x32_bf16 v[52:55], v[148:151], v[220:223], v[52:55]
	v_mfma_f32_16x16x32_bf16 v[52:55], v[144:147], v[216:219], v[52:55]
	v_mfma_f32_16x16x32_bf16 v[36:39], v[144:147], v[224:227], v[36:39]
	v_mfma_f32_16x16x32_bf16 v[36:39], v[148:151], v[228:231], v[36:39]
	v_mfma_f32_16x16x32_bf16 v[32:35], v[156:159], v[228:231], v[32:35]
	v_mfma_f32_16x16x32_bf16 v[32:35], v[152:155], v[224:227], v[32:35]
	v_mfma_f32_16x16x32_bf16 v[16:19], v[152:155], v[232:235], v[16:19]
	v_mfma_f32_16x16x32_bf16 v[16:19], v[156:159], v[236:239], v[16:19]
	v_mfma_f32_16x16x32_bf16 v[20:23], v[148:151], v[236:239], v[20:23]
	v_mfma_f32_16x16x32_bf16 v[20:23], v[144:147], v[232:235], v[20:23]
	s_setprio 0
	s_setprio 1
	v_mfma_f32_16x16x32_bf16 v[44:47], v[160:163], v[182:185], v[44:47]
	v_mfma_f32_16x16x32_bf16 v[44:47], v[164:167], v[188:191], v[44:47]
	v_mfma_f32_16x16x32_bf16 v[40:43], v[172:175], v[188:191], v[40:43]
	v_mfma_f32_16x16x32_bf16 v[40:43], v[168:171], v[182:185], v[40:43]
	v_mfma_f32_16x16x32_bf16 v[24:27], v[168:171], v[216:219], v[24:27]
	v_mfma_f32_16x16x32_bf16 v[24:27], v[172:175], v[220:223], v[24:27]
	v_mfma_f32_16x16x32_bf16 v[28:31], v[164:167], v[220:223], v[28:31]
	v_mfma_f32_16x16x32_bf16 v[28:31], v[160:163], v[216:219], v[28:31]
	v_mfma_f32_16x16x32_bf16 v[12:15], v[160:163], v[224:227], v[12:15]
	v_mfma_f32_16x16x32_bf16 v[12:15], v[164:167], v[228:231], v[12:15]
	v_mfma_f32_16x16x32_bf16 v[8:11], v[172:175], v[228:231], v[8:11]
	v_mfma_f32_16x16x32_bf16 v[8:11], v[168:171], v[224:227], v[8:11]
	v_mfma_f32_16x16x32_bf16 v[0:3], v[168:171], v[232:235], v[0:3]
	v_mfma_f32_16x16x32_bf16 v[0:3], v[172:175], v[236:239], v[0:3]
	v_mfma_f32_16x16x32_bf16 v[4:7], v[164:167], v[236:239], v[4:7]
	v_mfma_f32_16x16x32_bf16 v[4:7], v[160:163], v[232:235], v[4:7]
	s_setprio 0
	s_barrier
	s_add_i32 s74, 0, 0x18000
	s_add_i32 s75, 0, 0x1c000
	v_add_u32_e32 v156, s74, v142
	v_add_u32_e32 v172, s75, v142
	ds_read_b128 v[144:147], v156
	ds_read_b128 v[148:151], v156 offset:1024
	ds_read_b128 v[152:155], v156 offset:2048
	ds_read_b128 v[156:159], v156 offset:3072
	ds_read_b128 v[160:163], v172
	ds_read_b128 v[164:167], v172 offset:1024
	ds_read_b128 v[168:171], v172 offset:2048
	ds_read_b128 v[172:175], v172 offset:3072
	s_add_u32 s56, s56, 0x200000
	s_addc_u32 s57, s57, 0
	s_mov_b32 m0, s37
	v_lshl_add_u64 v[206:207], s[56:57], 0, v[134:135]
	ds_read_b128 v[182:185], v143 offset:32768
	ds_read_b128 v[188:191], v143 offset:33792
	ds_read_b128 v[216:219], v143 offset:34816
	ds_read_b128 v[220:223], v143 offset:35840
	ds_read_b128 v[224:227], v143 offset:36864
	ds_read_b128 v[228:231], v143 offset:37888
	ds_read_b128 v[232:235], v143 offset:38912
	ds_read_b128 v[236:239], v143 offset:39936
	global_load_lds_dwordx4 v[206:207], off
	v_lshl_add_u64 v[206:207], s[56:57], 0, v[132:133]
	s_mov_b32 m0, s44
	s_nop 0
	global_load_lds_dwordx4 v[206:207], off
	s_waitcnt vmcnt(8)
	s_waitcnt lgkmcnt(0)
	s_barrier
	s_setprio 1
	s_waitcnt lgkmcnt(0)
	v_mfma_f32_16x16x32_bf16 v[126:129], v[144:147], v[182:185], v[126:129]
	v_mfma_f32_16x16x32_bf16 v[126:129], v[148:151], v[188:191], v[126:129]
	v_mfma_f32_16x16x32_bf16 v[122:125], v[156:159], v[188:191], v[122:125]
	v_mfma_f32_16x16x32_bf16 v[122:125], v[152:155], v[182:185], v[122:125]
	v_mfma_f32_16x16x32_bf16 v[114:117], v[152:155], v[216:219], v[114:117]
	v_mfma_f32_16x16x32_bf16 v[114:117], v[156:159], v[220:223], v[114:117]
	v_mfma_f32_16x16x32_bf16 v[118:121], v[148:151], v[220:223], v[118:121]
	v_mfma_f32_16x16x32_bf16 v[118:121], v[144:147], v[216:219], v[118:121]
	v_mfma_f32_16x16x32_bf16 v[106:109], v[144:147], v[224:227], v[106:109]
	v_mfma_f32_16x16x32_bf16 v[106:109], v[148:151], v[228:231], v[106:109]
	v_mfma_f32_16x16x32_bf16 v[98:101], v[156:159], v[228:231], v[98:101]
	v_mfma_f32_16x16x32_bf16 v[98:101], v[152:155], v[224:227], v[98:101]
	v_mfma_f32_16x16x32_bf16 v[82:85], v[152:155], v[232:235], v[82:85]
	v_mfma_f32_16x16x32_bf16 v[82:85], v[156:159], v[236:239], v[82:85]
	v_mfma_f32_16x16x32_bf16 v[90:93], v[148:151], v[236:239], v[90:93]
	v_mfma_f32_16x16x32_bf16 v[90:93], v[144:147], v[232:235], v[90:93]
	s_setprio 0
	s_setprio 1
	v_mfma_f32_16x16x32_bf16 v[110:113], v[160:163], v[182:185], v[110:113]
	v_mfma_f32_16x16x32_bf16 v[110:113], v[164:167], v[188:191], v[110:113]
	v_mfma_f32_16x16x32_bf16 v[102:105], v[172:175], v[188:191], v[102:105]
	v_mfma_f32_16x16x32_bf16 v[102:105], v[168:171], v[182:185], v[102:105]
	v_mfma_f32_16x16x32_bf16 v[86:89], v[168:171], v[216:219], v[86:89]
	v_mfma_f32_16x16x32_bf16 v[86:89], v[172:175], v[220:223], v[86:89]
	v_mfma_f32_16x16x32_bf16 v[94:97], v[164:167], v[220:223], v[94:97]
	v_mfma_f32_16x16x32_bf16 v[94:97], v[160:163], v[216:219], v[94:97]
	v_mfma_f32_16x16x32_bf16 v[76:79], v[160:163], v[224:227], v[76:79]
	v_mfma_f32_16x16x32_bf16 v[76:79], v[164:167], v[228:231], v[76:79]
	v_mfma_f32_16x16x32_bf16 v[72:75], v[172:175], v[228:231], v[72:75]
	v_mfma_f32_16x16x32_bf16 v[72:75], v[168:171], v[224:227], v[72:75]
	v_mfma_f32_16x16x32_bf16 v[64:67], v[168:171], v[232:235], v[64:67]
	v_mfma_f32_16x16x32_bf16 v[64:67], v[172:175], v[236:239], v[64:67]
	v_mfma_f32_16x16x32_bf16 v[68:71], v[164:167], v[236:239], v[68:71]
	v_mfma_f32_16x16x32_bf16 v[68:71], v[160:163], v[232:235], v[68:71]
	s_setprio 0
	s_barrier
; #define PG8_STAGE(bufoff, gbase, voff) do { _Pragma("unroll") for (int _i = 0; _i < 2; ++_i) \
;         __builtin_amdgcn_global_load_lds((const unsigned*)((const char*)(gbase) + (voff)[_i]), (PG8_LAS unsigned*)(lds + (bufoff) + ldsw + _i * 8192), 16, 0, 0); } while (0)
; #define PG8_LDA(dst, b, h) do { _Pragma("unroll") for (int m = 0; m < 4; ++m) _Pragma("unroll") for (int k = 0; k < 2; ++k) dst[m][k] = *(const PG8_LAS bf16x8*)(lds + PG8_SA(b, h) + aoff + m * 2048 + k * 1024); } while (0)
; #define PG8_MMA(ai, bj, At, Bt) do { __builtin_amdgcn_s_setprio(1); _Pragma("unroll") for (int m = 0; m < 4; ++m) _Pragma("unroll") for (int n = 0; n < 2; ++n) _Pragma("unroll") for (int k = 0; k < 2; ++k) \
;         acc[ai][bj][m][n] = __builtin_amdgcn_mfma_f32_16x16x32_bf16(Bt[n][k], At[m][k], acc[ai][bj][m][n], 0, 0, 0); __builtin_amdgcn_s_setprio(0); } while (0)
; #define PG8_WAIT_V(n) asm volatile("s_waitcnt vmcnt(" #n ")" ::: "memory")
; #define PG8_WAIT_L(n) asm volatile("s_waitcnt lgkmcnt(" #n ")" ::: "memory")
; #define PG8_BAR __builtin_amdgcn_s_barrier()
; #define PG8_SCHED __builtin_amdgcn_sched_barrier(0)
; template <class Epi, class Sched, bool ALIGN_EPI = false, bool SP2 = false>
; __device__ __forceinline__ void gemm_phase(PG8_LAS unsigned char* lds, const Gemm g, const Sched& S, const Epi& E) {
;     ...
;             PG8_LDA(At, 1, 1); PG8_STAGE(PG8_SB(1, 0), b3, voffB); PG8_STAGE(PG8_SB(1, 1), b3 + hstepB, voffB); PG8_STAGE(PG8_SA(1, 0), a3, voffA);
;             PG8_WAIT_V(8); PG8_WAIT_L(0); PG8_BAR; PG8_MMA(1, 0, At, B0); PG8_MMA(1, 1, At, B1); PG8_BAR; PG8_SCHED;
;     ...
;         if constexpr (ALIGN_EPI) { if (wr == 0) PG8_BAR; }
	s_add_i32 s56, s74, s33
	v_lshl_add_u64 v[176:177], v[176:177], 0, s[60:61]
	s_mov_b32 m0, s56
	ds_read_b128 v[182:185], v143 offset:49152
	ds_read_b128 v[188:191], v143 offset:50176
	ds_read_b128 v[216:219], v143 offset:51200
	ds_read_b128 v[220:223], v143 offset:52224
	ds_read_b128 v[224:227], v143 offset:53248
	ds_read_b128 v[228:231], v143 offset:54272
	ds_read_b128 v[232:235], v143 offset:55296
	ds_read_b128 v[236:239], v143 offset:56320
	global_load_lds_dwordx4 v[176:177], off
	s_add_i32 m0, s56, 0x2000
	s_add_u32 s22, s22, 0x200080
	v_lshl_add_u64 v[176:177], v[192:193], 0, s[60:61]
	s_addc_u32 s23, s23, 0
	s_add_i32 s56, s75, s33
	global_load_lds_dwordx4 v[176:177], off
	v_lshl_add_u64 v[176:177], s[22:23], 0, v[80:81]
	s_mov_b32 m0, s56
	s_nop 0
	global_load_lds_dwordx4 v[176:177], off
	v_lshl_add_u64 v[176:177], s[22:23], 0, v[130:131]
	s_add_i32 m0, s56, 0x2000
	s_nop 0
	global_load_lds_dwordx4 v[176:177], off
	v_lshl_add_u64 v[176:177], v[202:203], 0, s[60:61]
	s_mov_b32 m0, s45
	s_nop 0
	global_load_lds_dwordx4 v[176:177], off
	v_lshl_add_u64 v[176:177], v[204:205], 0, s[60:61]
	s_mov_b32 m0, s49
	s_nop 0
	global_load_lds_dwordx4 v[176:177], off
	s_waitcnt vmcnt(8)
	s_waitcnt lgkmcnt(0)
	s_barrier
	s_setprio 1
	s_waitcnt lgkmcnt(0)
	v_mfma_f32_16x16x32_bf16 v[60:63], v[144:147], v[182:185], v[60:63]
	v_mfma_f32_16x16x32_bf16 v[60:63], v[148:151], v[188:191], v[60:63]
	v_mfma_f32_16x16x32_bf16 v[56:59], v[156:159], v[188:191], v[56:59]
	v_mfma_f32_16x16x32_bf16 v[56:59], v[152:155], v[182:185], v[56:59]
	v_mfma_f32_16x16x32_bf16 v[48:51], v[152:155], v[216:219], v[48:51]
	v_mfma_f32_16x16x32_bf16 v[48:51], v[156:159], v[220:223], v[48:51]
	v_mfma_f32_16x16x32_bf16 v[52:55], v[148:151], v[220:223], v[52:55]
	v_mfma_f32_16x16x32_bf16 v[52:55], v[144:147], v[216:219], v[52:55]
	v_mfma_f32_16x16x32_bf16 v[36:39], v[144:147], v[224:227], v[36:39]
	v_mfma_f32_16x16x32_bf16 v[36:39], v[148:151], v[228:231], v[36:39]
	v_mfma_f32_16x16x32_bf16 v[32:35], v[156:159], v[228:231], v[32:35]
	v_mfma_f32_16x16x32_bf16 v[32:35], v[152:155], v[224:227], v[32:35]
	v_mfma_f32_16x16x32_bf16 v[16:19], v[152:155], v[232:235], v[16:19]
	v_mfma_f32_16x16x32_bf16 v[16:19], v[156:159], v[236:239], v[16:19]
	v_mfma_f32_16x16x32_bf16 v[20:23], v[148:151], v[236:239], v[20:23]
	v_mfma_f32_16x16x32_bf16 v[20:23], v[144:147], v[232:235], v[20:23]
	s_setprio 0
	s_setprio 1
	v_mfma_f32_16x16x32_bf16 v[44:47], v[160:163], v[182:185], v[44:47]
	v_mfma_f32_16x16x32_bf16 v[44:47], v[164:167], v[188:191], v[44:47]
	v_mfma_f32_16x16x32_bf16 v[40:43], v[172:175], v[188:191], v[40:43]
	v_mfma_f32_16x16x32_bf16 v[40:43], v[168:171], v[182:185], v[40:43]
	v_mfma_f32_16x16x32_bf16 v[24:27], v[168:171], v[216:219], v[24:27]
	v_mfma_f32_16x16x32_bf16 v[24:27], v[172:175], v[220:223], v[24:27]
	v_mfma_f32_16x16x32_bf16 v[28:31], v[164:167], v[220:223], v[28:31]
	v_mfma_f32_16x16x32_bf16 v[28:31], v[160:163], v[216:219], v[28:31]
	v_mfma_f32_16x16x32_bf16 v[12:15], v[160:163], v[224:227], v[12:15]
	v_mfma_f32_16x16x32_bf16 v[12:15], v[164:167], v[228:231], v[12:15]
	v_mfma_f32_16x16x32_bf16 v[8:11], v[172:175], v[228:231], v[8:11]
	v_mfma_f32_16x16x32_bf16 v[8:11], v[168:171], v[224:227], v[8:11]
	v_mfma_f32_16x16x32_bf16 v[0:3], v[168:171], v[232:235], v[0:3]
	v_mfma_f32_16x16x32_bf16 v[0:3], v[172:175], v[236:239], v[0:3]
	v_mfma_f32_16x16x32_bf16 v[4:7], v[164:167], v[236:239], v[4:7]
	v_mfma_f32_16x16x32_bf16 v[4:7], v[160:163], v[232:235], v[4:7]
	s_setprio 0
	s_barrier
	s_add_i32 s73, s73, 2
	s_add_u32 s66, s66, 0x100
	s_addc_u32 s67, s67, 0
	s_add_u32 s41, s41, 0x100
	s_addc_u32 s43, s43, 0
	s_cmp_gt_u32 s73, 13
	s_cbranch_scc0 .LBB0_1367
	s_and_b64 vcc, exec, s[20:21]
	s_cbranch_vccz .LBB0_1370
	s_barrier

; #define PG8_STAGE(bufoff, gbase, voff) do { _Pragma("unroll") for (int _i = 0; _i < 2; ++_i) \
;         __builtin_amdgcn_global_load_lds((const unsigned*)((const char*)(gbase) + (voff)[_i]), (PG8_LAS unsigned*)(lds + (bufoff) + ldsw + _i * 8192), 16, 0, 0); } while (0)
; #define PG8_LDA(dst, b, h) do { _Pragma("unroll") for (int m = 0; m < 4; ++m) _Pragma("unroll") for (int k = 0; k < 2; ++k) dst[m][k] = *(const PG8_LAS bf16x8*)(lds + PG8_SA(b, h) + aoff + m * 2048 + k * 1024); } while (0)
; #define PG8_LDB(dst, b, h) do { _Pragma("unroll") for (int n = 0; n < 2; ++n) _Pragma("unroll") for (int k = 0; k < 2; ++k) dst[n][k] = *(const PG8_LAS bf16x8*)(lds + PG8_SB(b, h) + boff + n * 2048 + k * 1024); } while (0)
; #define PG8_MMA(ai, bj, At, Bt) do { __builtin_amdgcn_s_setprio(1); _Pragma("unroll") for (int m = 0; m < 4; ++m) _Pragma("unroll") for (int n = 0; n < 2; ++n) _Pragma("unroll") for (int k = 0; k < 2; ++k) \
;         acc[ai][bj][m][n] = __builtin_amdgcn_mfma_f32_16x16x32_bf16(Bt[n][k], At[m][k], acc[ai][bj][m][n], 0, 0, 0); __builtin_amdgcn_s_setprio(0); } while (0)
; #define PG8_WAIT_V(n) asm volatile("s_waitcnt vmcnt(" #n ")" ::: "memory")
; #define PG8_WAIT_L(n) asm volatile("s_waitcnt lgkmcnt(" #n ")" ::: "memory")
; #define PG8_BAR __builtin_amdgcn_s_barrier()
; #define PG8_SCHED __builtin_amdgcn_sched_barrier(0)
; template <class Epi, class Sched, bool ALIGN_EPI = false, bool SP2 = false>
; __device__ __forceinline__ void gemm_phase(PG8_LAS unsigned char* lds, const Gemm g, const Sched& S, const Epi& E) {
;     ...
;             const bool last = (t == nt - 2);
;             const char* a1 = cA + (size_t)(t + 1) * kstep;
;             const char* a2 = last ? nA : cA + (size_t)(t + 2) * kstep; const char* b2 = last ? nB : cB + (size_t)(t + 2) * kstep;
;             const char* a3 = a2 + kstep; const char* b3 = b2 + kstep;
;             if (last && has_next) S.a_ready(nxt);
;             if constexpr (SP2) {
;             PG8_LDB(B0, 0, 0); PG8_LDB(B1, 0, 1); PG8_SCHED; PG8_LDA(At, 0, 0); PG8_STAGE(PG8_SA(1, 1), a1 + hstepA, voffA);
;             PG8_WAIT_V(8); PG8_WAIT_L(0); PG8_BAR; PG8_MMA(0, 0, At, B0); PG8_MMA(0, 1, At, B1); PG8_BAR; PG8_SCHED;
;             PG8_LDA(At, 0, 1); PG8_STAGE(PG8_SB(0, 0), b2, voffB); PG8_STAGE(PG8_SB(0, 1), b2 + hstepB, voffB); PG8_STAGE(PG8_SA(0, 0), a2, voffA);
.LBB0_1446:
	s_add_u32 s22, s20, 0xffe00080
	s_addc_u32 s23, s21, -1
	s_add_i32 s74, 0, 0x10000
	s_cmpk_eq_i32 s73, 0x7c
	s_cselect_b32 s57, s43, s23
	s_cselect_b32 s56, s47, s22
	v_add_u32_e32 v144, s74, v148
	s_cselect_b32 s23, s49, s69
	s_cselect_b32 s22, s63, s68
	s_add_i32 s76, 0, 0x14000
	ds_read_b128 v[140:143], v144
	ds_read_b128 v[150:153], v144 offset:1024
	ds_read_b128 v[154:157], v144 offset:2048
	ds_read_b128 v[158:161], v144 offset:3072
	v_add_u32_e32 v144, s76, v148
	ds_read_b128 v[162:165], v144
	ds_read_b128 v[166:169], v144 offset:1024
	ds_read_b128 v[170:173], v144 offset:2048
	ds_read_b128 v[174:177], v144 offset:3072
	v_lshl_add_u64 v[144:145], s[20:21], 0, v[136:137]
	s_add_i32 m0, s91, 0xc000
	ds_read_b128 v[182:185], v149
	ds_read_b128 v[188:191], v149 offset:1024
	ds_read_b128 v[216:219], v149 offset:2048
	ds_read_b128 v[220:223], v149 offset:3072
	ds_read_b128 v[224:227], v149 offset:4096
	ds_read_b128 v[228:231], v149 offset:5120
	ds_read_b128 v[232:235], v149 offset:6144
	ds_read_b128 v[236:239], v149 offset:7168
	global_load_lds_dwordx4 v[144:145], off
	v_lshl_add_u64 v[144:145], s[20:21], 0, v[138:139]
	s_add_i32 m0, s91, 0xe000
	s_nop 0
	global_load_lds_dwordx4 v[144:145], off
	s_waitcnt vmcnt(8)
	s_waitcnt lgkmcnt(0)
	s_barrier
	s_setprio 1
	s_waitcnt lgkmcnt(0)
	v_mfma_f32_16x16x32_bf16 v[126:129], v[140:143], v[182:185], v[126:129]
	v_mfma_f32_16x16x32_bf16 v[126:129], v[150:153], v[188:191], v[126:129]
	v_mfma_f32_16x16x32_bf16 v[122:125], v[158:161], v[188:191], v[122:125]
	v_mfma_f32_16x16x32_bf16 v[122:125], v[154:157], v[182:185], v[122:125]
	v_mfma_f32_16x16x32_bf16 v[106:109], v[154:157], v[216:219], v[106:109]
	v_mfma_f32_16x16x32_bf16 v[106:109], v[158:161], v[220:223], v[106:109]
	v_mfma_f32_16x16x32_bf16 v[110:113], v[150:153], v[220:223], v[110:113]
	v_mfma_f32_16x16x32_bf16 v[110:113], v[140:143], v[216:219], v[110:113]
	v_mfma_f32_16x16x32_bf16 v[94:97], v[140:143], v[224:227], v[94:97]
	v_mfma_f32_16x16x32_bf16 v[94:97], v[150:153], v[228:231], v[94:97]
	v_mfma_f32_16x16x32_bf16 v[90:93], v[158:161], v[228:231], v[90:93]
	v_mfma_f32_16x16x32_bf16 v[90:93], v[154:157], v[224:227], v[90:93]
	v_mfma_f32_16x16x32_bf16 v[72:75], v[154:157], v[232:235], v[72:75]
	v_mfma_f32_16x16x32_bf16 v[72:75], v[158:161], v[236:239], v[72:75]
	v_mfma_f32_16x16x32_bf16 v[76:79], v[150:153], v[236:239], v[76:79]
	v_mfma_f32_16x16x32_bf16 v[76:79], v[140:143], v[232:235], v[76:79]
	s_setprio 0
	s_setprio 1
	v_mfma_f32_16x16x32_bf16 v[118:121], v[162:165], v[182:185], v[118:121]
	v_mfma_f32_16x16x32_bf16 v[118:121], v[166:169], v[188:191], v[118:121]
	v_mfma_f32_16x16x32_bf16 v[114:117], v[174:177], v[188:191], v[114:117]
	v_mfma_f32_16x16x32_bf16 v[114:117], v[170:173], v[182:185], v[114:117]
	v_mfma_f32_16x16x32_bf16 v[98:101], v[170:173], v[216:219], v[98:101]
	v_mfma_f32_16x16x32_bf16 v[98:101], v[174:177], v[220:223], v[98:101]
	v_mfma_f32_16x16x32_bf16 v[102:105], v[166:169], v[220:223], v[102:105]
	v_mfma_f32_16x16x32_bf16 v[102:105], v[162:165], v[216:219], v[102:105]
	v_mfma_f32_16x16x32_bf16 v[86:89], v[162:165], v[224:227], v[86:89]
	v_mfma_f32_16x16x32_bf16 v[86:89], v[166:169], v[228:231], v[86:89]
	v_mfma_f32_16x16x32_bf16 v[82:85], v[174:177], v[228:231], v[82:85]
	v_mfma_f32_16x16x32_bf16 v[82:85], v[170:173], v[224:227], v[82:85]
	v_mfma_f32_16x16x32_bf16 v[64:67], v[170:173], v[232:235], v[64:67]
	v_mfma_f32_16x16x32_bf16 v[64:67], v[174:177], v[236:239], v[64:67]
	v_mfma_f32_16x16x32_bf16 v[68:71], v[166:169], v[236:239], v[68:71]
	v_mfma_f32_16x16x32_bf16 v[68:71], v[162:165], v[232:235], v[68:71]
	s_setprio 0
	s_barrier
	s_add_i32 s74, s74, s71
	v_lshl_add_u64 v[144:145], s[22:23], 0, v[80:81]
	s_mov_b32 m0, s74
	ds_read_b128 v[182:185], v149 offset:16384
	ds_read_b128 v[188:191], v149 offset:17408
	ds_read_b128 v[216:219], v149 offset:18432
	ds_read_b128 v[220:223], v149 offset:19456
	ds_read_b128 v[224:227], v149 offset:20480
	ds_read_b128 v[228:231], v149 offset:21504
	ds_read_b128 v[232:235], v149 offset:22528
	ds_read_b128 v[236:239], v149 offset:23552
	global_load_lds_dwordx4 v[144:145], off
	s_add_i32 m0, s74, 0x2000
	s_add_u32 s74, s22, 0x200000
	v_lshl_add_u64 v[192:193], s[22:23], 0, v[134:135]
	s_addc_u32 s75, s23, 0
	s_add_i32 s76, s76, s71
	global_load_lds_dwordx4 v[192:193], off
	v_lshl_add_u64 v[202:203], s[74:75], 0, v[80:81]
	s_mov_b32 m0, s76
	v_lshl_add_u64 v[204:205], s[56:57], 0, v[132:133]
	global_load_lds_dwordx4 v[202:203], off
	v_lshl_add_u64 v[202:203], s[74:75], 0, v[134:135]
	s_add_i32 m0, s76, 0x2000
	s_nop 0
	global_load_lds_dwordx4 v[202:203], off
	v_lshl_add_u64 v[202:203], s[56:57], 0, v[130:131]
	s_mov_b32 m0, s91
	s_nop 0
	global_load_lds_dwordx4 v[202:203], off
	s_mov_b32 m0, s36
	s_nop 0
	global_load_lds_dwordx4 v[204:205], off
	s_waitcnt vmcnt(8)
	s_waitcnt lgkmcnt(0)
	s_barrier
; #define PG8_STAGE(bufoff, gbase, voff) do { _Pragma("unroll") for (int _i = 0; _i < 2; ++_i) \
;         __builtin_amdgcn_global_load_lds((const unsigned*)((const char*)(gbase) + (voff)[_i]), (PG8_LAS unsigned*)(lds + (bufoff) + ldsw + _i * 8192), 16, 0, 0); } while (0)
; #define PG8_LDA(dst, b, h) do { _Pragma("unroll") for (int m = 0; m < 4; ++m) _Pragma("unroll") for (int k = 0; k < 2; ++k) dst[m][k] = *(const PG8_LAS bf16x8*)(lds + PG8_SA(b, h) + aoff + m * 2048 + k * 1024); } while (0)
; #define PG8_LDB(dst, b, h) do { _Pragma("unroll") for (int n = 0; n < 2; ++n) _Pragma("unroll") for (int k = 0; k < 2; ++k) dst[n][k] = *(const PG8_LAS bf16x8*)(lds + PG8_SB(b, h) + boff + n * 2048 + k * 1024); } while (0)
; #define PG8_MMA(ai, bj, At, Bt) do { __builtin_amdgcn_s_setprio(1); _Pragma("unroll") for (int m = 0; m < 4; ++m) _Pragma("unroll") for (int n = 0; n < 2; ++n) _Pragma("unroll") for (int k = 0; k < 2; ++k) \
;         acc[ai][bj][m][n] = __builtin_amdgcn_mfma_f32_16x16x32_bf16(Bt[n][k], At[m][k], acc[ai][bj][m][n], 0, 0, 0); __builtin_amdgcn_s_setprio(0); } while (0)
; #define PG8_WAIT_V(n) asm volatile("s_waitcnt vmcnt(" #n ")" ::: "memory")
; #define PG8_WAIT_L(n) asm volatile("s_waitcnt lgkmcnt(" #n ")" ::: "memory")
; #define PG8_BAR __builtin_amdgcn_s_barrier()
; #define PG8_SCHED __builtin_amdgcn_sched_barrier(0)
; template <class Epi, class Sched, bool ALIGN_EPI = false, bool SP2 = false>
; __device__ __forceinline__ void gemm_phase(PG8_LAS unsigned char* lds, const Gemm g, const Sched& S, const Epi& E) {
;     ...
;             PG8_WAIT_V(8); PG8_WAIT_L(0); PG8_BAR; PG8_MMA(1, 0, At, B0); PG8_MMA(1, 1, At, B1); PG8_BAR; PG8_SCHED;
;             PG8_LDB(B0, 1, 0); PG8_LDB(B1, 1, 1); PG8_SCHED; PG8_LDA(At, 1, 0); PG8_STAGE(PG8_SA(0, 1), a2 + hstepA, voffA);
;             PG8_WAIT_V(8); PG8_WAIT_L(0); PG8_BAR; PG8_MMA(0, 0, At, B0); PG8_MMA(0, 1, At, B1); PG8_BAR; PG8_SCHED;
	s_setprio 1
	s_waitcnt lgkmcnt(0)
	v_mfma_f32_16x16x32_bf16 v[60:63], v[140:143], v[182:185], v[60:63]
	v_mfma_f32_16x16x32_bf16 v[60:63], v[150:153], v[188:191], v[60:63]
	v_mfma_f32_16x16x32_bf16 v[56:59], v[158:161], v[188:191], v[56:59]
	v_mfma_f32_16x16x32_bf16 v[56:59], v[154:157], v[182:185], v[56:59]
	v_mfma_f32_16x16x32_bf16 v[40:43], v[154:157], v[216:219], v[40:43]
	v_mfma_f32_16x16x32_bf16 v[40:43], v[158:161], v[220:223], v[40:43]
	v_mfma_f32_16x16x32_bf16 v[44:47], v[150:153], v[220:223], v[44:47]
	v_mfma_f32_16x16x32_bf16 v[44:47], v[140:143], v[216:219], v[44:47]
	v_mfma_f32_16x16x32_bf16 v[28:31], v[140:143], v[224:227], v[28:31]
	v_mfma_f32_16x16x32_bf16 v[28:31], v[150:153], v[228:231], v[28:31]
	v_mfma_f32_16x16x32_bf16 v[24:27], v[158:161], v[228:231], v[24:27]
	v_mfma_f32_16x16x32_bf16 v[24:27], v[154:157], v[224:227], v[24:27]
	v_mfma_f32_16x16x32_bf16 v[8:11], v[154:157], v[232:235], v[8:11]
	v_mfma_f32_16x16x32_bf16 v[8:11], v[158:161], v[236:239], v[8:11]
	v_mfma_f32_16x16x32_bf16 v[12:15], v[150:153], v[236:239], v[12:15]
	v_mfma_f32_16x16x32_bf16 v[12:15], v[140:143], v[232:235], v[12:15]
	s_setprio 0
	s_setprio 1
	v_mfma_f32_16x16x32_bf16 v[52:55], v[162:165], v[182:185], v[52:55]
	v_mfma_f32_16x16x32_bf16 v[52:55], v[166:169], v[188:191], v[52:55]
	v_mfma_f32_16x16x32_bf16 v[48:51], v[174:177], v[188:191], v[48:51]
	v_mfma_f32_16x16x32_bf16 v[48:51], v[170:173], v[182:185], v[48:51]
	v_mfma_f32_16x16x32_bf16 v[32:35], v[170:173], v[216:219], v[32:35]
	v_mfma_f32_16x16x32_bf16 v[32:35], v[174:177], v[220:223], v[32:35]
	v_mfma_f32_16x16x32_bf16 v[36:39], v[166:169], v[220:223], v[36:39]
	v_mfma_f32_16x16x32_bf16 v[36:39], v[162:165], v[216:219], v[36:39]
	v_mfma_f32_16x16x32_bf16 v[20:23], v[162:165], v[224:227], v[20:23]
	v_mfma_f32_16x16x32_bf16 v[20:23], v[166:169], v[228:231], v[20:23]
	v_mfma_f32_16x16x32_bf16 v[16:19], v[174:177], v[228:231], v[16:19]
	v_mfma_f32_16x16x32_bf16 v[16:19], v[170:173], v[224:227], v[16:19]
	v_mfma_f32_16x16x32_bf16 v[0:3], v[170:173], v[232:235], v[0:3]
	v_mfma_f32_16x16x32_bf16 v[0:3], v[174:177], v[236:239], v[0:3]
	v_mfma_f32_16x16x32_bf16 v[4:7], v[166:169], v[236:239], v[4:7]
	v_mfma_f32_16x16x32_bf16 v[4:7], v[162:165], v[232:235], v[4:7]
	s_setprio 0
	s_barrier
	s_add_i32 s74, 0, 0x18000
	s_add_i32 s75, 0, 0x1c000
	v_add_u32_e32 v158, s74, v148
	v_add_u32_e32 v174, s75, v148
	ds_read_b128 v[140:143], v158
	ds_read_b128 v[150:153], v158 offset:1024
	ds_read_b128 v[154:157], v158 offset:2048
	ds_read_b128 v[158:161], v158 offset:3072
	ds_read_b128 v[162:165], v174
	ds_read_b128 v[166:169], v174 offset:1024
	ds_read_b128 v[170:173], v174 offset:2048
	ds_read_b128 v[174:177], v174 offset:3072
	s_add_u32 s56, s56, 0x200000
	s_addc_u32 s57, s57, 0
	s_mov_b32 m0, s44
	v_lshl_add_u64 v[206:207], s[56:57], 0, v[130:131]
	ds_read_b128 v[182:185], v149 offset:32768
	ds_read_b128 v[188:191], v149 offset:33792
	ds_read_b128 v[216:219], v149 offset:34816
	ds_read_b128 v[220:223], v149 offset:35840
	ds_read_b128 v[224:227], v149 offset:36864
	ds_read_b128 v[228:231], v149 offset:37888
	ds_read_b128 v[232:235], v149 offset:38912
	ds_read_b128 v[236:239], v149 offset:39936
	global_load_lds_dwordx4 v[206:207], off
	v_lshl_add_u64 v[206:207], s[56:57], 0, v[132:133]
	s_mov_b32 m0, s45
	s_nop 0
	global_load_lds_dwordx4 v[206:207], off
	s_waitcnt vmcnt(8)
	s_waitcnt lgkmcnt(0)
	s_barrier
	s_setprio 1
	s_waitcnt lgkmcnt(0)
	v_mfma_f32_16x16x32_bf16 v[126:129], v[140:143], v[182:185], v[126:129]
	v_mfma_f32_16x16x32_bf16 v[126:129], v[150:153], v[188:191], v[126:129]
	v_mfma_f32_16x16x32_bf16 v[122:125], v[158:161], v[188:191], v[122:125]
	v_mfma_f32_16x16x32_bf16 v[122:125], v[154:157], v[182:185], v[122:125]
	v_mfma_f32_16x16x32_bf16 v[106:109], v[154:157], v[216:219], v[106:109]
	v_mfma_f32_16x16x32_bf16 v[106:109], v[158:161], v[220:223], v[106:109]
	v_mfma_f32_16x16x32_bf16 v[110:113], v[150:153], v[220:223], v[110:113]
	v_mfma_f32_16x16x32_bf16 v[110:113], v[140:143], v[216:219], v[110:113]
	v_mfma_f32_16x16x32_bf16 v[94:97], v[140:143], v[224:227], v[94:97]
	v_mfma_f32_16x16x32_bf16 v[94:97], v[150:153], v[228:231], v[94:97]
	v_mfma_f32_16x16x32_bf16 v[90:93], v[158:161], v[228:231], v[90:93]
	v_mfma_f32_16x16x32_bf16 v[90:93], v[154:157], v[224:227], v[90:93]
	v_mfma_f32_16x16x32_bf16 v[72:75], v[154:157], v[232:235], v[72:75]
	v_mfma_f32_16x16x32_bf16 v[72:75], v[158:161], v[236:239], v[72:75]
	v_mfma_f32_16x16x32_bf16 v[76:79], v[150:153], v[236:239], v[76:79]
	v_mfma_f32_16x16x32_bf16 v[76:79], v[140:143], v[232:235], v[76:79]
	s_setprio 0
	s_setprio 1
	v_mfma_f32_16x16x32_bf16 v[118:121], v[162:165], v[182:185], v[118:121]
	v_mfma_f32_16x16x32_bf16 v[118:121], v[166:169], v[188:191], v[118:121]
	v_mfma_f32_16x16x32_bf16 v[114:117], v[174:177], v[188:191], v[114:117]
	v_mfma_f32_16x16x32_bf16 v[114:117], v[170:173], v[182:185], v[114:117]
	v_mfma_f32_16x16x32_bf16 v[98:101], v[170:173], v[216:219], v[98:101]
	v_mfma_f32_16x16x32_bf16 v[98:101], v[174:177], v[220:223], v[98:101]
	v_mfma_f32_16x16x32_bf16 v[102:105], v[166:169], v[220:223], v[102:105]
	v_mfma_f32_16x16x32_bf16 v[102:105], v[162:165], v[216:219], v[102:105]
	v_mfma_f32_16x16x32_bf16 v[86:89], v[162:165], v[224:227], v[86:89]
	v_mfma_f32_16x16x32_bf16 v[86:89], v[166:169], v[228:231], v[86:89]
	v_mfma_f32_16x16x32_bf16 v[82:85], v[174:177], v[228:231], v[82:85]
	v_mfma_f32_16x16x32_bf16 v[82:85], v[170:173], v[224:227], v[82:85]
	v_mfma_f32_16x16x32_bf16 v[64:67], v[170:173], v[232:235], v[64:67]
	v_mfma_f32_16x16x32_bf16 v[64:67], v[174:177], v[236:239], v[64:67]
	v_mfma_f32_16x16x32_bf16 v[68:71], v[166:169], v[236:239], v[68:71]
	v_mfma_f32_16x16x32_bf16 v[68:71], v[162:165], v[232:235], v[68:71]
	s_setprio 0
	s_barrier
; #define PG8_STAGE(bufoff, gbase, voff) do { _Pragma("unroll") for (int _i = 0; _i < 2; ++_i) \
;         __builtin_amdgcn_global_load_lds((const unsigned*)((const char*)(gbase) + (voff)[_i]), (PG8_LAS unsigned*)(lds + (bufoff) + ldsw + _i * 8192), 16, 0, 0); } while (0)
; #define PG8_LDA(dst, b, h) do { _Pragma("unroll") for (int m = 0; m < 4; ++m) _Pragma("unroll") for (int k = 0; k < 2; ++k) dst[m][k] = *(const PG8_LAS bf16x8*)(lds + PG8_SA(b, h) + aoff + m * 2048 + k * 1024); } while (0)
; #define PG8_MMA(ai, bj, At, Bt) do { __builtin_amdgcn_s_setprio(1); _Pragma("unroll") for (int m = 0; m < 4; ++m) _Pragma("unroll") for (int n = 0; n < 2; ++n) _Pragma("unroll") for (int k = 0; k < 2; ++k) \
;         acc[ai][bj][m][n] = __builtin_amdgcn_mfma_f32_16x16x32_bf16(Bt[n][k], At[m][k], acc[ai][bj][m][n], 0, 0, 0); __builtin_amdgcn_s_setprio(0); } while (0)
; #define PG8_WAIT_V(n) asm volatile("s_waitcnt vmcnt(" #n ")" ::: "memory")
; #define PG8_WAIT_L(n) asm volatile("s_waitcnt lgkmcnt(" #n ")" ::: "memory")
; #define PG8_BAR __builtin_amdgcn_s_barrier()
; #define PG8_SCHED __builtin_amdgcn_sched_barrier(0)
; template <class Epi, class Sched, bool ALIGN_EPI = false, bool SP2 = false>
; __device__ __forceinline__ void gemm_phase(PG8_LAS unsigned char* lds, const Gemm g, const Sched& S, const Epi& E) {
;     ...
;             PG8_LDA(At, 1, 1); PG8_STAGE(PG8_SB(1, 0), b3, voffB); PG8_STAGE(PG8_SB(1, 1), b3 + hstepB, voffB); PG8_STAGE(PG8_SA(1, 0), a3, voffA);
;             PG8_WAIT_V(8); PG8_WAIT_L(0); PG8_BAR; PG8_MMA(1, 0, At, B0); PG8_MMA(1, 1, At, B1); PG8_BAR; PG8_SCHED;
;     ...
;         if constexpr (ALIGN_EPI) { if (wr == 0) PG8_BAR; }
	s_add_i32 s56, s74, s71
	v_lshl_add_u64 v[144:145], v[144:145], 0, s[60:61]
	s_mov_b32 m0, s56
	ds_read_b128 v[182:185], v149 offset:49152
	ds_read_b128 v[188:191], v149 offset:50176
	ds_read_b128 v[216:219], v149 offset:51200
	ds_read_b128 v[220:223], v149 offset:52224
	ds_read_b128 v[224:227], v149 offset:53248
	ds_read_b128 v[228:231], v149 offset:54272
	ds_read_b128 v[232:235], v149 offset:55296
	ds_read_b128 v[236:239], v149 offset:56320
	global_load_lds_dwordx4 v[144:145], off
	s_add_i32 m0, s56, 0x2000
	s_add_u32 s22, s22, 0x200080
	v_lshl_add_u64 v[144:145], v[192:193], 0, s[60:61]
	s_addc_u32 s23, s23, 0
	s_add_i32 s56, s75, s71
	global_load_lds_dwordx4 v[144:145], off
	v_lshl_add_u64 v[144:145], s[22:23], 0, v[80:81]
	s_mov_b32 m0, s56
	s_nop 0
	global_load_lds_dwordx4 v[144:145], off
	v_lshl_add_u64 v[144:145], s[22:23], 0, v[134:135]
	s_add_i32 m0, s56, 0x2000
	s_nop 0
	global_load_lds_dwordx4 v[144:145], off
	v_lshl_add_u64 v[144:145], v[202:203], 0, s[60:61]
	s_mov_b32 m0, s92
	s_nop 0
	global_load_lds_dwordx4 v[144:145], off
	v_lshl_add_u64 v[144:145], v[204:205], 0, s[60:61]
	s_mov_b32 m0, s37
	s_nop 0
	global_load_lds_dwordx4 v[144:145], off
	s_waitcnt vmcnt(8)
	s_waitcnt lgkmcnt(0)
	s_barrier
	s_setprio 1
	s_waitcnt lgkmcnt(0)
	v_mfma_f32_16x16x32_bf16 v[60:63], v[140:143], v[182:185], v[60:63]
	v_mfma_f32_16x16x32_bf16 v[60:63], v[150:153], v[188:191], v[60:63]
	v_mfma_f32_16x16x32_bf16 v[56:59], v[158:161], v[188:191], v[56:59]
	v_mfma_f32_16x16x32_bf16 v[56:59], v[154:157], v[182:185], v[56:59]
	v_mfma_f32_16x16x32_bf16 v[40:43], v[154:157], v[216:219], v[40:43]
	v_mfma_f32_16x16x32_bf16 v[40:43], v[158:161], v[220:223], v[40:43]
	v_mfma_f32_16x16x32_bf16 v[44:47], v[150:153], v[220:223], v[44:47]
	v_mfma_f32_16x16x32_bf16 v[44:47], v[140:143], v[216:219], v[44:47]
	v_mfma_f32_16x16x32_bf16 v[28:31], v[140:143], v[224:227], v[28:31]
	v_mfma_f32_16x16x32_bf16 v[28:31], v[150:153], v[228:231], v[28:31]
	v_mfma_f32_16x16x32_bf16 v[24:27], v[158:161], v[228:231], v[24:27]
	v_mfma_f32_16x16x32_bf16 v[24:27], v[154:157], v[224:227], v[24:27]
	v_mfma_f32_16x16x32_bf16 v[8:11], v[154:157], v[232:235], v[8:11]
	v_mfma_f32_16x16x32_bf16 v[8:11], v[158:161], v[236:239], v[8:11]
	v_mfma_f32_16x16x32_bf16 v[12:15], v[150:153], v[236:239], v[12:15]
	v_mfma_f32_16x16x32_bf16 v[12:15], v[140:143], v[232:235], v[12:15]
	s_setprio 0
	s_setprio 1
	v_mfma_f32_16x16x32_bf16 v[52:55], v[162:165], v[182:185], v[52:55]
	v_mfma_f32_16x16x32_bf16 v[52:55], v[166:169], v[188:191], v[52:55]
	v_mfma_f32_16x16x32_bf16 v[48:51], v[174:177], v[188:191], v[48:51]
	v_mfma_f32_16x16x32_bf16 v[48:51], v[170:173], v[182:185], v[48:51]
	v_mfma_f32_16x16x32_bf16 v[32:35], v[170:173], v[216:219], v[32:35]
	v_mfma_f32_16x16x32_bf16 v[32:35], v[174:177], v[220:223], v[32:35]
	v_mfma_f32_16x16x32_bf16 v[36:39], v[166:169], v[220:223], v[36:39]
	v_mfma_f32_16x16x32_bf16 v[36:39], v[162:165], v[216:219], v[36:39]
	v_mfma_f32_16x16x32_bf16 v[20:23], v[162:165], v[224:227], v[20:23]
	v_mfma_f32_16x16x32_bf16 v[20:23], v[166:169], v[228:231], v[20:23]
	v_mfma_f32_16x16x32_bf16 v[16:19], v[174:177], v[228:231], v[16:19]
	v_mfma_f32_16x16x32_bf16 v[16:19], v[170:173], v[224:227], v[16:19]
	v_mfma_f32_16x16x32_bf16 v[0:3], v[170:173], v[232:235], v[0:3]
	v_mfma_f32_16x16x32_bf16 v[0:3], v[174:177], v[236:239], v[0:3]
	v_mfma_f32_16x16x32_bf16 v[4:7], v[166:169], v[236:239], v[4:7]
	v_mfma_f32_16x16x32_bf16 v[4:7], v[162:165], v[232:235], v[4:7]
	s_setprio 0
	s_barrier
	s_add_i32 s73, s73, 2
	s_add_u32 s20, s20, 0x100
	s_addc_u32 s21, s21, 0
	s_add_u32 s68, s68, 0x100
	s_addc_u32 s69, s69, 0
	s_cmpk_gt_u32 s73, 0x7d
	s_cbranch_scc0 .LBB0_1446
	s_and_b64 vcc, exec, s[52:53]
	s_cbranch_vccz .LBB0_1449
	s_barrier
